# plus batched bias lookups in NA/SWA score tiles, new gemm1 epilogue with 16-byte stores via permlane16_swap
# speedup vs baseline: 1.0113x; 1.0113x over previous
.LBB0_138:
	v_or_b32_e32 v139, 0x10000, v150
	v_add_u32_e32 v144, 0x10400, v150
	ds_read_b128 v[140:143], v139
	ds_read_b128 v[144:147], v144
	v_add_u32_e32 v139, 0x10800, v150
	v_add_u32_e32 v151, 0x10c00, v150
	ds_read_b128 v[152:155], v139
	ds_read_b128 v[156:159], v151
	s_add_u32 s6, s4, 0xfffc0080
	s_addc_u32 s7, s5, -1
	s_cmp_eq_u32 s70, 12
	s_cselect_b32 s9, s13, s7
	s_cselect_b32 s8, s15, s6
	s_cselect_b32 s7, s26, s69
	s_cselect_b32 s6, s28, s29
	s_mov_b32 m0, s67
	v_lshl_add_u64 v[206:207], s[4:5], 0, v[134:135]
	ds_read_b128 v[160:163], v149
	ds_read_b128 v[164:167], v149 offset:1024
	ds_read_b128 v[168:171], v149 offset:2048
	ds_read_b128 v[172:175], v149 offset:3072
	ds_read_b128 v[176:179], v149 offset:4096
	ds_read_b128 v[180:183], v149 offset:5120
	ds_read_b128 v[184:187], v149 offset:6144
	ds_read_b128 v[188:191], v149 offset:7168
	global_load_lds_dwordx4 v[206:207], off
	v_lshl_add_u64 v[206:207], s[4:5], 0, v[136:137]
	s_mov_b32 m0, s68
	s_nop 0
	global_load_lds_dwordx4 v[206:207], off
	s_waitcnt lgkmcnt(8)
	s_barrier
	s_waitcnt lgkmcnt(0)
	s_setprio 1
	s_waitcnt lgkmcnt(0)
	v_mfma_f32_16x16x32_bf16 v[124:127], v[140:143], v[160:163], v[124:127]
	v_mfma_f32_16x16x32_bf16 v[120:123], v[152:155], v[160:163], v[120:123]
	v_mfma_f32_16x16x32_bf16 v[108:111], v[140:143], v[168:171], v[108:111]
	v_mfma_f32_16x16x32_bf16 v[104:107], v[152:155], v[168:171], v[104:107]
	v_mfma_f32_16x16x32_bf16 v[100:103], v[140:143], v[176:179], v[100:103]
	v_mfma_f32_16x16x32_bf16 v[96:99], v[152:155], v[176:179], v[96:99]
	v_mfma_f32_16x16x32_bf16 v[76:79], v[140:143], v[184:187], v[76:79]
	v_mfma_f32_16x16x32_bf16 v[72:75], v[152:155], v[184:187], v[72:75]
	v_mfma_f32_16x16x32_bf16 v[124:127], v[144:147], v[164:167], v[124:127]
	v_mfma_f32_16x16x32_bf16 v[120:123], v[156:159], v[164:167], v[120:123]
	v_mfma_f32_16x16x32_bf16 v[108:111], v[144:147], v[172:175], v[108:111]
	v_mfma_f32_16x16x32_bf16 v[104:107], v[156:159], v[172:175], v[104:107]
	v_mfma_f32_16x16x32_bf16 v[100:103], v[144:147], v[180:183], v[100:103]
	v_mfma_f32_16x16x32_bf16 v[96:99], v[156:159], v[180:183], v[96:99]
	v_mfma_f32_16x16x32_bf16 v[76:79], v[144:147], v[188:191], v[76:79]
	v_mfma_f32_16x16x32_bf16 v[72:75], v[156:159], v[188:191], v[72:75]
	s_setprio 0
	s_barrier
	v_or_b32_e32 v139, 0x14000, v150
	s_mov_b32 m0, s36
	v_add_u32_e32 v151, 0x14400, v150
	ds_read_b128 v[206:209], v139
	ds_read_b128 v[210:213], v151
	v_add_u32_e32 v139, 0x14800, v150
	v_lshl_add_u64 v[218:219], s[6:7], 0, v[128:129]
	v_add_u32_e32 v151, 0x14c00, v150
	ds_read_b128 v[214:217], v139
	ds_read_b128 v[236:239], v151
	global_load_lds_dwordx4 v[218:219], off
	v_lshl_add_u64 v[228:229], s[6:7], 0, v[130:131]
	s_mov_b32 m0, s37
	s_nop 0
	global_load_lds_dwordx4 v[228:229], off
	s_barrier
	s_waitcnt lgkmcnt(0)
	s_setprio 1
	s_waitcnt lgkmcnt(0)
	v_mfma_f32_16x16x32_bf16 v[116:119], v[206:209], v[160:163], v[116:119]
	v_mfma_f32_16x16x32_bf16 v[112:115], v[214:217], v[160:163], v[112:115]
	v_mfma_f32_16x16x32_bf16 v[92:95], v[206:209], v[168:171], v[92:95]
	v_mfma_f32_16x16x32_bf16 v[88:91], v[214:217], v[168:171], v[88:91]
	v_mfma_f32_16x16x32_bf16 v[84:87], v[206:209], v[176:179], v[84:87]
	v_mfma_f32_16x16x32_bf16 v[80:83], v[214:217], v[176:179], v[80:83]
	v_mfma_f32_16x16x32_bf16 v[68:71], v[206:209], v[184:187], v[68:71]
	v_mfma_f32_16x16x32_bf16 v[64:67], v[214:217], v[184:187], v[64:67]
	v_mfma_f32_16x16x32_bf16 v[116:119], v[210:213], v[164:167], v[116:119]
	v_mfma_f32_16x16x32_bf16 v[112:115], v[236:239], v[164:167], v[112:115]
	v_mfma_f32_16x16x32_bf16 v[92:95], v[210:213], v[172:175], v[92:95]
	v_mfma_f32_16x16x32_bf16 v[88:91], v[236:239], v[172:175], v[88:91]
	v_mfma_f32_16x16x32_bf16 v[84:87], v[210:213], v[180:183], v[84:87]
	v_mfma_f32_16x16x32_bf16 v[80:83], v[236:239], v[180:183], v[80:83]
	v_mfma_f32_16x16x32_bf16 v[68:71], v[210:213], v[188:191], v[68:71]
	v_mfma_f32_16x16x32_bf16 v[64:67], v[236:239], v[188:191], v[64:67]
	s_setprio 0
	s_mov_b32 m0, s35
	v_lshl_add_u64 v[232:233], s[8:9], 0, v[128:129]
	s_barrier
	ds_read_b128 v[160:163], v149 offset:16384
	ds_read_b128 v[164:167], v149 offset:17408
	ds_read_b128 v[168:171], v149 offset:18432
	ds_read_b128 v[172:175], v149 offset:19456
	ds_read_b128 v[176:179], v149 offset:20480
	ds_read_b128 v[180:183], v149 offset:21504
	ds_read_b128 v[184:187], v149 offset:22528
	ds_read_b128 v[188:191], v149 offset:23552
	global_load_lds_dwordx4 v[232:233], off
	v_lshl_add_u64 v[240:241], s[8:9], 0, v[130:131]
	s_mov_b32 m0, s38
	s_nop 0
	global_load_lds_dwordx4 v[240:241], off
	s_barrier
	s_waitcnt lgkmcnt(0)
	s_setprio 1
	s_waitcnt lgkmcnt(0)
	v_mfma_f32_16x16x32_bf16 v[60:63], v[140:143], v[160:163], v[60:63]
	v_mfma_f32_16x16x32_bf16 v[56:59], v[152:155], v[160:163], v[56:59]
	v_mfma_f32_16x16x32_bf16 v[44:47], v[140:143], v[168:171], v[44:47]
	v_mfma_f32_16x16x32_bf16 v[40:43], v[152:155], v[168:171], v[40:43]
	v_mfma_f32_16x16x32_bf16 v[28:31], v[140:143], v[176:179], v[28:31]
	v_mfma_f32_16x16x32_bf16 v[24:27], v[152:155], v[176:179], v[24:27]
	v_mfma_f32_16x16x32_bf16 v[12:15], v[140:143], v[184:187], v[12:15]
	v_mfma_f32_16x16x32_bf16 v[8:11], v[152:155], v[184:187], v[8:11]
	v_mfma_f32_16x16x32_bf16 v[60:63], v[144:147], v[164:167], v[60:63]
	v_mfma_f32_16x16x32_bf16 v[56:59], v[156:159], v[164:167], v[56:59]
	v_mfma_f32_16x16x32_bf16 v[44:47], v[144:147], v[172:175], v[44:47]
	v_mfma_f32_16x16x32_bf16 v[40:43], v[156:159], v[172:175], v[40:43]
	v_mfma_f32_16x16x32_bf16 v[28:31], v[144:147], v[180:183], v[28:31]
	v_mfma_f32_16x16x32_bf16 v[24:27], v[156:159], v[180:183], v[24:27]
	v_mfma_f32_16x16x32_bf16 v[12:15], v[144:147], v[188:191], v[12:15]
	v_mfma_f32_16x16x32_bf16 v[8:11], v[156:159], v[188:191], v[8:11]
	s_setprio 0
	s_barrier
	s_add_u32 s74, s6, 0x40000
	s_addc_u32 s75, s7, 0
	s_mov_b32 m0, s39
	v_lshl_add_u64 v[140:141], s[74:75], 0, v[128:129]
	global_load_lds_dwordx4 v[140:141], off
	v_lshl_add_u64 v[140:141], s[74:75], 0, v[130:131]
	s_mov_b32 m0, s40
	s_nop 0
	global_load_lds_dwordx4 v[140:141], off
	s_waitcnt vmcnt(6)
	s_barrier
	s_setprio 1
	v_mfma_f32_16x16x32_bf16 v[52:55], v[206:209], v[160:163], v[52:55]
	v_mfma_f32_16x16x32_bf16 v[48:51], v[214:217], v[160:163], v[48:51]
	v_mfma_f32_16x16x32_bf16 v[36:39], v[206:209], v[168:171], v[36:39]
	v_mfma_f32_16x16x32_bf16 v[32:35], v[214:217], v[168:171], v[32:35]
	v_mfma_f32_16x16x32_bf16 v[20:23], v[206:209], v[176:179], v[20:23]
	v_mfma_f32_16x16x32_bf16 v[16:19], v[214:217], v[176:179], v[16:19]
	v_mfma_f32_16x16x32_bf16 v[4:7], v[206:209], v[184:187], v[4:7]
	v_mfma_f32_16x16x32_bf16 v[0:3], v[214:217], v[184:187], v[0:3]
	v_mfma_f32_16x16x32_bf16 v[52:55], v[210:213], v[164:167], v[52:55]
	v_mfma_f32_16x16x32_bf16 v[48:51], v[236:239], v[164:167], v[48:51]
	v_mfma_f32_16x16x32_bf16 v[36:39], v[210:213], v[172:175], v[36:39]
	v_mfma_f32_16x16x32_bf16 v[32:35], v[236:239], v[172:175], v[32:35]
	v_mfma_f32_16x16x32_bf16 v[20:23], v[210:213], v[180:183], v[20:23]
	v_mfma_f32_16x16x32_bf16 v[16:19], v[236:239], v[180:183], v[16:19]
	v_mfma_f32_16x16x32_bf16 v[4:7], v[210:213], v[188:191], v[4:7]
	v_mfma_f32_16x16x32_bf16 v[0:3], v[236:239], v[188:191], v[0:3]
	s_setprio 0
	v_or_b32_e32 v139, 0x18000, v150
	v_add_u32_e32 v144, 0x18400, v150
	s_barrier
	ds_read_b128 v[140:143], v139
	ds_read_b128 v[144:147], v144
	v_add_u32_e32 v139, 0x18800, v150
	v_add_u32_e32 v151, 0x18c00, v150
	ds_read_b128 v[152:155], v139
	ds_read_b128 v[156:159], v151
	s_add_u32 s8, s8, 0x40000
	s_addc_u32 s9, s9, 0
	s_mov_b32 m0, s41
	v_lshl_add_u64 v[206:207], s[8:9], 0, v[128:129]
	ds_read_b128 v[160:163], v149 offset:32768
	ds_read_b128 v[164:167], v149 offset:33792
	ds_read_b128 v[168:171], v149 offset:34816
	ds_read_b128 v[172:175], v149 offset:35840
	ds_read_b128 v[176:179], v149 offset:36864
	ds_read_b128 v[180:183], v149 offset:37888
	ds_read_b128 v[184:187], v149 offset:38912
	ds_read_b128 v[188:191], v149 offset:39936
	global_load_lds_dwordx4 v[206:207], off
	v_lshl_add_u64 v[206:207], s[8:9], 0, v[130:131]
	s_mov_b32 m0, s42
	s_nop 0
	global_load_lds_dwordx4 v[206:207], off
	s_waitcnt lgkmcnt(8)
	s_barrier
	s_waitcnt lgkmcnt(0)
	s_setprio 1
	s_waitcnt lgkmcnt(0)
	v_mfma_f32_16x16x32_bf16 v[124:127], v[140:143], v[160:163], v[124:127]
	v_mfma_f32_16x16x32_bf16 v[120:123], v[152:155], v[160:163], v[120:123]
	v_mfma_f32_16x16x32_bf16 v[108:111], v[140:143], v[168:171], v[108:111]
	v_mfma_f32_16x16x32_bf16 v[104:107], v[152:155], v[168:171], v[104:107]
	v_mfma_f32_16x16x32_bf16 v[100:103], v[140:143], v[176:179], v[100:103]
	v_mfma_f32_16x16x32_bf16 v[96:99], v[152:155], v[176:179], v[96:99]
	v_mfma_f32_16x16x32_bf16 v[76:79], v[140:143], v[184:187], v[76:79]
	v_mfma_f32_16x16x32_bf16 v[72:75], v[152:155], v[184:187], v[72:75]
	v_mfma_f32_16x16x32_bf16 v[124:127], v[144:147], v[164:167], v[124:127]
	v_mfma_f32_16x16x32_bf16 v[120:123], v[156:159], v[164:167], v[120:123]
	v_mfma_f32_16x16x32_bf16 v[108:111], v[144:147], v[172:175], v[108:111]
	v_mfma_f32_16x16x32_bf16 v[104:107], v[156:159], v[172:175], v[104:107]
	v_mfma_f32_16x16x32_bf16 v[100:103], v[144:147], v[180:183], v[100:103]
	v_mfma_f32_16x16x32_bf16 v[96:99], v[156:159], v[180:183], v[96:99]
	v_mfma_f32_16x16x32_bf16 v[76:79], v[144:147], v[188:191], v[76:79]
	v_mfma_f32_16x16x32_bf16 v[72:75], v[156:159], v[188:191], v[72:75]
	s_setprio 0
	s_barrier
	v_or_b32_e32 v139, 0x1c000, v150
	s_mov_b32 m0, s43
	v_add_u32_e32 v151, 0x1c400, v150
	ds_read_b128 v[206:209], v139
	ds_read_b128 v[210:213], v151
	v_add_u32_e32 v139, 0x1c800, v150
	v_lshl_add_u64 v[218:219], v[218:219], 0, s[94:95]
	v_add_u32_e32 v151, 0x1cc00, v150
	ds_read_b128 v[214:217], v139
	ds_read_b128 v[236:239], v151
	global_load_lds_dwordx4 v[218:219], off
	v_lshl_add_u64 v[218:219], v[228:229], 0, s[94:95]
	s_mov_b32 m0, s44
	s_nop 0
	global_load_lds_dwordx4 v[218:219], off
	s_barrier
	s_waitcnt lgkmcnt(0)
	s_setprio 1
	s_waitcnt lgkmcnt(0)
	v_mfma_f32_16x16x32_bf16 v[116:119], v[206:209], v[160:163], v[116:119]
	v_mfma_f32_16x16x32_bf16 v[112:115], v[214:217], v[160:163], v[112:115]
	v_mfma_f32_16x16x32_bf16 v[92:95], v[206:209], v[168:171], v[92:95]
	v_mfma_f32_16x16x32_bf16 v[88:91], v[214:217], v[168:171], v[88:91]
	v_mfma_f32_16x16x32_bf16 v[84:87], v[206:209], v[176:179], v[84:87]
	v_mfma_f32_16x16x32_bf16 v[80:83], v[214:217], v[176:179], v[80:83]
	v_mfma_f32_16x16x32_bf16 v[68:71], v[206:209], v[184:187], v[68:71]
	v_mfma_f32_16x16x32_bf16 v[64:67], v[214:217], v[184:187], v[64:67]
	v_mfma_f32_16x16x32_bf16 v[116:119], v[210:213], v[164:167], v[116:119]
	v_mfma_f32_16x16x32_bf16 v[112:115], v[236:239], v[164:167], v[112:115]
	v_mfma_f32_16x16x32_bf16 v[92:95], v[210:213], v[172:175], v[92:95]
	v_mfma_f32_16x16x32_bf16 v[88:91], v[236:239], v[172:175], v[88:91]
	v_mfma_f32_16x16x32_bf16 v[84:87], v[210:213], v[180:183], v[84:87]
	v_mfma_f32_16x16x32_bf16 v[80:83], v[236:239], v[180:183], v[80:83]
	v_mfma_f32_16x16x32_bf16 v[68:71], v[210:213], v[188:191], v[68:71]
	v_mfma_f32_16x16x32_bf16 v[64:67], v[236:239], v[188:191], v[64:67]
	s_setprio 0
	s_mov_b32 m0, s45
	v_lshl_add_u64 v[218:219], v[232:233], 0, s[94:95]
	s_barrier
	ds_read_b128 v[160:163], v149 offset:49152
	ds_read_b128 v[164:167], v149 offset:50176
	ds_read_b128 v[168:171], v149 offset:51200
	ds_read_b128 v[172:175], v149 offset:52224
	ds_read_b128 v[176:179], v149 offset:53248
	ds_read_b128 v[180:183], v149 offset:54272
	ds_read_b128 v[184:187], v149 offset:55296
	ds_read_b128 v[188:191], v149 offset:56320
	global_load_lds_dwordx4 v[218:219], off
	v_lshl_add_u64 v[218:219], v[240:241], 0, s[94:95]
	s_mov_b32 m0, s46
	s_nop 0
	global_load_lds_dwordx4 v[218:219], off
	s_barrier
	s_waitcnt lgkmcnt(0)
	s_setprio 1
	s_waitcnt lgkmcnt(0)
	v_mfma_f32_16x16x32_bf16 v[60:63], v[140:143], v[160:163], v[60:63]
	v_mfma_f32_16x16x32_bf16 v[56:59], v[152:155], v[160:163], v[56:59]
	v_mfma_f32_16x16x32_bf16 v[44:47], v[140:143], v[168:171], v[44:47]
	v_mfma_f32_16x16x32_bf16 v[40:43], v[152:155], v[168:171], v[40:43]
	v_mfma_f32_16x16x32_bf16 v[28:31], v[140:143], v[176:179], v[28:31]
	v_mfma_f32_16x16x32_bf16 v[24:27], v[152:155], v[176:179], v[24:27]
	v_mfma_f32_16x16x32_bf16 v[12:15], v[140:143], v[184:187], v[12:15]
	v_mfma_f32_16x16x32_bf16 v[8:11], v[152:155], v[184:187], v[8:11]
	v_mfma_f32_16x16x32_bf16 v[60:63], v[144:147], v[164:167], v[60:63]
	v_mfma_f32_16x16x32_bf16 v[56:59], v[156:159], v[164:167], v[56:59]
	v_mfma_f32_16x16x32_bf16 v[44:47], v[144:147], v[172:175], v[44:47]
	v_mfma_f32_16x16x32_bf16 v[40:43], v[156:159], v[172:175], v[40:43]
	v_mfma_f32_16x16x32_bf16 v[28:31], v[144:147], v[180:183], v[28:31]
	v_mfma_f32_16x16x32_bf16 v[24:27], v[156:159], v[180:183], v[24:27]
	v_mfma_f32_16x16x32_bf16 v[12:15], v[144:147], v[188:191], v[12:15]
	v_mfma_f32_16x16x32_bf16 v[8:11], v[156:159], v[188:191], v[8:11]
	s_setprio 0
	s_barrier
	s_add_u32 s6, s6, 0x40080
	s_addc_u32 s7, s7, 0
	s_mov_b32 m0, s47
	v_lshl_add_u64 v[140:141], s[6:7], 0, v[128:129]
	global_load_lds_dwordx4 v[140:141], off
	v_lshl_add_u64 v[140:141], s[6:7], 0, v[130:131]
	s_mov_b32 m0, s64
	s_nop 0
	global_load_lds_dwordx4 v[140:141], off
	s_waitcnt vmcnt(6)
	s_barrier
	s_setprio 1
	v_mfma_f32_16x16x32_bf16 v[52:55], v[206:209], v[160:163], v[52:55]
	v_mfma_f32_16x16x32_bf16 v[48:51], v[214:217], v[160:163], v[48:51]
	v_mfma_f32_16x16x32_bf16 v[36:39], v[206:209], v[168:171], v[36:39]
	v_mfma_f32_16x16x32_bf16 v[32:35], v[214:217], v[168:171], v[32:35]
	v_mfma_f32_16x16x32_bf16 v[20:23], v[206:209], v[176:179], v[20:23]
	v_mfma_f32_16x16x32_bf16 v[16:19], v[214:217], v[176:179], v[16:19]
	v_mfma_f32_16x16x32_bf16 v[4:7], v[206:209], v[184:187], v[4:7]
	v_mfma_f32_16x16x32_bf16 v[0:3], v[214:217], v[184:187], v[0:3]
	v_mfma_f32_16x16x32_bf16 v[52:55], v[210:213], v[164:167], v[52:55]
	v_mfma_f32_16x16x32_bf16 v[48:51], v[236:239], v[164:167], v[48:51]
	v_mfma_f32_16x16x32_bf16 v[36:39], v[210:213], v[172:175], v[36:39]
	v_mfma_f32_16x16x32_bf16 v[32:35], v[236:239], v[172:175], v[32:35]
	v_mfma_f32_16x16x32_bf16 v[20:23], v[210:213], v[180:183], v[20:23]
	v_mfma_f32_16x16x32_bf16 v[16:19], v[236:239], v[180:183], v[16:19]
	v_mfma_f32_16x16x32_bf16 v[4:7], v[210:213], v[188:191], v[4:7]
	v_mfma_f32_16x16x32_bf16 v[0:3], v[236:239], v[188:191], v[0:3]
	s_setprio 0
	s_add_i32 s70, s70, 2
	s_add_u32 s4, s4, 0x100
	s_addc_u32 s5, s5, 0
	s_add_u32 s29, s29, 0x100
	s_addc_u32 s69, s69, 0
	s_cmp_gt_u32 s70, 13
	s_barrier
	s_cbranch_scc0 .LBB0_138
	s_lshl_b32 s13, s24, 8
	s_cmp_gt_i32 s11, 1
	s_mov_b64 s[4:5], -1
	s_cbranch_scc0 .LBB0_429
	s_add_i32 s4, s11, -2
	s_cmp_eq_u32 s11, 7
	s_cselect_b32 s5, 1, 0
	s_add_i32 s4, s4, s5
	s_mul_i32 s4, s4, 0x2800000
	s_add_u32 s4, s4, 0x186d8000
	s_lshl_b32 s5, s13, 9
	v_readlane_b32 s6, v253, 1
	v_readlane_b32 s7, v253, 2
	v_lshrrev_b32_e32 v140, 6, v195
	v_lshrrev_b32_e32 v141, 2, v140
	v_and_b32_e32 v140, 3, v140
	v_and_b32_e32 v142, 15, v195
	v_bfe_u32 v143, v195, 4, 2
	s_add_u32 s6, s6, s4
	s_addc_u32 s7, s7, 0
	s_add_u32 s6, s6, s5
	s_addc_u32 s7, s7, 0
	v_lshl_add_u32 v141, v141, 6, v142
	v_lshlrev_b32_e32 v141, 9, v141
	v_lshl_add_u32 v141, v140, 6, v141
	v_lshl_add_u32 v141, v143, 3, v141
	v_and_b32_e32 v142, 1, v143
	v_mul_u32_u24_e32 v142, 24, v142
	v_add_u32_e32 v144, v141, v142
	s_cmp_eq_u32 s11, 2
	s_cbranch_scc1 .Lg1_silu
	s_cmp_eq_u32 s11, 4
	s_cbranch_scc1 .Lg1_sigmoid
	s_bitcmp1_b32 s11, 0
	s_cbranch_scc0 .Lg1_scale1
	s_cmp_eq_u32 s11, 3
	s_cbranch_scc1 .Lg1_scale1
	s_mov_b32 s26, 0x3e000000
	s_mov_b32 s8, s6
	s_mov_b32 s9, s7
	v_pk_mul_f32 v[152:153], v[124:125], s[26:27] op_sel_hi:[1,0]
	v_pk_mul_f32 v[154:155], v[126:127], s[26:27] op_sel_hi:[1,0]
	v_pk_mul_f32 v[156:157], v[120:121], s[26:27] op_sel_hi:[1,0]
	v_pk_mul_f32 v[158:159], v[122:123], s[26:27] op_sel_hi:[1,0]
	v_cvt_pk_bf16_f32 v160, v152, v153
	v_cvt_pk_bf16_f32 v161, v154, v155
	v_cvt_pk_bf16_f32 v162, v156, v157
	v_cvt_pk_bf16_f32 v163, v158, v159
	s_nop 1
	v_permlane16_swap_b32_e32 v160, v162
	v_permlane16_swap_b32_e32 v161, v163
	global_store_dwordx4 v144, v[160:163], s[8:9]
	v_pk_mul_f32 v[152:153], v[116:117], s[26:27] op_sel_hi:[1,0]
	v_pk_mul_f32 v[154:155], v[118:119], s[26:27] op_sel_hi:[1,0]
	v_pk_mul_f32 v[156:157], v[112:113], s[26:27] op_sel_hi:[1,0]
	v_pk_mul_f32 v[158:159], v[114:115], s[26:27] op_sel_hi:[1,0]
	v_cvt_pk_bf16_f32 v164, v152, v153
	v_cvt_pk_bf16_f32 v165, v154, v155
	v_cvt_pk_bf16_f32 v166, v156, v157
	v_cvt_pk_bf16_f32 v167, v158, v159
	s_nop 1
	v_permlane16_swap_b32_e32 v164, v166
	v_permlane16_swap_b32_e32 v165, v167
	global_store_dwordx4 v144, v[164:167], s[8:9] offset:256
	s_add_u32 s8, s6, 0x2000
	s_addc_u32 s9, s7, 0
	v_pk_mul_f32 v[152:153], v[108:109], s[26:27] op_sel_hi:[1,0]
	v_pk_mul_f32 v[154:155], v[110:111], s[26:27] op_sel_hi:[1,0]
	v_pk_mul_f32 v[156:157], v[104:105], s[26:27] op_sel_hi:[1,0]
	v_pk_mul_f32 v[158:159], v[106:107], s[26:27] op_sel_hi:[1,0]
	v_cvt_pk_bf16_f32 v160, v152, v153
	v_cvt_pk_bf16_f32 v161, v154, v155
	v_cvt_pk_bf16_f32 v162, v156, v157
	v_cvt_pk_bf16_f32 v163, v158, v159
	s_nop 1
	v_permlane16_swap_b32_e32 v160, v162
	v_permlane16_swap_b32_e32 v161, v163
	global_store_dwordx4 v144, v[160:163], s[8:9]
	v_pk_mul_f32 v[152:153], v[92:93], s[26:27] op_sel_hi:[1,0]
	v_pk_mul_f32 v[154:155], v[94:95], s[26:27] op_sel_hi:[1,0]
	v_pk_mul_f32 v[156:157], v[88:89], s[26:27] op_sel_hi:[1,0]
	v_pk_mul_f32 v[158:159], v[90:91], s[26:27] op_sel_hi:[1,0]
	v_cvt_pk_bf16_f32 v164, v152, v153
	v_cvt_pk_bf16_f32 v165, v154, v155
	v_cvt_pk_bf16_f32 v166, v156, v157
	v_cvt_pk_bf16_f32 v167, v158, v159
	s_nop 1
	v_permlane16_swap_b32_e32 v164, v166
	v_permlane16_swap_b32_e32 v165, v167
	global_store_dwordx4 v144, v[164:167], s[8:9] offset:256
	s_add_u32 s8, s6, 0x4000
	s_addc_u32 s9, s7, 0
	v_pk_mul_f32 v[152:153], v[100:101], s[26:27] op_sel_hi:[1,0]
	v_pk_mul_f32 v[154:155], v[102:103], s[26:27] op_sel_hi:[1,0]
	v_pk_mul_f32 v[156:157], v[96:97], s[26:27] op_sel_hi:[1,0]
	v_pk_mul_f32 v[158:159], v[98:99], s[26:27] op_sel_hi:[1,0]
	v_cvt_pk_bf16_f32 v160, v152, v153
	v_cvt_pk_bf16_f32 v161, v154, v155
	v_cvt_pk_bf16_f32 v162, v156, v157
	v_cvt_pk_bf16_f32 v163, v158, v159
	s_nop 1
	v_permlane16_swap_b32_e32 v160, v162
	v_permlane16_swap_b32_e32 v161, v163
	global_store_dwordx4 v144, v[160:163], s[8:9]
	v_pk_mul_f32 v[152:153], v[84:85], s[26:27] op_sel_hi:[1,0]
	v_pk_mul_f32 v[154:155], v[86:87], s[26:27] op_sel_hi:[1,0]
	v_pk_mul_f32 v[156:157], v[80:81], s[26:27] op_sel_hi:[1,0]
	v_pk_mul_f32 v[158:159], v[82:83], s[26:27] op_sel_hi:[1,0]
	v_cvt_pk_bf16_f32 v164, v152, v153
	v_cvt_pk_bf16_f32 v165, v154, v155
	v_cvt_pk_bf16_f32 v166, v156, v157
	v_cvt_pk_bf16_f32 v167, v158, v159
	s_nop 1
	v_permlane16_swap_b32_e32 v164, v166
	v_permlane16_swap_b32_e32 v165, v167
	global_store_dwordx4 v144, v[164:167], s[8:9] offset:256
	s_add_u32 s8, s6, 0x6000
	s_addc_u32 s9, s7, 0
	v_pk_mul_f32 v[152:153], v[76:77], s[26:27] op_sel_hi:[1,0]
	v_pk_mul_f32 v[154:155], v[78:79], s[26:27] op_sel_hi:[1,0]
	v_pk_mul_f32 v[156:157], v[72:73], s[26:27] op_sel_hi:[1,0]
	v_pk_mul_f32 v[158:159], v[74:75], s[26:27] op_sel_hi:[1,0]
	v_cvt_pk_bf16_f32 v160, v152, v153
	v_cvt_pk_bf16_f32 v161, v154, v155
	v_cvt_pk_bf16_f32 v162, v156, v157
	v_cvt_pk_bf16_f32 v163, v158, v159
	s_nop 1
	v_permlane16_swap_b32_e32 v160, v162
	v_permlane16_swap_b32_e32 v161, v163
	global_store_dwordx4 v144, v[160:163], s[8:9]
	v_pk_mul_f32 v[152:153], v[68:69], s[26:27] op_sel_hi:[1,0]
	v_pk_mul_f32 v[154:155], v[70:71], s[26:27] op_sel_hi:[1,0]
	v_pk_mul_f32 v[156:157], v[64:65], s[26:27] op_sel_hi:[1,0]
	v_pk_mul_f32 v[158:159], v[66:67], s[26:27] op_sel_hi:[1,0]
	v_cvt_pk_bf16_f32 v164, v152, v153
	v_cvt_pk_bf16_f32 v165, v154, v155
	v_cvt_pk_bf16_f32 v166, v156, v157
	v_cvt_pk_bf16_f32 v167, v158, v159
	s_nop 1
	v_permlane16_swap_b32_e32 v164, v166
	v_permlane16_swap_b32_e32 v165, v167
	global_store_dwordx4 v144, v[164:167], s[8:9] offset:256
	s_add_u32 s8, s6, 0x10000
	s_addc_u32 s9, s7, 0
	v_pk_mul_f32 v[152:153], v[60:61], s[26:27] op_sel_hi:[1,0]
	v_pk_mul_f32 v[154:155], v[62:63], s[26:27] op_sel_hi:[1,0]
	v_pk_mul_f32 v[156:157], v[56:57], s[26:27] op_sel_hi:[1,0]
	v_pk_mul_f32 v[158:159], v[58:59], s[26:27] op_sel_hi:[1,0]
	v_cvt_pk_bf16_f32 v160, v152, v153
	v_cvt_pk_bf16_f32 v161, v154, v155
	v_cvt_pk_bf16_f32 v162, v156, v157
	v_cvt_pk_bf16_f32 v163, v158, v159
	s_nop 1
	v_permlane16_swap_b32_e32 v160, v162
	v_permlane16_swap_b32_e32 v161, v163
	global_store_dwordx4 v144, v[160:163], s[8:9]
	v_pk_mul_f32 v[152:153], v[52:53], s[26:27] op_sel_hi:[1,0]
	v_pk_mul_f32 v[154:155], v[54:55], s[26:27] op_sel_hi:[1,0]
	v_pk_mul_f32 v[156:157], v[48:49], s[26:27] op_sel_hi:[1,0]
	v_pk_mul_f32 v[158:159], v[50:51], s[26:27] op_sel_hi:[1,0]
	v_cvt_pk_bf16_f32 v164, v152, v153
	v_cvt_pk_bf16_f32 v165, v154, v155
	v_cvt_pk_bf16_f32 v166, v156, v157
	v_cvt_pk_bf16_f32 v167, v158, v159
	s_nop 1
	v_permlane16_swap_b32_e32 v164, v166
	v_permlane16_swap_b32_e32 v165, v167
	global_store_dwordx4 v144, v[164:167], s[8:9] offset:256
	s_add_u32 s8, s6, 0x12000
	s_addc_u32 s9, s7, 0
	v_pk_mul_f32 v[152:153], v[44:45], s[26:27] op_sel_hi:[1,0]
	v_pk_mul_f32 v[154:155], v[46:47], s[26:27] op_sel_hi:[1,0]
	v_pk_mul_f32 v[156:157], v[40:41], s[26:27] op_sel_hi:[1,0]
	v_pk_mul_f32 v[158:159], v[42:43], s[26:27] op_sel_hi:[1,0]
	v_cvt_pk_bf16_f32 v160, v152, v153
	v_cvt_pk_bf16_f32 v161, v154, v155
	v_cvt_pk_bf16_f32 v162, v156, v157
	v_cvt_pk_bf16_f32 v163, v158, v159
	s_nop 1
	v_permlane16_swap_b32_e32 v160, v162
	v_permlane16_swap_b32_e32 v161, v163
	global_store_dwordx4 v144, v[160:163], s[8:9]
	v_pk_mul_f32 v[152:153], v[36:37], s[26:27] op_sel_hi:[1,0]
	v_pk_mul_f32 v[154:155], v[38:39], s[26:27] op_sel_hi:[1,0]
	v_pk_mul_f32 v[156:157], v[32:33], s[26:27] op_sel_hi:[1,0]
	v_pk_mul_f32 v[158:159], v[34:35], s[26:27] op_sel_hi:[1,0]
	v_cvt_pk_bf16_f32 v164, v152, v153
	v_cvt_pk_bf16_f32 v165, v154, v155
	v_cvt_pk_bf16_f32 v166, v156, v157
	v_cvt_pk_bf16_f32 v167, v158, v159
	s_nop 1
	v_permlane16_swap_b32_e32 v164, v166
	v_permlane16_swap_b32_e32 v165, v167
	global_store_dwordx4 v144, v[164:167], s[8:9] offset:256
	s_add_u32 s8, s6, 0x14000
	s_addc_u32 s9, s7, 0
	v_pk_mul_f32 v[152:153], v[28:29], s[26:27] op_sel_hi:[1,0]
	v_pk_mul_f32 v[154:155], v[30:31], s[26:27] op_sel_hi:[1,0]
	v_pk_mul_f32 v[156:157], v[24:25], s[26:27] op_sel_hi:[1,0]
	v_pk_mul_f32 v[158:159], v[26:27], s[26:27] op_sel_hi:[1,0]
	v_cvt_pk_bf16_f32 v160, v152, v153
	v_cvt_pk_bf16_f32 v161, v154, v155
	v_cvt_pk_bf16_f32 v162, v156, v157
	v_cvt_pk_bf16_f32 v163, v158, v159
	s_nop 1
	v_permlane16_swap_b32_e32 v160, v162
	v_permlane16_swap_b32_e32 v161, v163
	global_store_dwordx4 v144, v[160:163], s[8:9]
	v_pk_mul_f32 v[152:153], v[20:21], s[26:27] op_sel_hi:[1,0]
	v_pk_mul_f32 v[154:155], v[22:23], s[26:27] op_sel_hi:[1,0]
	v_pk_mul_f32 v[156:157], v[16:17], s[26:27] op_sel_hi:[1,0]
	v_pk_mul_f32 v[158:159], v[18:19], s[26:27] op_sel_hi:[1,0]
	v_cvt_pk_bf16_f32 v164, v152, v153
	v_cvt_pk_bf16_f32 v165, v154, v155
	v_cvt_pk_bf16_f32 v166, v156, v157
	v_cvt_pk_bf16_f32 v167, v158, v159
	s_nop 1
	v_permlane16_swap_b32_e32 v164, v166
	v_permlane16_swap_b32_e32 v165, v167
	global_store_dwordx4 v144, v[164:167], s[8:9] offset:256
	s_add_u32 s8, s6, 0x16000
	s_addc_u32 s9, s7, 0
	v_pk_mul_f32 v[152:153], v[12:13], s[26:27] op_sel_hi:[1,0]
	v_pk_mul_f32 v[154:155], v[14:15], s[26:27] op_sel_hi:[1,0]
	v_pk_mul_f32 v[156:157], v[8:9], s[26:27] op_sel_hi:[1,0]
	v_pk_mul_f32 v[158:159], v[10:11], s[26:27] op_sel_hi:[1,0]
	v_cvt_pk_bf16_f32 v160, v152, v153
	v_cvt_pk_bf16_f32 v161, v154, v155
	v_cvt_pk_bf16_f32 v162, v156, v157
	v_cvt_pk_bf16_f32 v163, v158, v159
	s_nop 1
	v_permlane16_swap_b32_e32 v160, v162
	v_permlane16_swap_b32_e32 v161, v163
	global_store_dwordx4 v144, v[160:163], s[8:9]
	v_pk_mul_f32 v[152:153], v[4:5], s[26:27] op_sel_hi:[1,0]
	v_pk_mul_f32 v[154:155], v[6:7], s[26:27] op_sel_hi:[1,0]
	v_pk_mul_f32 v[156:157], v[0:1], s[26:27] op_sel_hi:[1,0]
	v_pk_mul_f32 v[158:159], v[2:3], s[26:27] op_sel_hi:[1,0]
	v_cvt_pk_bf16_f32 v164, v152, v153
	v_cvt_pk_bf16_f32 v165, v154, v155
	v_cvt_pk_bf16_f32 v166, v156, v157
	v_cvt_pk_bf16_f32 v167, v158, v159
	s_nop 1
	v_permlane16_swap_b32_e32 v164, v166
	v_permlane16_swap_b32_e32 v165, v167
	global_store_dwordx4 v144, v[164:167], s[8:9] offset:256
	s_branch .Lg1_done
.Lg1_scale1:
	s_mov_b32 s8, s6
	s_mov_b32 s9, s7
	v_cvt_pk_bf16_f32 v160, v124, v125
	v_cvt_pk_bf16_f32 v161, v126, v127
	v_cvt_pk_bf16_f32 v162, v120, v121
	v_cvt_pk_bf16_f32 v163, v122, v123
	s_nop 1
	v_permlane16_swap_b32_e32 v160, v162
	v_permlane16_swap_b32_e32 v161, v163
	global_store_dwordx4 v144, v[160:163], s[8:9]
	v_cvt_pk_bf16_f32 v164, v116, v117
	v_cvt_pk_bf16_f32 v165, v118, v119
	v_cvt_pk_bf16_f32 v166, v112, v113
	v_cvt_pk_bf16_f32 v167, v114, v115
	s_nop 1
	v_permlane16_swap_b32_e32 v164, v166
	v_permlane16_swap_b32_e32 v165, v167
	global_store_dwordx4 v144, v[164:167], s[8:9] offset:256
	s_add_u32 s8, s6, 0x2000
	s_addc_u32 s9, s7, 0
	v_cvt_pk_bf16_f32 v160, v108, v109
	v_cvt_pk_bf16_f32 v161, v110, v111
	v_cvt_pk_bf16_f32 v162, v104, v105
	v_cvt_pk_bf16_f32 v163, v106, v107
	s_nop 1
	v_permlane16_swap_b32_e32 v160, v162
	v_permlane16_swap_b32_e32 v161, v163
	global_store_dwordx4 v144, v[160:163], s[8:9]
	v_cvt_pk_bf16_f32 v164, v92, v93
	v_cvt_pk_bf16_f32 v165, v94, v95
	v_cvt_pk_bf16_f32 v166, v88, v89
	v_cvt_pk_bf16_f32 v167, v90, v91
	s_nop 1
	v_permlane16_swap_b32_e32 v164, v166
	v_permlane16_swap_b32_e32 v165, v167
	global_store_dwordx4 v144, v[164:167], s[8:9] offset:256
	s_add_u32 s8, s6, 0x4000
	s_addc_u32 s9, s7, 0
	v_cvt_pk_bf16_f32 v160, v100, v101
	v_cvt_pk_bf16_f32 v161, v102, v103
	v_cvt_pk_bf16_f32 v162, v96, v97
	v_cvt_pk_bf16_f32 v163, v98, v99
	s_nop 1
	v_permlane16_swap_b32_e32 v160, v162
	v_permlane16_swap_b32_e32 v161, v163
	global_store_dwordx4 v144, v[160:163], s[8:9]
	v_cvt_pk_bf16_f32 v164, v84, v85
	v_cvt_pk_bf16_f32 v165, v86, v87
	v_cvt_pk_bf16_f32 v166, v80, v81
	v_cvt_pk_bf16_f32 v167, v82, v83
	s_nop 1
	v_permlane16_swap_b32_e32 v164, v166
	v_permlane16_swap_b32_e32 v165, v167
	global_store_dwordx4 v144, v[164:167], s[8:9] offset:256
	s_add_u32 s8, s6, 0x6000
	s_addc_u32 s9, s7, 0
	v_cvt_pk_bf16_f32 v160, v76, v77
	v_cvt_pk_bf16_f32 v161, v78, v79
	v_cvt_pk_bf16_f32 v162, v72, v73
	v_cvt_pk_bf16_f32 v163, v74, v75
	s_nop 1
	v_permlane16_swap_b32_e32 v160, v162
	v_permlane16_swap_b32_e32 v161, v163
	global_store_dwordx4 v144, v[160:163], s[8:9]
	v_cvt_pk_bf16_f32 v164, v68, v69
	v_cvt_pk_bf16_f32 v165, v70, v71
	v_cvt_pk_bf16_f32 v166, v64, v65
	v_cvt_pk_bf16_f32 v167, v66, v67
	s_nop 1
	v_permlane16_swap_b32_e32 v164, v166
	v_permlane16_swap_b32_e32 v165, v167
	global_store_dwordx4 v144, v[164:167], s[8:9] offset:256
	s_add_u32 s8, s6, 0x10000
	s_addc_u32 s9, s7, 0
	v_cvt_pk_bf16_f32 v160, v60, v61
	v_cvt_pk_bf16_f32 v161, v62, v63
	v_cvt_pk_bf16_f32 v162, v56, v57
	v_cvt_pk_bf16_f32 v163, v58, v59
	s_nop 1
	v_permlane16_swap_b32_e32 v160, v162
	v_permlane16_swap_b32_e32 v161, v163
	global_store_dwordx4 v144, v[160:163], s[8:9]
	v_cvt_pk_bf16_f32 v164, v52, v53
	v_cvt_pk_bf16_f32 v165, v54, v55
	v_cvt_pk_bf16_f32 v166, v48, v49
	v_cvt_pk_bf16_f32 v167, v50, v51
	s_nop 1
	v_permlane16_swap_b32_e32 v164, v166
	v_permlane16_swap_b32_e32 v165, v167
	global_store_dwordx4 v144, v[164:167], s[8:9] offset:256
	s_add_u32 s8, s6, 0x12000
	s_addc_u32 s9, s7, 0
	v_cvt_pk_bf16_f32 v160, v44, v45
	v_cvt_pk_bf16_f32 v161, v46, v47
	v_cvt_pk_bf16_f32 v162, v40, v41
	v_cvt_pk_bf16_f32 v163, v42, v43
	s_nop 1
	v_permlane16_swap_b32_e32 v160, v162
	v_permlane16_swap_b32_e32 v161, v163
	global_store_dwordx4 v144, v[160:163], s[8:9]
	v_cvt_pk_bf16_f32 v164, v36, v37
	v_cvt_pk_bf16_f32 v165, v38, v39
	v_cvt_pk_bf16_f32 v166, v32, v33
	v_cvt_pk_bf16_f32 v167, v34, v35
	s_nop 1
	v_permlane16_swap_b32_e32 v164, v166
	v_permlane16_swap_b32_e32 v165, v167
	global_store_dwordx4 v144, v[164:167], s[8:9] offset:256
	s_add_u32 s8, s6, 0x14000
	s_addc_u32 s9, s7, 0
	v_cvt_pk_bf16_f32 v160, v28, v29
	v_cvt_pk_bf16_f32 v161, v30, v31
	v_cvt_pk_bf16_f32 v162, v24, v25
	v_cvt_pk_bf16_f32 v163, v26, v27
	s_nop 1
	v_permlane16_swap_b32_e32 v160, v162
	v_permlane16_swap_b32_e32 v161, v163
	global_store_dwordx4 v144, v[160:163], s[8:9]
	v_cvt_pk_bf16_f32 v164, v20, v21
	v_cvt_pk_bf16_f32 v165, v22, v23
	v_cvt_pk_bf16_f32 v166, v16, v17
	v_cvt_pk_bf16_f32 v167, v18, v19
	s_nop 1
	v_permlane16_swap_b32_e32 v164, v166
	v_permlane16_swap_b32_e32 v165, v167
	global_store_dwordx4 v144, v[164:167], s[8:9] offset:256
	s_add_u32 s8, s6, 0x16000
	s_addc_u32 s9, s7, 0
	v_cvt_pk_bf16_f32 v160, v12, v13
	v_cvt_pk_bf16_f32 v161, v14, v15
	v_cvt_pk_bf16_f32 v162, v8, v9
	v_cvt_pk_bf16_f32 v163, v10, v11
	s_nop 1
	v_permlane16_swap_b32_e32 v160, v162
	v_permlane16_swap_b32_e32 v161, v163
	global_store_dwordx4 v144, v[160:163], s[8:9]
	v_cvt_pk_bf16_f32 v164, v4, v5
	v_cvt_pk_bf16_f32 v165, v6, v7
	v_cvt_pk_bf16_f32 v166, v0, v1
	v_cvt_pk_bf16_f32 v167, v2, v3
	s_nop 1
	v_permlane16_swap_b32_e32 v164, v166
	v_permlane16_swap_b32_e32 v165, v167
	global_store_dwordx4 v144, v[164:167], s[8:9] offset:256
	s_branch .Lg1_done
.Lg1_silu:
	s_mov_b32 s8, s6
	s_mov_b32 s9, s7
	v_mul_f32_e32 v152, 0xbfb8aa3b, v124
	v_mul_f32_e32 v153, 0xbfb8aa3b, v125
	v_mul_f32_e32 v154, 0xbfb8aa3b, v126
	v_mul_f32_e32 v155, 0xbfb8aa3b, v127
	v_mul_f32_e32 v156, 0xbfb8aa3b, v120
	v_mul_f32_e32 v157, 0xbfb8aa3b, v121
	v_mul_f32_e32 v158, 0xbfb8aa3b, v122
	v_mul_f32_e32 v159, 0xbfb8aa3b, v123
	v_exp_f32_e32 v152, v152
	v_exp_f32_e32 v153, v153
	v_exp_f32_e32 v154, v154
	v_exp_f32_e32 v155, v155
	v_exp_f32_e32 v156, v156
	v_exp_f32_e32 v157, v157
	v_exp_f32_e32 v158, v158
	v_exp_f32_e32 v159, v159
	v_add_f32_e32 v152, 1.0, v152
	v_add_f32_e32 v153, 1.0, v153
	v_add_f32_e32 v154, 1.0, v154
	v_add_f32_e32 v155, 1.0, v155
	v_add_f32_e32 v156, 1.0, v156
	v_add_f32_e32 v157, 1.0, v157
	v_add_f32_e32 v158, 1.0, v158
	v_add_f32_e32 v159, 1.0, v159
	v_rcp_f32_e32 v152, v152
	v_rcp_f32_e32 v153, v153
	v_rcp_f32_e32 v154, v154
	v_rcp_f32_e32 v155, v155
	v_rcp_f32_e32 v156, v156
	v_rcp_f32_e32 v157, v157
	v_rcp_f32_e32 v158, v158
	v_rcp_f32_e32 v159, v159
	v_pk_mul_f32 v[152:153], v[124:125], v[152:153]
	v_pk_mul_f32 v[154:155], v[126:127], v[154:155]
	v_pk_mul_f32 v[156:157], v[120:121], v[156:157]
	v_pk_mul_f32 v[158:159], v[122:123], v[158:159]
	v_cvt_pk_bf16_f32 v160, v152, v153
	v_cvt_pk_bf16_f32 v161, v154, v155
	v_cvt_pk_bf16_f32 v162, v156, v157
	v_cvt_pk_bf16_f32 v163, v158, v159
	s_nop 1
	v_permlane16_swap_b32_e32 v160, v162
	v_permlane16_swap_b32_e32 v161, v163
	global_store_dwordx4 v144, v[160:163], s[8:9]
	v_mul_f32_e32 v152, 0xbfb8aa3b, v116
	v_mul_f32_e32 v153, 0xbfb8aa3b, v117
	v_mul_f32_e32 v154, 0xbfb8aa3b, v118
	v_mul_f32_e32 v155, 0xbfb8aa3b, v119
	v_mul_f32_e32 v156, 0xbfb8aa3b, v112
	v_mul_f32_e32 v157, 0xbfb8aa3b, v113
	v_mul_f32_e32 v158, 0xbfb8aa3b, v114
	v_mul_f32_e32 v159, 0xbfb8aa3b, v115
	v_exp_f32_e32 v152, v152
	v_exp_f32_e32 v153, v153
	v_exp_f32_e32 v154, v154
	v_exp_f32_e32 v155, v155
	v_exp_f32_e32 v156, v156
	v_exp_f32_e32 v157, v157
	v_exp_f32_e32 v158, v158
	v_exp_f32_e32 v159, v159
	v_add_f32_e32 v152, 1.0, v152
	v_add_f32_e32 v153, 1.0, v153
	v_add_f32_e32 v154, 1.0, v154
	v_add_f32_e32 v155, 1.0, v155
	v_add_f32_e32 v156, 1.0, v156
	v_add_f32_e32 v157, 1.0, v157
	v_add_f32_e32 v158, 1.0, v158
	v_add_f32_e32 v159, 1.0, v159
	v_rcp_f32_e32 v152, v152
	v_rcp_f32_e32 v153, v153
	v_rcp_f32_e32 v154, v154
	v_rcp_f32_e32 v155, v155
	v_rcp_f32_e32 v156, v156
	v_rcp_f32_e32 v157, v157
	v_rcp_f32_e32 v158, v158
	v_rcp_f32_e32 v159, v159
	v_pk_mul_f32 v[152:153], v[116:117], v[152:153]
	v_pk_mul_f32 v[154:155], v[118:119], v[154:155]
	v_pk_mul_f32 v[156:157], v[112:113], v[156:157]
	v_pk_mul_f32 v[158:159], v[114:115], v[158:159]
	v_cvt_pk_bf16_f32 v164, v152, v153
	v_cvt_pk_bf16_f32 v165, v154, v155
	v_cvt_pk_bf16_f32 v166, v156, v157
	v_cvt_pk_bf16_f32 v167, v158, v159
	s_nop 1
	v_permlane16_swap_b32_e32 v164, v166
	v_permlane16_swap_b32_e32 v165, v167
	global_store_dwordx4 v144, v[164:167], s[8:9] offset:256
	s_add_u32 s8, s6, 0x2000
	s_addc_u32 s9, s7, 0
	v_mul_f32_e32 v152, 0xbfb8aa3b, v108
	v_mul_f32_e32 v153, 0xbfb8aa3b, v109
	v_mul_f32_e32 v154, 0xbfb8aa3b, v110
	v_mul_f32_e32 v155, 0xbfb8aa3b, v111
	v_mul_f32_e32 v156, 0xbfb8aa3b, v104
	v_mul_f32_e32 v157, 0xbfb8aa3b, v105
	v_mul_f32_e32 v158, 0xbfb8aa3b, v106
	v_mul_f32_e32 v159, 0xbfb8aa3b, v107
	v_exp_f32_e32 v152, v152
	v_exp_f32_e32 v153, v153
	v_exp_f32_e32 v154, v154
	v_exp_f32_e32 v155, v155
	v_exp_f32_e32 v156, v156
	v_exp_f32_e32 v157, v157
	v_exp_f32_e32 v158, v158
	v_exp_f32_e32 v159, v159
	v_add_f32_e32 v152, 1.0, v152
	v_add_f32_e32 v153, 1.0, v153
	v_add_f32_e32 v154, 1.0, v154
	v_add_f32_e32 v155, 1.0, v155
	v_add_f32_e32 v156, 1.0, v156
	v_add_f32_e32 v157, 1.0, v157
	v_add_f32_e32 v158, 1.0, v158
	v_add_f32_e32 v159, 1.0, v159
	v_rcp_f32_e32 v152, v152
	v_rcp_f32_e32 v153, v153
	v_rcp_f32_e32 v154, v154
	v_rcp_f32_e32 v155, v155
	v_rcp_f32_e32 v156, v156
	v_rcp_f32_e32 v157, v157
	v_rcp_f32_e32 v158, v158
	v_rcp_f32_e32 v159, v159
	v_pk_mul_f32 v[152:153], v[108:109], v[152:153]
	v_pk_mul_f32 v[154:155], v[110:111], v[154:155]
	v_pk_mul_f32 v[156:157], v[104:105], v[156:157]
	v_pk_mul_f32 v[158:159], v[106:107], v[158:159]
	v_cvt_pk_bf16_f32 v160, v152, v153
	v_cvt_pk_bf16_f32 v161, v154, v155
	v_cvt_pk_bf16_f32 v162, v156, v157
	v_cvt_pk_bf16_f32 v163, v158, v159
	s_nop 1
	v_permlane16_swap_b32_e32 v160, v162
	v_permlane16_swap_b32_e32 v161, v163
	global_store_dwordx4 v144, v[160:163], s[8:9]
	v_mul_f32_e32 v152, 0xbfb8aa3b, v92
	v_mul_f32_e32 v153, 0xbfb8aa3b, v93
	v_mul_f32_e32 v154, 0xbfb8aa3b, v94
	v_mul_f32_e32 v155, 0xbfb8aa3b, v95
	v_mul_f32_e32 v156, 0xbfb8aa3b, v88
	v_mul_f32_e32 v157, 0xbfb8aa3b, v89
	v_mul_f32_e32 v158, 0xbfb8aa3b, v90
	v_mul_f32_e32 v159, 0xbfb8aa3b, v91
	v_exp_f32_e32 v152, v152
	v_exp_f32_e32 v153, v153
	v_exp_f32_e32 v154, v154
	v_exp_f32_e32 v155, v155
	v_exp_f32_e32 v156, v156
	v_exp_f32_e32 v157, v157
	v_exp_f32_e32 v158, v158
	v_exp_f32_e32 v159, v159
	v_add_f32_e32 v152, 1.0, v152
	v_add_f32_e32 v153, 1.0, v153
	v_add_f32_e32 v154, 1.0, v154
	v_add_f32_e32 v155, 1.0, v155
	v_add_f32_e32 v156, 1.0, v156
	v_add_f32_e32 v157, 1.0, v157
	v_add_f32_e32 v158, 1.0, v158
	v_add_f32_e32 v159, 1.0, v159
	v_rcp_f32_e32 v152, v152
	v_rcp_f32_e32 v153, v153
	v_rcp_f32_e32 v154, v154
	v_rcp_f32_e32 v155, v155
	v_rcp_f32_e32 v156, v156
	v_rcp_f32_e32 v157, v157
	v_rcp_f32_e32 v158, v158
	v_rcp_f32_e32 v159, v159
	v_pk_mul_f32 v[152:153], v[92:93], v[152:153]
	v_pk_mul_f32 v[154:155], v[94:95], v[154:155]
	v_pk_mul_f32 v[156:157], v[88:89], v[156:157]
	v_pk_mul_f32 v[158:159], v[90:91], v[158:159]
	v_cvt_pk_bf16_f32 v164, v152, v153
	v_cvt_pk_bf16_f32 v165, v154, v155
	v_cvt_pk_bf16_f32 v166, v156, v157
	v_cvt_pk_bf16_f32 v167, v158, v159
	s_nop 1
	v_permlane16_swap_b32_e32 v164, v166
	v_permlane16_swap_b32_e32 v165, v167
	global_store_dwordx4 v144, v[164:167], s[8:9] offset:256
	s_add_u32 s8, s6, 0x4000
	s_addc_u32 s9, s7, 0
	v_mul_f32_e32 v152, 0xbfb8aa3b, v100
	v_mul_f32_e32 v153, 0xbfb8aa3b, v101
	v_mul_f32_e32 v154, 0xbfb8aa3b, v102
	v_mul_f32_e32 v155, 0xbfb8aa3b, v103
	v_mul_f32_e32 v156, 0xbfb8aa3b, v96
	v_mul_f32_e32 v157, 0xbfb8aa3b, v97
	v_mul_f32_e32 v158, 0xbfb8aa3b, v98
	v_mul_f32_e32 v159, 0xbfb8aa3b, v99
	v_exp_f32_e32 v152, v152
	v_exp_f32_e32 v153, v153
	v_exp_f32_e32 v154, v154
	v_exp_f32_e32 v155, v155
	v_exp_f32_e32 v156, v156
	v_exp_f32_e32 v157, v157
	v_exp_f32_e32 v158, v158
	v_exp_f32_e32 v159, v159
	v_add_f32_e32 v152, 1.0, v152
	v_add_f32_e32 v153, 1.0, v153
	v_add_f32_e32 v154, 1.0, v154
	v_add_f32_e32 v155, 1.0, v155
	v_add_f32_e32 v156, 1.0, v156
	v_add_f32_e32 v157, 1.0, v157
	v_add_f32_e32 v158, 1.0, v158
	v_add_f32_e32 v159, 1.0, v159
	v_rcp_f32_e32 v152, v152
	v_rcp_f32_e32 v153, v153
	v_rcp_f32_e32 v154, v154
	v_rcp_f32_e32 v155, v155
	v_rcp_f32_e32 v156, v156
	v_rcp_f32_e32 v157, v157
	v_rcp_f32_e32 v158, v158
	v_rcp_f32_e32 v159, v159
	v_pk_mul_f32 v[152:153], v[100:101], v[152:153]
	v_pk_mul_f32 v[154:155], v[102:103], v[154:155]
	v_pk_mul_f32 v[156:157], v[96:97], v[156:157]
	v_pk_mul_f32 v[158:159], v[98:99], v[158:159]
	v_cvt_pk_bf16_f32 v160, v152, v153
	v_cvt_pk_bf16_f32 v161, v154, v155
	v_cvt_pk_bf16_f32 v162, v156, v157
	v_cvt_pk_bf16_f32 v163, v158, v159
	s_nop 1
	v_permlane16_swap_b32_e32 v160, v162
	v_permlane16_swap_b32_e32 v161, v163
	global_store_dwordx4 v144, v[160:163], s[8:9]
	v_mul_f32_e32 v152, 0xbfb8aa3b, v84
	v_mul_f32_e32 v153, 0xbfb8aa3b, v85
	v_mul_f32_e32 v154, 0xbfb8aa3b, v86
	v_mul_f32_e32 v155, 0xbfb8aa3b, v87
	v_mul_f32_e32 v156, 0xbfb8aa3b, v80
	v_mul_f32_e32 v157, 0xbfb8aa3b, v81
	v_mul_f32_e32 v158, 0xbfb8aa3b, v82
	v_mul_f32_e32 v159, 0xbfb8aa3b, v83
	v_exp_f32_e32 v152, v152
	v_exp_f32_e32 v153, v153
	v_exp_f32_e32 v154, v154
	v_exp_f32_e32 v155, v155
	v_exp_f32_e32 v156, v156
	v_exp_f32_e32 v157, v157
	v_exp_f32_e32 v158, v158
	v_exp_f32_e32 v159, v159
	v_add_f32_e32 v152, 1.0, v152
	v_add_f32_e32 v153, 1.0, v153
	v_add_f32_e32 v154, 1.0, v154
	v_add_f32_e32 v155, 1.0, v155
	v_add_f32_e32 v156, 1.0, v156
	v_add_f32_e32 v157, 1.0, v157
	v_add_f32_e32 v158, 1.0, v158
	v_add_f32_e32 v159, 1.0, v159
	v_rcp_f32_e32 v152, v152
	v_rcp_f32_e32 v153, v153
	v_rcp_f32_e32 v154, v154
	v_rcp_f32_e32 v155, v155
	v_rcp_f32_e32 v156, v156
	v_rcp_f32_e32 v157, v157
	v_rcp_f32_e32 v158, v158
	v_rcp_f32_e32 v159, v159
	v_pk_mul_f32 v[152:153], v[84:85], v[152:153]
	v_pk_mul_f32 v[154:155], v[86:87], v[154:155]
	v_pk_mul_f32 v[156:157], v[80:81], v[156:157]
	v_pk_mul_f32 v[158:159], v[82:83], v[158:159]
	v_cvt_pk_bf16_f32 v164, v152, v153
	v_cvt_pk_bf16_f32 v165, v154, v155
	v_cvt_pk_bf16_f32 v166, v156, v157
	v_cvt_pk_bf16_f32 v167, v158, v159
	s_nop 1
	v_permlane16_swap_b32_e32 v164, v166
	v_permlane16_swap_b32_e32 v165, v167
	global_store_dwordx4 v144, v[164:167], s[8:9] offset:256
	s_add_u32 s8, s6, 0x6000
	s_addc_u32 s9, s7, 0
	v_mul_f32_e32 v152, 0xbfb8aa3b, v76
	v_mul_f32_e32 v153, 0xbfb8aa3b, v77
	v_mul_f32_e32 v154, 0xbfb8aa3b, v78
	v_mul_f32_e32 v155, 0xbfb8aa3b, v79
	v_mul_f32_e32 v156, 0xbfb8aa3b, v72
	v_mul_f32_e32 v157, 0xbfb8aa3b, v73
	v_mul_f32_e32 v158, 0xbfb8aa3b, v74
	v_mul_f32_e32 v159, 0xbfb8aa3b, v75
	v_exp_f32_e32 v152, v152
	v_exp_f32_e32 v153, v153
	v_exp_f32_e32 v154, v154
	v_exp_f32_e32 v155, v155
	v_exp_f32_e32 v156, v156
	v_exp_f32_e32 v157, v157
	v_exp_f32_e32 v158, v158
	v_exp_f32_e32 v159, v159
	v_add_f32_e32 v152, 1.0, v152
	v_add_f32_e32 v153, 1.0, v153
	v_add_f32_e32 v154, 1.0, v154
	v_add_f32_e32 v155, 1.0, v155
	v_add_f32_e32 v156, 1.0, v156
	v_add_f32_e32 v157, 1.0, v157
	v_add_f32_e32 v158, 1.0, v158
	v_add_f32_e32 v159, 1.0, v159
	v_rcp_f32_e32 v152, v152
	v_rcp_f32_e32 v153, v153
	v_rcp_f32_e32 v154, v154
	v_rcp_f32_e32 v155, v155
	v_rcp_f32_e32 v156, v156
	v_rcp_f32_e32 v157, v157
	v_rcp_f32_e32 v158, v158
	v_rcp_f32_e32 v159, v159
	v_pk_mul_f32 v[152:153], v[76:77], v[152:153]
	v_pk_mul_f32 v[154:155], v[78:79], v[154:155]
	v_pk_mul_f32 v[156:157], v[72:73], v[156:157]
	v_pk_mul_f32 v[158:159], v[74:75], v[158:159]
	v_cvt_pk_bf16_f32 v160, v152, v153
	v_cvt_pk_bf16_f32 v161, v154, v155
	v_cvt_pk_bf16_f32 v162, v156, v157
	v_cvt_pk_bf16_f32 v163, v158, v159
	s_nop 1
	v_permlane16_swap_b32_e32 v160, v162
	v_permlane16_swap_b32_e32 v161, v163
	global_store_dwordx4 v144, v[160:163], s[8:9]
	v_mul_f32_e32 v152, 0xbfb8aa3b, v68
	v_mul_f32_e32 v153, 0xbfb8aa3b, v69
	v_mul_f32_e32 v154, 0xbfb8aa3b, v70
	v_mul_f32_e32 v155, 0xbfb8aa3b, v71
	v_mul_f32_e32 v156, 0xbfb8aa3b, v64
	v_mul_f32_e32 v157, 0xbfb8aa3b, v65
	v_mul_f32_e32 v158, 0xbfb8aa3b, v66
	v_mul_f32_e32 v159, 0xbfb8aa3b, v67
	v_exp_f32_e32 v152, v152
	v_exp_f32_e32 v153, v153
	v_exp_f32_e32 v154, v154
	v_exp_f32_e32 v155, v155
	v_exp_f32_e32 v156, v156
	v_exp_f32_e32 v157, v157
	v_exp_f32_e32 v158, v158
	v_exp_f32_e32 v159, v159
	v_add_f32_e32 v152, 1.0, v152
	v_add_f32_e32 v153, 1.0, v153
	v_add_f32_e32 v154, 1.0, v154
	v_add_f32_e32 v155, 1.0, v155
	v_add_f32_e32 v156, 1.0, v156
	v_add_f32_e32 v157, 1.0, v157
	v_add_f32_e32 v158, 1.0, v158
	v_add_f32_e32 v159, 1.0, v159
	v_rcp_f32_e32 v152, v152
	v_rcp_f32_e32 v153, v153
	v_rcp_f32_e32 v154, v154
	v_rcp_f32_e32 v155, v155
	v_rcp_f32_e32 v156, v156
	v_rcp_f32_e32 v157, v157
	v_rcp_f32_e32 v158, v158
	v_rcp_f32_e32 v159, v159
	v_pk_mul_f32 v[152:153], v[68:69], v[152:153]
	v_pk_mul_f32 v[154:155], v[70:71], v[154:155]
	v_pk_mul_f32 v[156:157], v[64:65], v[156:157]
	v_pk_mul_f32 v[158:159], v[66:67], v[158:159]
	v_cvt_pk_bf16_f32 v164, v152, v153
	v_cvt_pk_bf16_f32 v165, v154, v155
	v_cvt_pk_bf16_f32 v166, v156, v157
	v_cvt_pk_bf16_f32 v167, v158, v159
	s_nop 1
	v_permlane16_swap_b32_e32 v164, v166
	v_permlane16_swap_b32_e32 v165, v167
	global_store_dwordx4 v144, v[164:167], s[8:9] offset:256
	s_add_u32 s8, s6, 0x10000
	s_addc_u32 s9, s7, 0
	v_mul_f32_e32 v152, 0xbfb8aa3b, v60
	v_mul_f32_e32 v153, 0xbfb8aa3b, v61
	v_mul_f32_e32 v154, 0xbfb8aa3b, v62
	v_mul_f32_e32 v155, 0xbfb8aa3b, v63
	v_mul_f32_e32 v156, 0xbfb8aa3b, v56
	v_mul_f32_e32 v157, 0xbfb8aa3b, v57
	v_mul_f32_e32 v158, 0xbfb8aa3b, v58
	v_mul_f32_e32 v159, 0xbfb8aa3b, v59
	v_exp_f32_e32 v152, v152
	v_exp_f32_e32 v153, v153
	v_exp_f32_e32 v154, v154
	v_exp_f32_e32 v155, v155
	v_exp_f32_e32 v156, v156
	v_exp_f32_e32 v157, v157
	v_exp_f32_e32 v158, v158
	v_exp_f32_e32 v159, v159
	v_add_f32_e32 v152, 1.0, v152
	v_add_f32_e32 v153, 1.0, v153
	v_add_f32_e32 v154, 1.0, v154
	v_add_f32_e32 v155, 1.0, v155
	v_add_f32_e32 v156, 1.0, v156
	v_add_f32_e32 v157, 1.0, v157
	v_add_f32_e32 v158, 1.0, v158
	v_add_f32_e32 v159, 1.0, v159
	v_rcp_f32_e32 v152, v152
	v_rcp_f32_e32 v153, v153
	v_rcp_f32_e32 v154, v154
	v_rcp_f32_e32 v155, v155
	v_rcp_f32_e32 v156, v156
	v_rcp_f32_e32 v157, v157
	v_rcp_f32_e32 v158, v158
	v_rcp_f32_e32 v159, v159
	v_pk_mul_f32 v[152:153], v[60:61], v[152:153]
	v_pk_mul_f32 v[154:155], v[62:63], v[154:155]
	v_pk_mul_f32 v[156:157], v[56:57], v[156:157]
	v_pk_mul_f32 v[158:159], v[58:59], v[158:159]
	v_cvt_pk_bf16_f32 v160, v152, v153
	v_cvt_pk_bf16_f32 v161, v154, v155
	v_cvt_pk_bf16_f32 v162, v156, v157
	v_cvt_pk_bf16_f32 v163, v158, v159
	s_nop 1
	v_permlane16_swap_b32_e32 v160, v162
	v_permlane16_swap_b32_e32 v161, v163
	global_store_dwordx4 v144, v[160:163], s[8:9]
	v_mul_f32_e32 v152, 0xbfb8aa3b, v52
	v_mul_f32_e32 v153, 0xbfb8aa3b, v53
	v_mul_f32_e32 v154, 0xbfb8aa3b, v54
	v_mul_f32_e32 v155, 0xbfb8aa3b, v55
	v_mul_f32_e32 v156, 0xbfb8aa3b, v48
	v_mul_f32_e32 v157, 0xbfb8aa3b, v49
	v_mul_f32_e32 v158, 0xbfb8aa3b, v50
	v_mul_f32_e32 v159, 0xbfb8aa3b, v51
	v_exp_f32_e32 v152, v152
	v_exp_f32_e32 v153, v153
	v_exp_f32_e32 v154, v154
	v_exp_f32_e32 v155, v155
	v_exp_f32_e32 v156, v156
	v_exp_f32_e32 v157, v157
	v_exp_f32_e32 v158, v158
	v_exp_f32_e32 v159, v159
	v_add_f32_e32 v152, 1.0, v152
	v_add_f32_e32 v153, 1.0, v153
	v_add_f32_e32 v154, 1.0, v154
	v_add_f32_e32 v155, 1.0, v155
	v_add_f32_e32 v156, 1.0, v156
	v_add_f32_e32 v157, 1.0, v157
	v_add_f32_e32 v158, 1.0, v158
	v_add_f32_e32 v159, 1.0, v159
	v_rcp_f32_e32 v152, v152
	v_rcp_f32_e32 v153, v153
	v_rcp_f32_e32 v154, v154
	v_rcp_f32_e32 v155, v155
	v_rcp_f32_e32 v156, v156
	v_rcp_f32_e32 v157, v157
	v_rcp_f32_e32 v158, v158
	v_rcp_f32_e32 v159, v159
	v_pk_mul_f32 v[152:153], v[52:53], v[152:153]
	v_pk_mul_f32 v[154:155], v[54:55], v[154:155]
	v_pk_mul_f32 v[156:157], v[48:49], v[156:157]
	v_pk_mul_f32 v[158:159], v[50:51], v[158:159]
	v_cvt_pk_bf16_f32 v164, v152, v153
	v_cvt_pk_bf16_f32 v165, v154, v155
	v_cvt_pk_bf16_f32 v166, v156, v157
	v_cvt_pk_bf16_f32 v167, v158, v159
	s_nop 1
	v_permlane16_swap_b32_e32 v164, v166
	v_permlane16_swap_b32_e32 v165, v167
	global_store_dwordx4 v144, v[164:167], s[8:9] offset:256
	s_add_u32 s8, s6, 0x12000
	s_addc_u32 s9, s7, 0
	v_mul_f32_e32 v152, 0xbfb8aa3b, v44
	v_mul_f32_e32 v153, 0xbfb8aa3b, v45
	v_mul_f32_e32 v154, 0xbfb8aa3b, v46
	v_mul_f32_e32 v155, 0xbfb8aa3b, v47
	v_mul_f32_e32 v156, 0xbfb8aa3b, v40
	v_mul_f32_e32 v157, 0xbfb8aa3b, v41
	v_mul_f32_e32 v158, 0xbfb8aa3b, v42
	v_mul_f32_e32 v159, 0xbfb8aa3b, v43
	v_exp_f32_e32 v152, v152
	v_exp_f32_e32 v153, v153
	v_exp_f32_e32 v154, v154
	v_exp_f32_e32 v155, v155
	v_exp_f32_e32 v156, v156
	v_exp_f32_e32 v157, v157
	v_exp_f32_e32 v158, v158
	v_exp_f32_e32 v159, v159
	v_add_f32_e32 v152, 1.0, v152
	v_add_f32_e32 v153, 1.0, v153
	v_add_f32_e32 v154, 1.0, v154
	v_add_f32_e32 v155, 1.0, v155
	v_add_f32_e32 v156, 1.0, v156
	v_add_f32_e32 v157, 1.0, v157
	v_add_f32_e32 v158, 1.0, v158
	v_add_f32_e32 v159, 1.0, v159
	v_rcp_f32_e32 v152, v152
	v_rcp_f32_e32 v153, v153
	v_rcp_f32_e32 v154, v154
	v_rcp_f32_e32 v155, v155
	v_rcp_f32_e32 v156, v156
	v_rcp_f32_e32 v157, v157
	v_rcp_f32_e32 v158, v158
	v_rcp_f32_e32 v159, v159
	v_pk_mul_f32 v[152:153], v[44:45], v[152:153]
	v_pk_mul_f32 v[154:155], v[46:47], v[154:155]
	v_pk_mul_f32 v[156:157], v[40:41], v[156:157]
	v_pk_mul_f32 v[158:159], v[42:43], v[158:159]
	v_cvt_pk_bf16_f32 v160, v152, v153
	v_cvt_pk_bf16_f32 v161, v154, v155
	v_cvt_pk_bf16_f32 v162, v156, v157
	v_cvt_pk_bf16_f32 v163, v158, v159
	s_nop 1
	v_permlane16_swap_b32_e32 v160, v162
	v_permlane16_swap_b32_e32 v161, v163
	global_store_dwordx4 v144, v[160:163], s[8:9]
	v_mul_f32_e32 v152, 0xbfb8aa3b, v36
	v_mul_f32_e32 v153, 0xbfb8aa3b, v37
	v_mul_f32_e32 v154, 0xbfb8aa3b, v38
	v_mul_f32_e32 v155, 0xbfb8aa3b, v39
	v_mul_f32_e32 v156, 0xbfb8aa3b, v32
	v_mul_f32_e32 v157, 0xbfb8aa3b, v33
	v_mul_f32_e32 v158, 0xbfb8aa3b, v34
	v_mul_f32_e32 v159, 0xbfb8aa3b, v35
	v_exp_f32_e32 v152, v152
	v_exp_f32_e32 v153, v153
	v_exp_f32_e32 v154, v154
	v_exp_f32_e32 v155, v155
	v_exp_f32_e32 v156, v156
	v_exp_f32_e32 v157, v157
	v_exp_f32_e32 v158, v158
	v_exp_f32_e32 v159, v159
	v_add_f32_e32 v152, 1.0, v152
	v_add_f32_e32 v153, 1.0, v153
	v_add_f32_e32 v154, 1.0, v154
	v_add_f32_e32 v155, 1.0, v155
	v_add_f32_e32 v156, 1.0, v156
	v_add_f32_e32 v157, 1.0, v157
	v_add_f32_e32 v158, 1.0, v158
	v_add_f32_e32 v159, 1.0, v159
	v_rcp_f32_e32 v152, v152
	v_rcp_f32_e32 v153, v153
	v_rcp_f32_e32 v154, v154
	v_rcp_f32_e32 v155, v155
	v_rcp_f32_e32 v156, v156
	v_rcp_f32_e32 v157, v157
	v_rcp_f32_e32 v158, v158
	v_rcp_f32_e32 v159, v159
	v_pk_mul_f32 v[152:153], v[36:37], v[152:153]
	v_pk_mul_f32 v[154:155], v[38:39], v[154:155]
	v_pk_mul_f32 v[156:157], v[32:33], v[156:157]
	v_pk_mul_f32 v[158:159], v[34:35], v[158:159]
	v_cvt_pk_bf16_f32 v164, v152, v153
	v_cvt_pk_bf16_f32 v165, v154, v155
	v_cvt_pk_bf16_f32 v166, v156, v157
	v_cvt_pk_bf16_f32 v167, v158, v159
	s_nop 1
	v_permlane16_swap_b32_e32 v164, v166
	v_permlane16_swap_b32_e32 v165, v167
	global_store_dwordx4 v144, v[164:167], s[8:9] offset:256
	s_add_u32 s8, s6, 0x14000
	s_addc_u32 s9, s7, 0
	v_mul_f32_e32 v152, 0xbfb8aa3b, v28
	v_mul_f32_e32 v153, 0xbfb8aa3b, v29
	v_mul_f32_e32 v154, 0xbfb8aa3b, v30
	v_mul_f32_e32 v155, 0xbfb8aa3b, v31
	v_mul_f32_e32 v156, 0xbfb8aa3b, v24
	v_mul_f32_e32 v157, 0xbfb8aa3b, v25
	v_mul_f32_e32 v158, 0xbfb8aa3b, v26
	v_mul_f32_e32 v159, 0xbfb8aa3b, v27
	v_exp_f32_e32 v152, v152
	v_exp_f32_e32 v153, v153
	v_exp_f32_e32 v154, v154
	v_exp_f32_e32 v155, v155
	v_exp_f32_e32 v156, v156
	v_exp_f32_e32 v157, v157
	v_exp_f32_e32 v158, v158
	v_exp_f32_e32 v159, v159
	v_add_f32_e32 v152, 1.0, v152
	v_add_f32_e32 v153, 1.0, v153
	v_add_f32_e32 v154, 1.0, v154
	v_add_f32_e32 v155, 1.0, v155
	v_add_f32_e32 v156, 1.0, v156
	v_add_f32_e32 v157, 1.0, v157
	v_add_f32_e32 v158, 1.0, v158
	v_add_f32_e32 v159, 1.0, v159
	v_rcp_f32_e32 v152, v152
	v_rcp_f32_e32 v153, v153
	v_rcp_f32_e32 v154, v154
	v_rcp_f32_e32 v155, v155
	v_rcp_f32_e32 v156, v156
	v_rcp_f32_e32 v157, v157
	v_rcp_f32_e32 v158, v158
	v_rcp_f32_e32 v159, v159
	v_pk_mul_f32 v[152:153], v[28:29], v[152:153]
	v_pk_mul_f32 v[154:155], v[30:31], v[154:155]
	v_pk_mul_f32 v[156:157], v[24:25], v[156:157]
	v_pk_mul_f32 v[158:159], v[26:27], v[158:159]
	v_cvt_pk_bf16_f32 v160, v152, v153
	v_cvt_pk_bf16_f32 v161, v154, v155
	v_cvt_pk_bf16_f32 v162, v156, v157
	v_cvt_pk_bf16_f32 v163, v158, v159
	s_nop 1
	v_permlane16_swap_b32_e32 v160, v162
	v_permlane16_swap_b32_e32 v161, v163
	global_store_dwordx4 v144, v[160:163], s[8:9]
	v_mul_f32_e32 v152, 0xbfb8aa3b, v20
	v_mul_f32_e32 v153, 0xbfb8aa3b, v21
	v_mul_f32_e32 v154, 0xbfb8aa3b, v22
	v_mul_f32_e32 v155, 0xbfb8aa3b, v23
	v_mul_f32_e32 v156, 0xbfb8aa3b, v16
	v_mul_f32_e32 v157, 0xbfb8aa3b, v17
	v_mul_f32_e32 v158, 0xbfb8aa3b, v18
	v_mul_f32_e32 v159, 0xbfb8aa3b, v19
	v_exp_f32_e32 v152, v152
	v_exp_f32_e32 v153, v153
	v_exp_f32_e32 v154, v154
	v_exp_f32_e32 v155, v155
	v_exp_f32_e32 v156, v156
	v_exp_f32_e32 v157, v157
	v_exp_f32_e32 v158, v158
	v_exp_f32_e32 v159, v159
	v_add_f32_e32 v152, 1.0, v152
	v_add_f32_e32 v153, 1.0, v153
	v_add_f32_e32 v154, 1.0, v154
	v_add_f32_e32 v155, 1.0, v155
	v_add_f32_e32 v156, 1.0, v156
	v_add_f32_e32 v157, 1.0, v157
	v_add_f32_e32 v158, 1.0, v158
	v_add_f32_e32 v159, 1.0, v159
	v_rcp_f32_e32 v152, v152
	v_rcp_f32_e32 v153, v153
	v_rcp_f32_e32 v154, v154
	v_rcp_f32_e32 v155, v155
	v_rcp_f32_e32 v156, v156
	v_rcp_f32_e32 v157, v157
	v_rcp_f32_e32 v158, v158
	v_rcp_f32_e32 v159, v159
	v_pk_mul_f32 v[152:153], v[20:21], v[152:153]
	v_pk_mul_f32 v[154:155], v[22:23], v[154:155]
	v_pk_mul_f32 v[156:157], v[16:17], v[156:157]
	v_pk_mul_f32 v[158:159], v[18:19], v[158:159]
	v_cvt_pk_bf16_f32 v164, v152, v153
	v_cvt_pk_bf16_f32 v165, v154, v155
	v_cvt_pk_bf16_f32 v166, v156, v157
	v_cvt_pk_bf16_f32 v167, v158, v159
	s_nop 1
	v_permlane16_swap_b32_e32 v164, v166
	v_permlane16_swap_b32_e32 v165, v167
	global_store_dwordx4 v144, v[164:167], s[8:9] offset:256
	s_add_u32 s8, s6, 0x16000
	s_addc_u32 s9, s7, 0
	v_mul_f32_e32 v152, 0xbfb8aa3b, v12
	v_mul_f32_e32 v153, 0xbfb8aa3b, v13
	v_mul_f32_e32 v154, 0xbfb8aa3b, v14
	v_mul_f32_e32 v155, 0xbfb8aa3b, v15
	v_mul_f32_e32 v156, 0xbfb8aa3b, v8
	v_mul_f32_e32 v157, 0xbfb8aa3b, v9
	v_mul_f32_e32 v158, 0xbfb8aa3b, v10
	v_mul_f32_e32 v159, 0xbfb8aa3b, v11
	v_exp_f32_e32 v152, v152
	v_exp_f32_e32 v153, v153
	v_exp_f32_e32 v154, v154
	v_exp_f32_e32 v155, v155
	v_exp_f32_e32 v156, v156
	v_exp_f32_e32 v157, v157
	v_exp_f32_e32 v158, v158
	v_exp_f32_e32 v159, v159
	v_add_f32_e32 v152, 1.0, v152
	v_add_f32_e32 v153, 1.0, v153
	v_add_f32_e32 v154, 1.0, v154
	v_add_f32_e32 v155, 1.0, v155
	v_add_f32_e32 v156, 1.0, v156
	v_add_f32_e32 v157, 1.0, v157
	v_add_f32_e32 v158, 1.0, v158
	v_add_f32_e32 v159, 1.0, v159
	v_rcp_f32_e32 v152, v152
	v_rcp_f32_e32 v153, v153
	v_rcp_f32_e32 v154, v154
	v_rcp_f32_e32 v155, v155
	v_rcp_f32_e32 v156, v156
	v_rcp_f32_e32 v157, v157
	v_rcp_f32_e32 v158, v158
	v_rcp_f32_e32 v159, v159
	v_pk_mul_f32 v[152:153], v[12:13], v[152:153]
	v_pk_mul_f32 v[154:155], v[14:15], v[154:155]
	v_pk_mul_f32 v[156:157], v[8:9], v[156:157]
	v_pk_mul_f32 v[158:159], v[10:11], v[158:159]
	v_cvt_pk_bf16_f32 v160, v152, v153
	v_cvt_pk_bf16_f32 v161, v154, v155
	v_cvt_pk_bf16_f32 v162, v156, v157
	v_cvt_pk_bf16_f32 v163, v158, v159
	s_nop 1
	v_permlane16_swap_b32_e32 v160, v162
	v_permlane16_swap_b32_e32 v161, v163
	global_store_dwordx4 v144, v[160:163], s[8:9]
	v_mul_f32_e32 v152, 0xbfb8aa3b, v4
	v_mul_f32_e32 v153, 0xbfb8aa3b, v5
	v_mul_f32_e32 v154, 0xbfb8aa3b, v6
	v_mul_f32_e32 v155, 0xbfb8aa3b, v7
	v_mul_f32_e32 v156, 0xbfb8aa3b, v0
	v_mul_f32_e32 v157, 0xbfb8aa3b, v1
	v_mul_f32_e32 v158, 0xbfb8aa3b, v2
	v_mul_f32_e32 v159, 0xbfb8aa3b, v3
	v_exp_f32_e32 v152, v152
	v_exp_f32_e32 v153, v153
	v_exp_f32_e32 v154, v154
	v_exp_f32_e32 v155, v155
	v_exp_f32_e32 v156, v156
	v_exp_f32_e32 v157, v157
	v_exp_f32_e32 v158, v158
	v_exp_f32_e32 v159, v159
	v_add_f32_e32 v152, 1.0, v152
	v_add_f32_e32 v153, 1.0, v153
	v_add_f32_e32 v154, 1.0, v154
	v_add_f32_e32 v155, 1.0, v155
	v_add_f32_e32 v156, 1.0, v156
	v_add_f32_e32 v157, 1.0, v157
	v_add_f32_e32 v158, 1.0, v158
	v_add_f32_e32 v159, 1.0, v159
	v_rcp_f32_e32 v152, v152
	v_rcp_f32_e32 v153, v153
	v_rcp_f32_e32 v154, v154
	v_rcp_f32_e32 v155, v155
	v_rcp_f32_e32 v156, v156
	v_rcp_f32_e32 v157, v157
	v_rcp_f32_e32 v158, v158
	v_rcp_f32_e32 v159, v159
	v_pk_mul_f32 v[152:153], v[4:5], v[152:153]
	v_pk_mul_f32 v[154:155], v[6:7], v[154:155]
	v_pk_mul_f32 v[156:157], v[0:1], v[156:157]
	v_pk_mul_f32 v[158:159], v[2:3], v[158:159]
	v_cvt_pk_bf16_f32 v164, v152, v153
	v_cvt_pk_bf16_f32 v165, v154, v155
	v_cvt_pk_bf16_f32 v166, v156, v157
	v_cvt_pk_bf16_f32 v167, v158, v159
	s_nop 1
	v_permlane16_swap_b32_e32 v164, v166
	v_permlane16_swap_b32_e32 v165, v167
	global_store_dwordx4 v144, v[164:167], s[8:9] offset:256
	s_branch .Lg1_done
.Lg1_sigmoid:
	s_mov_b32 s8, s6
	s_mov_b32 s9, s7
	v_mul_f32_e32 v152, 0xbfb8aa3b, v124
	v_mul_f32_e32 v153, 0xbfb8aa3b, v125
	v_mul_f32_e32 v154, 0xbfb8aa3b, v126
	v_mul_f32_e32 v155, 0xbfb8aa3b, v127
	v_mul_f32_e32 v156, 0xbfb8aa3b, v120
	v_mul_f32_e32 v157, 0xbfb8aa3b, v121
	v_mul_f32_e32 v158, 0xbfb8aa3b, v122
	v_mul_f32_e32 v159, 0xbfb8aa3b, v123
	v_exp_f32_e32 v152, v152
	v_exp_f32_e32 v153, v153
	v_exp_f32_e32 v154, v154
	v_exp_f32_e32 v155, v155
	v_exp_f32_e32 v156, v156
	v_exp_f32_e32 v157, v157
	v_exp_f32_e32 v158, v158
	v_exp_f32_e32 v159, v159
	v_add_f32_e32 v152, 1.0, v152
	v_add_f32_e32 v153, 1.0, v153
	v_add_f32_e32 v154, 1.0, v154
	v_add_f32_e32 v155, 1.0, v155
	v_add_f32_e32 v156, 1.0, v156
	v_add_f32_e32 v157, 1.0, v157
	v_add_f32_e32 v158, 1.0, v158
	v_add_f32_e32 v159, 1.0, v159
	v_rcp_f32_e32 v152, v152
	v_rcp_f32_e32 v153, v153
	v_rcp_f32_e32 v154, v154
	v_rcp_f32_e32 v155, v155
	v_rcp_f32_e32 v156, v156
	v_rcp_f32_e32 v157, v157
	v_rcp_f32_e32 v158, v158
	v_rcp_f32_e32 v159, v159
	s_nop 0
	v_cvt_pk_bf16_f32 v160, v152, v153
	v_cvt_pk_bf16_f32 v161, v154, v155
	v_cvt_pk_bf16_f32 v162, v156, v157
	v_cvt_pk_bf16_f32 v163, v158, v159
	s_nop 1
	v_permlane16_swap_b32_e32 v160, v162
	v_permlane16_swap_b32_e32 v161, v163
	global_store_dwordx4 v144, v[160:163], s[8:9]
	v_mul_f32_e32 v152, 0xbfb8aa3b, v116
	v_mul_f32_e32 v153, 0xbfb8aa3b, v117
	v_mul_f32_e32 v154, 0xbfb8aa3b, v118
	v_mul_f32_e32 v155, 0xbfb8aa3b, v119
	v_mul_f32_e32 v156, 0xbfb8aa3b, v112
	v_mul_f32_e32 v157, 0xbfb8aa3b, v113
	v_mul_f32_e32 v158, 0xbfb8aa3b, v114
	v_mul_f32_e32 v159, 0xbfb8aa3b, v115
	v_exp_f32_e32 v152, v152
	v_exp_f32_e32 v153, v153
	v_exp_f32_e32 v154, v154
	v_exp_f32_e32 v155, v155
	v_exp_f32_e32 v156, v156
	v_exp_f32_e32 v157, v157
	v_exp_f32_e32 v158, v158
	v_exp_f32_e32 v159, v159
	v_add_f32_e32 v152, 1.0, v152
	v_add_f32_e32 v153, 1.0, v153
	v_add_f32_e32 v154, 1.0, v154
	v_add_f32_e32 v155, 1.0, v155
	v_add_f32_e32 v156, 1.0, v156
	v_add_f32_e32 v157, 1.0, v157
	v_add_f32_e32 v158, 1.0, v158
	v_add_f32_e32 v159, 1.0, v159
	v_rcp_f32_e32 v152, v152
	v_rcp_f32_e32 v153, v153
	v_rcp_f32_e32 v154, v154
	v_rcp_f32_e32 v155, v155
	v_rcp_f32_e32 v156, v156
	v_rcp_f32_e32 v157, v157
	v_rcp_f32_e32 v158, v158
	v_rcp_f32_e32 v159, v159
	s_nop 0
	v_cvt_pk_bf16_f32 v164, v152, v153
	v_cvt_pk_bf16_f32 v165, v154, v155
	v_cvt_pk_bf16_f32 v166, v156, v157
	v_cvt_pk_bf16_f32 v167, v158, v159
	s_nop 1
	v_permlane16_swap_b32_e32 v164, v166
	v_permlane16_swap_b32_e32 v165, v167
	global_store_dwordx4 v144, v[164:167], s[8:9] offset:256
	s_add_u32 s8, s6, 0x2000
	s_addc_u32 s9, s7, 0
	v_mul_f32_e32 v152, 0xbfb8aa3b, v108
	v_mul_f32_e32 v153, 0xbfb8aa3b, v109
	v_mul_f32_e32 v154, 0xbfb8aa3b, v110
	v_mul_f32_e32 v155, 0xbfb8aa3b, v111
	v_mul_f32_e32 v156, 0xbfb8aa3b, v104
	v_mul_f32_e32 v157, 0xbfb8aa3b, v105
	v_mul_f32_e32 v158, 0xbfb8aa3b, v106
	v_mul_f32_e32 v159, 0xbfb8aa3b, v107
	v_exp_f32_e32 v152, v152
	v_exp_f32_e32 v153, v153
	v_exp_f32_e32 v154, v154
	v_exp_f32_e32 v155, v155
	v_exp_f32_e32 v156, v156
	v_exp_f32_e32 v157, v157
	v_exp_f32_e32 v158, v158
	v_exp_f32_e32 v159, v159
	v_add_f32_e32 v152, 1.0, v152
	v_add_f32_e32 v153, 1.0, v153
	v_add_f32_e32 v154, 1.0, v154
	v_add_f32_e32 v155, 1.0, v155
	v_add_f32_e32 v156, 1.0, v156
	v_add_f32_e32 v157, 1.0, v157
	v_add_f32_e32 v158, 1.0, v158
	v_add_f32_e32 v159, 1.0, v159
	v_rcp_f32_e32 v152, v152
	v_rcp_f32_e32 v153, v153
	v_rcp_f32_e32 v154, v154
	v_rcp_f32_e32 v155, v155
	v_rcp_f32_e32 v156, v156
	v_rcp_f32_e32 v157, v157
	v_rcp_f32_e32 v158, v158
	v_rcp_f32_e32 v159, v159
	s_nop 0
	v_cvt_pk_bf16_f32 v160, v152, v153
	v_cvt_pk_bf16_f32 v161, v154, v155
	v_cvt_pk_bf16_f32 v162, v156, v157
	v_cvt_pk_bf16_f32 v163, v158, v159
	s_nop 1
	v_permlane16_swap_b32_e32 v160, v162
	v_permlane16_swap_b32_e32 v161, v163
	global_store_dwordx4 v144, v[160:163], s[8:9]
	v_mul_f32_e32 v152, 0xbfb8aa3b, v92
	v_mul_f32_e32 v153, 0xbfb8aa3b, v93
	v_mul_f32_e32 v154, 0xbfb8aa3b, v94
	v_mul_f32_e32 v155, 0xbfb8aa3b, v95
	v_mul_f32_e32 v156, 0xbfb8aa3b, v88
	v_mul_f32_e32 v157, 0xbfb8aa3b, v89
	v_mul_f32_e32 v158, 0xbfb8aa3b, v90
	v_mul_f32_e32 v159, 0xbfb8aa3b, v91
	v_exp_f32_e32 v152, v152
	v_exp_f32_e32 v153, v153
	v_exp_f32_e32 v154, v154
	v_exp_f32_e32 v155, v155
	v_exp_f32_e32 v156, v156
	v_exp_f32_e32 v157, v157
	v_exp_f32_e32 v158, v158
	v_exp_f32_e32 v159, v159
	v_add_f32_e32 v152, 1.0, v152
	v_add_f32_e32 v153, 1.0, v153
	v_add_f32_e32 v154, 1.0, v154
	v_add_f32_e32 v155, 1.0, v155
	v_add_f32_e32 v156, 1.0, v156
	v_add_f32_e32 v157, 1.0, v157
	v_add_f32_e32 v158, 1.0, v158
	v_add_f32_e32 v159, 1.0, v159
	v_rcp_f32_e32 v152, v152
	v_rcp_f32_e32 v153, v153
	v_rcp_f32_e32 v154, v154
	v_rcp_f32_e32 v155, v155
	v_rcp_f32_e32 v156, v156
	v_rcp_f32_e32 v157, v157
	v_rcp_f32_e32 v158, v158
	v_rcp_f32_e32 v159, v159
	s_nop 0
	v_cvt_pk_bf16_f32 v164, v152, v153
	v_cvt_pk_bf16_f32 v165, v154, v155
	v_cvt_pk_bf16_f32 v166, v156, v157
	v_cvt_pk_bf16_f32 v167, v158, v159
	s_nop 1
	v_permlane16_swap_b32_e32 v164, v166
	v_permlane16_swap_b32_e32 v165, v167
	global_store_dwordx4 v144, v[164:167], s[8:9] offset:256
	s_add_u32 s8, s6, 0x4000
	s_addc_u32 s9, s7, 0
	v_mul_f32_e32 v152, 0xbfb8aa3b, v100
	v_mul_f32_e32 v153, 0xbfb8aa3b, v101
	v_mul_f32_e32 v154, 0xbfb8aa3b, v102
	v_mul_f32_e32 v155, 0xbfb8aa3b, v103
	v_mul_f32_e32 v156, 0xbfb8aa3b, v96
	v_mul_f32_e32 v157, 0xbfb8aa3b, v97
	v_mul_f32_e32 v158, 0xbfb8aa3b, v98
	v_mul_f32_e32 v159, 0xbfb8aa3b, v99
	v_exp_f32_e32 v152, v152
	v_exp_f32_e32 v153, v153
	v_exp_f32_e32 v154, v154
	v_exp_f32_e32 v155, v155
	v_exp_f32_e32 v156, v156
	v_exp_f32_e32 v157, v157
	v_exp_f32_e32 v158, v158
	v_exp_f32_e32 v159, v159
	v_add_f32_e32 v152, 1.0, v152
	v_add_f32_e32 v153, 1.0, v153
	v_add_f32_e32 v154, 1.0, v154
	v_add_f32_e32 v155, 1.0, v155
	v_add_f32_e32 v156, 1.0, v156
	v_add_f32_e32 v157, 1.0, v157
	v_add_f32_e32 v158, 1.0, v158
	v_add_f32_e32 v159, 1.0, v159
	v_rcp_f32_e32 v152, v152
	v_rcp_f32_e32 v153, v153
	v_rcp_f32_e32 v154, v154
	v_rcp_f32_e32 v155, v155
	v_rcp_f32_e32 v156, v156
	v_rcp_f32_e32 v157, v157
	v_rcp_f32_e32 v158, v158
	v_rcp_f32_e32 v159, v159
	s_nop 0
	v_cvt_pk_bf16_f32 v160, v152, v153
	v_cvt_pk_bf16_f32 v161, v154, v155
	v_cvt_pk_bf16_f32 v162, v156, v157
	v_cvt_pk_bf16_f32 v163, v158, v159
	s_nop 1
	v_permlane16_swap_b32_e32 v160, v162
	v_permlane16_swap_b32_e32 v161, v163
	global_store_dwordx4 v144, v[160:163], s[8:9]
	v_mul_f32_e32 v152, 0xbfb8aa3b, v84
	v_mul_f32_e32 v153, 0xbfb8aa3b, v85
	v_mul_f32_e32 v154, 0xbfb8aa3b, v86
	v_mul_f32_e32 v155, 0xbfb8aa3b, v87
	v_mul_f32_e32 v156, 0xbfb8aa3b, v80
	v_mul_f32_e32 v157, 0xbfb8aa3b, v81
	v_mul_f32_e32 v158, 0xbfb8aa3b, v82
	v_mul_f32_e32 v159, 0xbfb8aa3b, v83
	v_exp_f32_e32 v152, v152
	v_exp_f32_e32 v153, v153
	v_exp_f32_e32 v154, v154
	v_exp_f32_e32 v155, v155
	v_exp_f32_e32 v156, v156
	v_exp_f32_e32 v157, v157
	v_exp_f32_e32 v158, v158
	v_exp_f32_e32 v159, v159
	v_add_f32_e32 v152, 1.0, v152
	v_add_f32_e32 v153, 1.0, v153
	v_add_f32_e32 v154, 1.0, v154
	v_add_f32_e32 v155, 1.0, v155
	v_add_f32_e32 v156, 1.0, v156
	v_add_f32_e32 v157, 1.0, v157
	v_add_f32_e32 v158, 1.0, v158
	v_add_f32_e32 v159, 1.0, v159
	v_rcp_f32_e32 v152, v152
	v_rcp_f32_e32 v153, v153
	v_rcp_f32_e32 v154, v154
	v_rcp_f32_e32 v155, v155
	v_rcp_f32_e32 v156, v156
	v_rcp_f32_e32 v157, v157
	v_rcp_f32_e32 v158, v158
	v_rcp_f32_e32 v159, v159
	s_nop 0
	v_cvt_pk_bf16_f32 v164, v152, v153
	v_cvt_pk_bf16_f32 v165, v154, v155
	v_cvt_pk_bf16_f32 v166, v156, v157
	v_cvt_pk_bf16_f32 v167, v158, v159
	s_nop 1
	v_permlane16_swap_b32_e32 v164, v166
	v_permlane16_swap_b32_e32 v165, v167
	global_store_dwordx4 v144, v[164:167], s[8:9] offset:256
	s_add_u32 s8, s6, 0x6000
	s_addc_u32 s9, s7, 0
	v_mul_f32_e32 v152, 0xbfb8aa3b, v76
	v_mul_f32_e32 v153, 0xbfb8aa3b, v77
	v_mul_f32_e32 v154, 0xbfb8aa3b, v78
	v_mul_f32_e32 v155, 0xbfb8aa3b, v79
	v_mul_f32_e32 v156, 0xbfb8aa3b, v72
	v_mul_f32_e32 v157, 0xbfb8aa3b, v73
	v_mul_f32_e32 v158, 0xbfb8aa3b, v74
	v_mul_f32_e32 v159, 0xbfb8aa3b, v75
	v_exp_f32_e32 v152, v152
	v_exp_f32_e32 v153, v153
	v_exp_f32_e32 v154, v154
	v_exp_f32_e32 v155, v155
	v_exp_f32_e32 v156, v156
	v_exp_f32_e32 v157, v157
	v_exp_f32_e32 v158, v158
	v_exp_f32_e32 v159, v159
	v_add_f32_e32 v152, 1.0, v152
	v_add_f32_e32 v153, 1.0, v153
	v_add_f32_e32 v154, 1.0, v154
	v_add_f32_e32 v155, 1.0, v155
	v_add_f32_e32 v156, 1.0, v156
	v_add_f32_e32 v157, 1.0, v157
	v_add_f32_e32 v158, 1.0, v158
	v_add_f32_e32 v159, 1.0, v159
	v_rcp_f32_e32 v152, v152
	v_rcp_f32_e32 v153, v153
	v_rcp_f32_e32 v154, v154
	v_rcp_f32_e32 v155, v155
	v_rcp_f32_e32 v156, v156
	v_rcp_f32_e32 v157, v157
	v_rcp_f32_e32 v158, v158
	v_rcp_f32_e32 v159, v159
	s_nop 0
	v_cvt_pk_bf16_f32 v160, v152, v153
	v_cvt_pk_bf16_f32 v161, v154, v155
	v_cvt_pk_bf16_f32 v162, v156, v157
	v_cvt_pk_bf16_f32 v163, v158, v159
	s_nop 1
	v_permlane16_swap_b32_e32 v160, v162
	v_permlane16_swap_b32_e32 v161, v163
	global_store_dwordx4 v144, v[160:163], s[8:9]
	v_mul_f32_e32 v152, 0xbfb8aa3b, v68
	v_mul_f32_e32 v153, 0xbfb8aa3b, v69
	v_mul_f32_e32 v154, 0xbfb8aa3b, v70
	v_mul_f32_e32 v155, 0xbfb8aa3b, v71
	v_mul_f32_e32 v156, 0xbfb8aa3b, v64
	v_mul_f32_e32 v157, 0xbfb8aa3b, v65
	v_mul_f32_e32 v158, 0xbfb8aa3b, v66
	v_mul_f32_e32 v159, 0xbfb8aa3b, v67
	v_exp_f32_e32 v152, v152
	v_exp_f32_e32 v153, v153
	v_exp_f32_e32 v154, v154
	v_exp_f32_e32 v155, v155
	v_exp_f32_e32 v156, v156
	v_exp_f32_e32 v157, v157
	v_exp_f32_e32 v158, v158
	v_exp_f32_e32 v159, v159
	v_add_f32_e32 v152, 1.0, v152
	v_add_f32_e32 v153, 1.0, v153
	v_add_f32_e32 v154, 1.0, v154
	v_add_f32_e32 v155, 1.0, v155
	v_add_f32_e32 v156, 1.0, v156
	v_add_f32_e32 v157, 1.0, v157
	v_add_f32_e32 v158, 1.0, v158
	v_add_f32_e32 v159, 1.0, v159
	v_rcp_f32_e32 v152, v152
	v_rcp_f32_e32 v153, v153
	v_rcp_f32_e32 v154, v154
	v_rcp_f32_e32 v155, v155
	v_rcp_f32_e32 v156, v156
	v_rcp_f32_e32 v157, v157
	v_rcp_f32_e32 v158, v158
	v_rcp_f32_e32 v159, v159
	s_nop 0
	v_cvt_pk_bf16_f32 v164, v152, v153
	v_cvt_pk_bf16_f32 v165, v154, v155
	v_cvt_pk_bf16_f32 v166, v156, v157
	v_cvt_pk_bf16_f32 v167, v158, v159
	s_nop 1
	v_permlane16_swap_b32_e32 v164, v166
	v_permlane16_swap_b32_e32 v165, v167
	global_store_dwordx4 v144, v[164:167], s[8:9] offset:256
	s_add_u32 s8, s6, 0x10000
	s_addc_u32 s9, s7, 0
	v_mul_f32_e32 v152, 0xbfb8aa3b, v60
	v_mul_f32_e32 v153, 0xbfb8aa3b, v61
	v_mul_f32_e32 v154, 0xbfb8aa3b, v62
	v_mul_f32_e32 v155, 0xbfb8aa3b, v63
	v_mul_f32_e32 v156, 0xbfb8aa3b, v56
	v_mul_f32_e32 v157, 0xbfb8aa3b, v57
	v_mul_f32_e32 v158, 0xbfb8aa3b, v58
	v_mul_f32_e32 v159, 0xbfb8aa3b, v59
	v_exp_f32_e32 v152, v152
	v_exp_f32_e32 v153, v153
	v_exp_f32_e32 v154, v154
	v_exp_f32_e32 v155, v155
	v_exp_f32_e32 v156, v156
	v_exp_f32_e32 v157, v157
	v_exp_f32_e32 v158, v158
	v_exp_f32_e32 v159, v159
	v_add_f32_e32 v152, 1.0, v152
	v_add_f32_e32 v153, 1.0, v153
	v_add_f32_e32 v154, 1.0, v154
	v_add_f32_e32 v155, 1.0, v155
	v_add_f32_e32 v156, 1.0, v156
	v_add_f32_e32 v157, 1.0, v157
	v_add_f32_e32 v158, 1.0, v158
	v_add_f32_e32 v159, 1.0, v159
	v_rcp_f32_e32 v152, v152
	v_rcp_f32_e32 v153, v153
	v_rcp_f32_e32 v154, v154
	v_rcp_f32_e32 v155, v155
	v_rcp_f32_e32 v156, v156
	v_rcp_f32_e32 v157, v157
	v_rcp_f32_e32 v158, v158
	v_rcp_f32_e32 v159, v159
	s_nop 0
	v_cvt_pk_bf16_f32 v160, v152, v153
	v_cvt_pk_bf16_f32 v161, v154, v155
	v_cvt_pk_bf16_f32 v162, v156, v157
	v_cvt_pk_bf16_f32 v163, v158, v159
	s_nop 1
	v_permlane16_swap_b32_e32 v160, v162
	v_permlane16_swap_b32_e32 v161, v163
	global_store_dwordx4 v144, v[160:163], s[8:9]
	v_mul_f32_e32 v152, 0xbfb8aa3b, v52
	v_mul_f32_e32 v153, 0xbfb8aa3b, v53
	v_mul_f32_e32 v154, 0xbfb8aa3b, v54
	v_mul_f32_e32 v155, 0xbfb8aa3b, v55
	v_mul_f32_e32 v156, 0xbfb8aa3b, v48
	v_mul_f32_e32 v157, 0xbfb8aa3b, v49
	v_mul_f32_e32 v158, 0xbfb8aa3b, v50
	v_mul_f32_e32 v159, 0xbfb8aa3b, v51
	v_exp_f32_e32 v152, v152
	v_exp_f32_e32 v153, v153
	v_exp_f32_e32 v154, v154
	v_exp_f32_e32 v155, v155
	v_exp_f32_e32 v156, v156
	v_exp_f32_e32 v157, v157
	v_exp_f32_e32 v158, v158
	v_exp_f32_e32 v159, v159
	v_add_f32_e32 v152, 1.0, v152
	v_add_f32_e32 v153, 1.0, v153
	v_add_f32_e32 v154, 1.0, v154
	v_add_f32_e32 v155, 1.0, v155
	v_add_f32_e32 v156, 1.0, v156
	v_add_f32_e32 v157, 1.0, v157
	v_add_f32_e32 v158, 1.0, v158
	v_add_f32_e32 v159, 1.0, v159
	v_rcp_f32_e32 v152, v152
	v_rcp_f32_e32 v153, v153
	v_rcp_f32_e32 v154, v154
	v_rcp_f32_e32 v155, v155
	v_rcp_f32_e32 v156, v156
	v_rcp_f32_e32 v157, v157
	v_rcp_f32_e32 v158, v158
	v_rcp_f32_e32 v159, v159
	s_nop 0
	v_cvt_pk_bf16_f32 v164, v152, v153
	v_cvt_pk_bf16_f32 v165, v154, v155
	v_cvt_pk_bf16_f32 v166, v156, v157
	v_cvt_pk_bf16_f32 v167, v158, v159
	s_nop 1
	v_permlane16_swap_b32_e32 v164, v166
	v_permlane16_swap_b32_e32 v165, v167
	global_store_dwordx4 v144, v[164:167], s[8:9] offset:256
	s_add_u32 s8, s6, 0x12000
	s_addc_u32 s9, s7, 0
	v_mul_f32_e32 v152, 0xbfb8aa3b, v44
	v_mul_f32_e32 v153, 0xbfb8aa3b, v45
	v_mul_f32_e32 v154, 0xbfb8aa3b, v46
	v_mul_f32_e32 v155, 0xbfb8aa3b, v47
	v_mul_f32_e32 v156, 0xbfb8aa3b, v40
	v_mul_f32_e32 v157, 0xbfb8aa3b, v41
	v_mul_f32_e32 v158, 0xbfb8aa3b, v42
	v_mul_f32_e32 v159, 0xbfb8aa3b, v43
	v_exp_f32_e32 v152, v152
	v_exp_f32_e32 v153, v153
	v_exp_f32_e32 v154, v154
	v_exp_f32_e32 v155, v155
	v_exp_f32_e32 v156, v156
	v_exp_f32_e32 v157, v157
	v_exp_f32_e32 v158, v158
	v_exp_f32_e32 v159, v159
	v_add_f32_e32 v152, 1.0, v152
	v_add_f32_e32 v153, 1.0, v153
	v_add_f32_e32 v154, 1.0, v154
	v_add_f32_e32 v155, 1.0, v155
	v_add_f32_e32 v156, 1.0, v156
	v_add_f32_e32 v157, 1.0, v157
	v_add_f32_e32 v158, 1.0, v158
	v_add_f32_e32 v159, 1.0, v159
	v_rcp_f32_e32 v152, v152
	v_rcp_f32_e32 v153, v153
	v_rcp_f32_e32 v154, v154
	v_rcp_f32_e32 v155, v155
	v_rcp_f32_e32 v156, v156
	v_rcp_f32_e32 v157, v157
	v_rcp_f32_e32 v158, v158
	v_rcp_f32_e32 v159, v159
	s_nop 0
	v_cvt_pk_bf16_f32 v160, v152, v153
	v_cvt_pk_bf16_f32 v161, v154, v155
	v_cvt_pk_bf16_f32 v162, v156, v157
	v_cvt_pk_bf16_f32 v163, v158, v159
	s_nop 1
	v_permlane16_swap_b32_e32 v160, v162
	v_permlane16_swap_b32_e32 v161, v163
	global_store_dwordx4 v144, v[160:163], s[8:9]
	v_mul_f32_e32 v152, 0xbfb8aa3b, v36
	v_mul_f32_e32 v153, 0xbfb8aa3b, v37
	v_mul_f32_e32 v154, 0xbfb8aa3b, v38
	v_mul_f32_e32 v155, 0xbfb8aa3b, v39
	v_mul_f32_e32 v156, 0xbfb8aa3b, v32
	v_mul_f32_e32 v157, 0xbfb8aa3b, v33
	v_mul_f32_e32 v158, 0xbfb8aa3b, v34
	v_mul_f32_e32 v159, 0xbfb8aa3b, v35
	v_exp_f32_e32 v152, v152
	v_exp_f32_e32 v153, v153
	v_exp_f32_e32 v154, v154
	v_exp_f32_e32 v155, v155
	v_exp_f32_e32 v156, v156
	v_exp_f32_e32 v157, v157
	v_exp_f32_e32 v158, v158
	v_exp_f32_e32 v159, v159
	v_add_f32_e32 v152, 1.0, v152
	v_add_f32_e32 v153, 1.0, v153
	v_add_f32_e32 v154, 1.0, v154
	v_add_f32_e32 v155, 1.0, v155
	v_add_f32_e32 v156, 1.0, v156
	v_add_f32_e32 v157, 1.0, v157
	v_add_f32_e32 v158, 1.0, v158
	v_add_f32_e32 v159, 1.0, v159
	v_rcp_f32_e32 v152, v152
	v_rcp_f32_e32 v153, v153
	v_rcp_f32_e32 v154, v154
	v_rcp_f32_e32 v155, v155
	v_rcp_f32_e32 v156, v156
	v_rcp_f32_e32 v157, v157
	v_rcp_f32_e32 v158, v158
	v_rcp_f32_e32 v159, v159
	s_nop 0
	v_cvt_pk_bf16_f32 v164, v152, v153
	v_cvt_pk_bf16_f32 v165, v154, v155
	v_cvt_pk_bf16_f32 v166, v156, v157
	v_cvt_pk_bf16_f32 v167, v158, v159
	s_nop 1
	v_permlane16_swap_b32_e32 v164, v166
	v_permlane16_swap_b32_e32 v165, v167
	global_store_dwordx4 v144, v[164:167], s[8:9] offset:256
	s_add_u32 s8, s6, 0x14000
	s_addc_u32 s9, s7, 0
	v_mul_f32_e32 v152, 0xbfb8aa3b, v28
	v_mul_f32_e32 v153, 0xbfb8aa3b, v29
	v_mul_f32_e32 v154, 0xbfb8aa3b, v30
	v_mul_f32_e32 v155, 0xbfb8aa3b, v31
	v_mul_f32_e32 v156, 0xbfb8aa3b, v24
	v_mul_f32_e32 v157, 0xbfb8aa3b, v25
	v_mul_f32_e32 v158, 0xbfb8aa3b, v26
	v_mul_f32_e32 v159, 0xbfb8aa3b, v27
	v_exp_f32_e32 v152, v152
	v_exp_f32_e32 v153, v153
	v_exp_f32_e32 v154, v154
	v_exp_f32_e32 v155, v155
	v_exp_f32_e32 v156, v156
	v_exp_f32_e32 v157, v157
	v_exp_f32_e32 v158, v158
	v_exp_f32_e32 v159, v159
	v_add_f32_e32 v152, 1.0, v152
	v_add_f32_e32 v153, 1.0, v153
	v_add_f32_e32 v154, 1.0, v154
	v_add_f32_e32 v155, 1.0, v155
	v_add_f32_e32 v156, 1.0, v156
	v_add_f32_e32 v157, 1.0, v157
	v_add_f32_e32 v158, 1.0, v158
	v_add_f32_e32 v159, 1.0, v159
	v_rcp_f32_e32 v152, v152
	v_rcp_f32_e32 v153, v153
	v_rcp_f32_e32 v154, v154
	v_rcp_f32_e32 v155, v155
	v_rcp_f32_e32 v156, v156
	v_rcp_f32_e32 v157, v157
	v_rcp_f32_e32 v158, v158
	v_rcp_f32_e32 v159, v159
	s_nop 0
	v_cvt_pk_bf16_f32 v160, v152, v153
	v_cvt_pk_bf16_f32 v161, v154, v155
	v_cvt_pk_bf16_f32 v162, v156, v157
	v_cvt_pk_bf16_f32 v163, v158, v159
	s_nop 1
	v_permlane16_swap_b32_e32 v160, v162
	v_permlane16_swap_b32_e32 v161, v163
	global_store_dwordx4 v144, v[160:163], s[8:9]
	v_mul_f32_e32 v152, 0xbfb8aa3b, v20
	v_mul_f32_e32 v153, 0xbfb8aa3b, v21
	v_mul_f32_e32 v154, 0xbfb8aa3b, v22
	v_mul_f32_e32 v155, 0xbfb8aa3b, v23
	v_mul_f32_e32 v156, 0xbfb8aa3b, v16
	v_mul_f32_e32 v157, 0xbfb8aa3b, v17
	v_mul_f32_e32 v158, 0xbfb8aa3b, v18
	v_mul_f32_e32 v159, 0xbfb8aa3b, v19
	v_exp_f32_e32 v152, v152
	v_exp_f32_e32 v153, v153
	v_exp_f32_e32 v154, v154
	v_exp_f32_e32 v155, v155
	v_exp_f32_e32 v156, v156
	v_exp_f32_e32 v157, v157
	v_exp_f32_e32 v158, v158
	v_exp_f32_e32 v159, v159
	v_add_f32_e32 v152, 1.0, v152
	v_add_f32_e32 v153, 1.0, v153
	v_add_f32_e32 v154, 1.0, v154
	v_add_f32_e32 v155, 1.0, v155
	v_add_f32_e32 v156, 1.0, v156
	v_add_f32_e32 v157, 1.0, v157
	v_add_f32_e32 v158, 1.0, v158
	v_add_f32_e32 v159, 1.0, v159
	v_rcp_f32_e32 v152, v152
	v_rcp_f32_e32 v153, v153
	v_rcp_f32_e32 v154, v154
	v_rcp_f32_e32 v155, v155
	v_rcp_f32_e32 v156, v156
	v_rcp_f32_e32 v157, v157
	v_rcp_f32_e32 v158, v158
	v_rcp_f32_e32 v159, v159
	s_nop 0
	v_cvt_pk_bf16_f32 v164, v152, v153
	v_cvt_pk_bf16_f32 v165, v154, v155
	v_cvt_pk_bf16_f32 v166, v156, v157
	v_cvt_pk_bf16_f32 v167, v158, v159
	s_nop 1
	v_permlane16_swap_b32_e32 v164, v166
	v_permlane16_swap_b32_e32 v165, v167
	global_store_dwordx4 v144, v[164:167], s[8:9] offset:256
	s_add_u32 s8, s6, 0x16000
	s_addc_u32 s9, s7, 0
	v_mul_f32_e32 v152, 0xbfb8aa3b, v12
	v_mul_f32_e32 v153, 0xbfb8aa3b, v13
	v_mul_f32_e32 v154, 0xbfb8aa3b, v14
	v_mul_f32_e32 v155, 0xbfb8aa3b, v15
	v_mul_f32_e32 v156, 0xbfb8aa3b, v8
	v_mul_f32_e32 v157, 0xbfb8aa3b, v9
	v_mul_f32_e32 v158, 0xbfb8aa3b, v10
	v_mul_f32_e32 v159, 0xbfb8aa3b, v11
	v_exp_f32_e32 v152, v152
	v_exp_f32_e32 v153, v153
	v_exp_f32_e32 v154, v154
	v_exp_f32_e32 v155, v155
	v_exp_f32_e32 v156, v156
	v_exp_f32_e32 v157, v157
	v_exp_f32_e32 v158, v158
	v_exp_f32_e32 v159, v159
	v_add_f32_e32 v152, 1.0, v152
	v_add_f32_e32 v153, 1.0, v153
	v_add_f32_e32 v154, 1.0, v154
	v_add_f32_e32 v155, 1.0, v155
	v_add_f32_e32 v156, 1.0, v156
	v_add_f32_e32 v157, 1.0, v157
	v_add_f32_e32 v158, 1.0, v158
	v_add_f32_e32 v159, 1.0, v159
	v_rcp_f32_e32 v152, v152
	v_rcp_f32_e32 v153, v153
	v_rcp_f32_e32 v154, v154
	v_rcp_f32_e32 v155, v155
	v_rcp_f32_e32 v156, v156
	v_rcp_f32_e32 v157, v157
	v_rcp_f32_e32 v158, v158
	v_rcp_f32_e32 v159, v159
	s_nop 0
	v_cvt_pk_bf16_f32 v160, v152, v153
	v_cvt_pk_bf16_f32 v161, v154, v155
	v_cvt_pk_bf16_f32 v162, v156, v157
	v_cvt_pk_bf16_f32 v163, v158, v159
	s_nop 1
	v_permlane16_swap_b32_e32 v160, v162
	v_permlane16_swap_b32_e32 v161, v163
	global_store_dwordx4 v144, v[160:163], s[8:9]
	v_mul_f32_e32 v152, 0xbfb8aa3b, v4
	v_mul_f32_e32 v153, 0xbfb8aa3b, v5
	v_mul_f32_e32 v154, 0xbfb8aa3b, v6
	v_mul_f32_e32 v155, 0xbfb8aa3b, v7
	v_mul_f32_e32 v156, 0xbfb8aa3b, v0
	v_mul_f32_e32 v157, 0xbfb8aa3b, v1
	v_mul_f32_e32 v158, 0xbfb8aa3b, v2
	v_mul_f32_e32 v159, 0xbfb8aa3b, v3
	v_exp_f32_e32 v152, v152
	v_exp_f32_e32 v153, v153
	v_exp_f32_e32 v154, v154
	v_exp_f32_e32 v155, v155
	v_exp_f32_e32 v156, v156
	v_exp_f32_e32 v157, v157
	v_exp_f32_e32 v158, v158
	v_exp_f32_e32 v159, v159
	v_add_f32_e32 v152, 1.0, v152
	v_add_f32_e32 v153, 1.0, v153
	v_add_f32_e32 v154, 1.0, v154
	v_add_f32_e32 v155, 1.0, v155
	v_add_f32_e32 v156, 1.0, v156
	v_add_f32_e32 v157, 1.0, v157
	v_add_f32_e32 v158, 1.0, v158
	v_add_f32_e32 v159, 1.0, v159
	v_rcp_f32_e32 v152, v152
	v_rcp_f32_e32 v153, v153
	v_rcp_f32_e32 v154, v154
	v_rcp_f32_e32 v155, v155
	v_rcp_f32_e32 v156, v156
	v_rcp_f32_e32 v157, v157
	v_rcp_f32_e32 v158, v158
	v_rcp_f32_e32 v159, v159
	s_nop 0
	v_cvt_pk_bf16_f32 v164, v152, v153
	v_cvt_pk_bf16_f32 v165, v154, v155
	v_cvt_pk_bf16_f32 v166, v156, v157
	v_cvt_pk_bf16_f32 v167, v158, v159
	s_nop 1
	v_permlane16_swap_b32_e32 v164, v166
	v_permlane16_swap_b32_e32 v165, v167
	global_store_dwordx4 v144, v[164:167], s[8:9] offset:256
.Lg1_done:
.LBB0_428:
	s_mov_b64 s[4:5], 0
.LBB0_429:
	s_and_b64 vcc, exec, s[4:5]
	s_cbranch_vccz .LBB0_134
	s_cmpk_lt_i32 s24, 0x100
	s_movk_i32 s4, 0xf00
	s_cselect_b32 s4, s4, 0x1f00
	s_and_b32 s6, s4, s13
	v_add_u32_e32 v142, s6, v148
	v_ashrrev_i32_e32 v143, 31, v142
	v_lshlrev_b64 v[142:143], 8, v[142:143]
	v_lshl_add_u64 v[144:145], v[132:133], 0, v[142:143]
	global_load_dwordx4 v[152:155], v[144:145], off
	global_load_dwordx4 v[156:159], v[144:145], off offset:128
	s_cmp_eq_u32 s11, 0
	s_cselect_b64 vcc, -1, 0
	v_mov_b32_e32 v139, 0x3e000000
	v_cndmask_b32_e32 v140, 1.0, v139, vcc
	s_and_b64 s[4:5], vcc, exec
	s_mov_b32 s4, 0xe6d8000
	s_cselect_b32 s4, s4, 0x10ed8000
	v_readlane_b32 s8, v253, 1
	v_add_u32_e32 v142, s13, v148
	v_readlane_b32 s9, v253, 2
	s_add_u32 s4, s8, s4
	v_ashrrev_i32_e32 v143, 31, v142
	s_addc_u32 s5, s9, 0
	v_lshlrev_b64 v[142:143], 9, v[142:143]
	v_lshl_add_u64 v[142:143], s[4:5], 0, v[142:143]
	s_movk_i32 s4, 0x1000
	s_movk_i32 s5, 0x2000
	s_mov_b32 s11, s1
	v_lshl_add_u64 v[142:143], v[142:143], 0, s[10:11]
	v_mov_b32_e32 v139, v193
	v_lshl_add_u64 v[142:143], v[142:143], 0, v[138:139]
	s_waitcnt vmcnt(0)
	v_pk_mul_f32 v[146:147], v[120:121], v[156:157]
	s_nop 0
	v_pk_fma_f32 v[146:147], v[124:125], v[152:153], v[146:147] neg_lo:[0,0,1] neg_hi:[0,0,1]
	v_pk_mul_f32 v[124:125], v[124:125], v[156:157]
	v_pk_mul_f32 v[160:161], v[122:123], v[158:159]
	v_pk_fma_f32 v[120:121], v[120:121], v[152:153], v[124:125]
	v_pk_mul_f32 v[124:125], v[126:127], v[158:159]
	v_pk_mul_f32 v[120:121], v[140:141], v[120:121] op_sel_hi:[0,1]
	v_pk_fma_f32 v[122:123], v[122:123], v[154:155], v[124:125]
	v_cvt_pk_bf16_f32 v120, v120, v121
	v_pk_mul_f32 v[122:123], v[140:141], v[122:123] op_sel_hi:[0,1]
	v_cvt_pk_bf16_f32 v121, v122, v123
	v_pk_mul_f32 v[122:123], v[112:113], v[156:157]
	v_pk_mul_f32 v[124:125], v[114:115], v[158:159]
	v_pk_fma_f32 v[122:123], v[116:117], v[152:153], v[122:123] neg_lo:[0,0,1] neg_hi:[0,0,1]
	v_pk_mul_f32 v[116:117], v[116:117], v[156:157]
	v_pk_fma_f32 v[124:125], v[118:119], v[154:155], v[124:125] neg_lo:[0,0,1] neg_hi:[0,0,1]
	v_pk_fma_f32 v[112:113], v[112:113], v[152:153], v[116:117]
	v_pk_mul_f32 v[116:117], v[118:119], v[158:159]
	v_pk_mul_f32 v[112:113], v[140:141], v[112:113] op_sel_hi:[0,1]
	v_pk_fma_f32 v[114:115], v[114:115], v[154:155], v[116:117]
	v_cvt_pk_bf16_f32 v112, v112, v113
	v_pk_mul_f32 v[114:115], v[140:141], v[114:115] op_sel_hi:[0,1]
	v_cvt_pk_bf16_f32 v113, v114, v115
	v_add_co_u32_e32 v114, vcc, s4, v144
	v_pk_mul_f32 v[122:123], v[140:141], v[122:123] op_sel_hi:[0,1]
	s_nop 0
	v_addc_co_u32_e32 v115, vcc, 0, v145, vcc
	v_add_co_u32_e32 v152, vcc, s5, v144
	v_pk_mul_f32 v[124:125], v[140:141], v[124:125] op_sel_hi:[0,1]
	s_nop 0
	v_addc_co_u32_e32 v153, vcc, 0, v145, vcc
	v_pk_fma_f32 v[160:161], v[126:127], v[154:155], v[160:161] neg_lo:[0,0,1] neg_hi:[0,0,1]
	v_cvt_pk_bf16_f32 v122, v122, v123
	v_cvt_pk_bf16_f32 v123, v124, v125
	global_load_dwordx4 v[116:119], v[152:153], off offset:-4096
	global_load_dwordx4 v[124:127], v[114:115], off offset:128
	s_movk_i32 s4, 0x3000
	v_pk_mul_f32 v[146:147], v[140:141], v[146:147] op_sel_hi:[0,1]
	v_pk_mul_f32 v[160:161], v[140:141], v[160:161] op_sel_hi:[0,1]
	v_cvt_pk_bf16_f32 v146, v146, v147
	v_cvt_pk_bf16_f32 v147, v160, v161
	s_waitcnt vmcnt(0)
	v_pk_mul_f32 v[114:115], v[104:105], v[124:125]
	s_nop 0
	v_pk_fma_f32 v[114:115], v[108:109], v[116:117], v[114:115] neg_lo:[0,0,1] neg_hi:[0,0,1]
	v_pk_mul_f32 v[108:109], v[108:109], v[124:125]
	v_pk_mul_f32 v[154:155], v[106:107], v[126:127]
	v_pk_fma_f32 v[104:105], v[104:105], v[116:117], v[108:109]
	v_pk_mul_f32 v[108:109], v[110:111], v[126:127]
	v_pk_mul_f32 v[104:105], v[140:141], v[104:105] op_sel_hi:[0,1]
	v_pk_fma_f32 v[106:107], v[106:107], v[118:119], v[108:109]
	v_cvt_pk_bf16_f32 v104, v104, v105
	v_pk_mul_f32 v[106:107], v[140:141], v[106:107] op_sel_hi:[0,1]
	v_cvt_pk_bf16_f32 v105, v106, v107
	v_pk_mul_f32 v[106:107], v[88:89], v[124:125]
	v_pk_mul_f32 v[108:109], v[90:91], v[126:127]
	v_pk_fma_f32 v[106:107], v[92:93], v[116:117], v[106:107] neg_lo:[0,0,1] neg_hi:[0,0,1]
	v_pk_fma_f32 v[108:109], v[94:95], v[118:119], v[108:109] neg_lo:[0,0,1] neg_hi:[0,0,1]
	v_pk_mul_f32 v[92:93], v[92:93], v[124:125]
	v_pk_mul_f32 v[106:107], v[140:141], v[106:107] op_sel_hi:[0,1]
	v_pk_mul_f32 v[108:109], v[140:141], v[108:109] op_sel_hi:[0,1]
	v_pk_fma_f32 v[88:89], v[88:89], v[116:117], v[92:93]
	v_pk_mul_f32 v[92:93], v[94:95], v[126:127]
	v_pk_fma_f32 v[154:155], v[110:111], v[118:119], v[154:155] neg_lo:[0,0,1] neg_hi:[0,0,1]
	v_cvt_pk_bf16_f32 v106, v106, v107
	v_cvt_pk_bf16_f32 v107, v108, v109
	v_pk_fma_f32 v[90:91], v[90:91], v[118:119], v[92:93]
	global_load_dwordx4 v[108:111], v[152:153], off
	global_load_dwordx4 v[116:119], v[152:153], off offset:128
	v_pk_mul_f32 v[88:89], v[140:141], v[88:89] op_sel_hi:[0,1]
	v_pk_mul_f32 v[90:91], v[140:141], v[90:91] op_sel_hi:[0,1]
	v_cvt_pk_bf16_f32 v88, v88, v89
	v_cvt_pk_bf16_f32 v89, v90, v91
	v_pk_mul_f32 v[114:115], v[140:141], v[114:115] op_sel_hi:[0,1]
	v_pk_mul_f32 v[154:155], v[140:141], v[154:155] op_sel_hi:[0,1]
	v_cvt_pk_bf16_f32 v114, v114, v115
	v_cvt_pk_bf16_f32 v115, v154, v155
	s_waitcnt vmcnt(0)
	v_pk_mul_f32 v[90:91], v[96:97], v[116:117]
	v_pk_mul_f32 v[92:93], v[98:99], v[118:119]
	v_pk_fma_f32 v[90:91], v[100:101], v[108:109], v[90:91] neg_lo:[0,0,1] neg_hi:[0,0,1]
	v_pk_fma_f32 v[92:93], v[102:103], v[110:111], v[92:93] neg_lo:[0,0,1] neg_hi:[0,0,1]
	v_pk_mul_f32 v[90:91], v[140:141], v[90:91] op_sel_hi:[0,1]
	v_pk_mul_f32 v[92:93], v[140:141], v[92:93] op_sel_hi:[0,1]
	v_cvt_pk_bf16_f32 v90, v90, v91
	v_cvt_pk_bf16_f32 v91, v92, v93
	v_pk_mul_f32 v[92:93], v[100:101], v[116:117]
	v_pk_mul_f32 v[94:95], v[102:103], v[118:119]
	v_pk_fma_f32 v[92:93], v[96:97], v[108:109], v[92:93]
	v_pk_fma_f32 v[94:95], v[98:99], v[110:111], v[94:95]
	v_pk_mul_f32 v[92:93], v[140:141], v[92:93] op_sel_hi:[0,1]
	v_pk_mul_f32 v[94:95], v[140:141], v[94:95] op_sel_hi:[0,1]
	v_cvt_pk_bf16_f32 v92, v92, v93
	v_cvt_pk_bf16_f32 v93, v94, v95
	v_pk_mul_f32 v[94:95], v[80:81], v[116:117]
	v_pk_mul_f32 v[96:97], v[82:83], v[118:119]
	v_pk_fma_f32 v[94:95], v[84:85], v[108:109], v[94:95] neg_lo:[0,0,1] neg_hi:[0,0,1]
	v_pk_mul_f32 v[84:85], v[84:85], v[116:117]
	v_pk_fma_f32 v[96:97], v[86:87], v[110:111], v[96:97] neg_lo:[0,0,1] neg_hi:[0,0,1]
	v_pk_fma_f32 v[80:81], v[80:81], v[108:109], v[84:85]
	v_pk_mul_f32 v[84:85], v[86:87], v[118:119]
	v_pk_mul_f32 v[94:95], v[140:141], v[94:95] op_sel_hi:[0,1]
	v_pk_fma_f32 v[82:83], v[82:83], v[110:111], v[84:85]
	v_add_co_u32_e32 v84, vcc, s4, v144
	v_pk_mul_f32 v[96:97], v[140:141], v[96:97] op_sel_hi:[0,1]
	v_pk_mul_f32 v[80:81], v[140:141], v[80:81] op_sel_hi:[0,1]
	v_pk_mul_f32 v[82:83], v[140:141], v[82:83] op_sel_hi:[0,1]
	v_addc_co_u32_e32 v85, vcc, 0, v145, vcc
	v_cvt_pk_bf16_f32 v94, v94, v95
	v_cvt_pk_bf16_f32 v95, v96, v97
	v_cvt_pk_bf16_f32 v96, v80, v81
	v_cvt_pk_bf16_f32 v97, v82, v83
	global_load_dwordx4 v[80:83], v[84:85], off
	s_nop 0
	global_load_dwordx4 v[84:87], v[84:85], off offset:128
	v_add_co_u32_e32 v100, vcc, s5, v142
	s_movk_i32 s4, 0x4000
	s_nop 0
	v_addc_co_u32_e32 v101, vcc, 0, v143, vcc
	global_store_dwordx2 v[142:143], v[146:147], off
	global_store_dwordx2 v[142:143], v[120:121], off offset:64
	global_store_dwordx2 v[142:143], v[122:123], off offset:256
	global_store_dwordx2 v[142:143], v[112:113], off offset:320
	global_store_dwordx2 v[100:101], v[114:115], off
	global_store_dwordx2 v[100:101], v[104:105], off offset:64
	global_store_dwordx2 v[100:101], v[106:107], off offset:256
	global_store_dwordx2 v[100:101], v[88:89], off offset:320
	v_add_co_u32_e32 v88, vcc, s4, v142
	s_movk_i32 s4, 0x6000
	s_nop 0
	v_addc_co_u32_e32 v89, vcc, 0, v143, vcc
	global_store_dwordx2 v[88:89], v[90:91], off
	global_store_dwordx2 v[88:89], v[92:93], off offset:64
	global_store_dwordx2 v[88:89], v[94:95], off offset:256
	global_store_dwordx2 v[88:89], v[96:97], off offset:320
	s_waitcnt vmcnt(0)
	v_pk_mul_f32 v[98:99], v[72:73], v[84:85]
	s_nop 0
	v_pk_fma_f32 v[98:99], v[76:77], v[80:81], v[98:99] neg_lo:[0,0,1] neg_hi:[0,0,1]
	v_pk_mul_f32 v[88:89], v[74:75], v[86:87]
	v_pk_mul_f32 v[76:77], v[76:77], v[84:85]
	v_pk_fma_f32 v[88:89], v[78:79], v[82:83], v[88:89] neg_lo:[0,0,1] neg_hi:[0,0,1]
	v_pk_fma_f32 v[72:73], v[72:73], v[80:81], v[76:77]
	v_pk_mul_f32 v[76:77], v[78:79], v[86:87]
	v_pk_mul_f32 v[88:89], v[140:141], v[88:89] op_sel_hi:[0,1]
	v_pk_fma_f32 v[74:75], v[74:75], v[82:83], v[76:77]
	v_cvt_pk_bf16_f32 v91, v88, v89
	v_add_co_u32_e32 v88, vcc, s4, v142
	v_pk_mul_f32 v[72:73], v[140:141], v[72:73] op_sel_hi:[0,1]
	v_pk_mul_f32 v[74:75], v[140:141], v[74:75] op_sel_hi:[0,1]
	v_addc_co_u32_e32 v89, vcc, 0, v143, vcc
	v_cvt_pk_bf16_f32 v72, v72, v73
	v_cvt_pk_bf16_f32 v73, v74, v75
	global_store_dwordx2 v[88:89], v[72:73], off offset:64
	v_pk_mul_f32 v[72:73], v[64:65], v[84:85]
	v_pk_mul_f32 v[74:75], v[66:67], v[86:87]
	v_pk_fma_f32 v[72:73], v[68:69], v[80:81], v[72:73] neg_lo:[0,0,1] neg_hi:[0,0,1]
	v_pk_mul_f32 v[68:69], v[68:69], v[84:85]
	v_pk_fma_f32 v[74:75], v[70:71], v[82:83], v[74:75] neg_lo:[0,0,1] neg_hi:[0,0,1]
	v_pk_fma_f32 v[64:65], v[64:65], v[80:81], v[68:69]
	v_pk_mul_f32 v[68:69], v[70:71], v[86:87]
	v_pk_mul_f32 v[64:65], v[140:141], v[64:65] op_sel_hi:[0,1]
	v_pk_fma_f32 v[66:67], v[66:67], v[82:83], v[68:69]
	v_cvt_pk_bf16_f32 v64, v64, v65
	v_pk_mul_f32 v[66:67], v[140:141], v[66:67] op_sel_hi:[0,1]
	v_cvt_pk_bf16_f32 v65, v66, v67
	s_mov_b32 s4, 0x8000
	v_pk_mul_f32 v[98:99], v[140:141], v[98:99] op_sel_hi:[0,1]
	v_pk_mul_f32 v[72:73], v[140:141], v[72:73] op_sel_hi:[0,1]
	v_pk_mul_f32 v[74:75], v[140:141], v[74:75] op_sel_hi:[0,1]
	global_store_dwordx2 v[88:89], v[64:65], off offset:320
	v_add_co_u32_e32 v64, vcc, s4, v144
	v_cvt_pk_bf16_f32 v90, v98, v99
	v_cvt_pk_bf16_f32 v72, v72, v73
	v_cvt_pk_bf16_f32 v73, v74, v75
	v_addc_co_u32_e32 v65, vcc, 0, v145, vcc
	s_mov_b32 s4, 0x9000
	global_store_dwordx2 v[88:89], v[90:91], off
	global_store_dwordx2 v[88:89], v[72:73], off offset:256
	v_add_co_u32_e32 v74, vcc, s4, v144
	s_mov_b32 s4, 0xa000
	s_nop 0
	v_addc_co_u32_e32 v75, vcc, 0, v145, vcc
	global_load_dwordx4 v[66:69], v[74:75], off offset:-4096
	global_load_dwordx4 v[70:73], v[64:65], off offset:128
	s_waitcnt vmcnt(0)
	v_pk_mul_f32 v[64:65], v[56:57], v[70:71]
	s_nop 0
	v_pk_fma_f32 v[64:65], v[60:61], v[66:67], v[64:65] neg_lo:[0,0,1] neg_hi:[0,0,1]
	v_pk_mul_f32 v[60:61], v[60:61], v[70:71]
	v_pk_mul_f32 v[76:77], v[58:59], v[72:73]
	v_pk_fma_f32 v[56:57], v[56:57], v[66:67], v[60:61]
	v_pk_mul_f32 v[60:61], v[62:63], v[72:73]
	v_pk_mul_f32 v[56:57], v[140:141], v[56:57] op_sel_hi:[0,1]
	v_pk_fma_f32 v[58:59], v[58:59], v[68:69], v[60:61]
	v_cvt_pk_bf16_f32 v56, v56, v57
	v_pk_mul_f32 v[58:59], v[140:141], v[58:59] op_sel_hi:[0,1]
	v_cvt_pk_bf16_f32 v57, v58, v59
	v_pk_mul_f32 v[58:59], v[48:49], v[70:71]
	v_pk_mul_f32 v[60:61], v[50:51], v[72:73]
	v_pk_fma_f32 v[58:59], v[52:53], v[66:67], v[58:59] neg_lo:[0,0,1] neg_hi:[0,0,1]
	v_pk_fma_f32 v[60:61], v[54:55], v[68:69], v[60:61] neg_lo:[0,0,1] neg_hi:[0,0,1]
	v_pk_mul_f32 v[52:53], v[52:53], v[70:71]
	v_pk_mul_f32 v[58:59], v[140:141], v[58:59] op_sel_hi:[0,1]
	v_pk_mul_f32 v[60:61], v[140:141], v[60:61] op_sel_hi:[0,1]
	v_pk_fma_f32 v[48:49], v[48:49], v[66:67], v[52:53]
	v_pk_mul_f32 v[52:53], v[54:55], v[72:73]
	v_pk_fma_f32 v[76:77], v[62:63], v[68:69], v[76:77] neg_lo:[0,0,1] neg_hi:[0,0,1]
	v_cvt_pk_bf16_f32 v58, v58, v59
	v_cvt_pk_bf16_f32 v59, v60, v61
	v_pk_fma_f32 v[50:51], v[50:51], v[68:69], v[52:53]
	global_load_dwordx4 v[52:55], v[74:75], off
	global_load_dwordx4 v[60:63], v[74:75], off offset:128
	v_pk_mul_f32 v[48:49], v[140:141], v[48:49] op_sel_hi:[0,1]
	v_pk_mul_f32 v[50:51], v[140:141], v[50:51] op_sel_hi:[0,1]
	v_cvt_pk_bf16_f32 v48, v48, v49
	v_cvt_pk_bf16_f32 v49, v50, v51
	v_pk_mul_f32 v[64:65], v[140:141], v[64:65] op_sel_hi:[0,1]
	v_pk_mul_f32 v[76:77], v[140:141], v[76:77] op_sel_hi:[0,1]
	v_cvt_pk_bf16_f32 v64, v64, v65
	v_cvt_pk_bf16_f32 v65, v76, v77
	s_waitcnt vmcnt(0)
	v_pk_mul_f32 v[50:51], v[40:41], v[60:61]
	s_nop 0
	v_pk_fma_f32 v[50:51], v[44:45], v[52:53], v[50:51] neg_lo:[0,0,1] neg_hi:[0,0,1]
	v_pk_mul_f32 v[44:45], v[44:45], v[60:61]
	v_pk_mul_f32 v[66:67], v[42:43], v[62:63]
	v_pk_fma_f32 v[40:41], v[40:41], v[52:53], v[44:45]
	v_pk_mul_f32 v[44:45], v[46:47], v[62:63]
	v_pk_mul_f32 v[40:41], v[140:141], v[40:41] op_sel_hi:[0,1]
	v_pk_fma_f32 v[42:43], v[42:43], v[54:55], v[44:45]
	v_cvt_pk_bf16_f32 v40, v40, v41
	v_pk_mul_f32 v[42:43], v[140:141], v[42:43] op_sel_hi:[0,1]
	v_cvt_pk_bf16_f32 v41, v42, v43
	v_pk_mul_f32 v[42:43], v[32:33], v[60:61]
	v_pk_mul_f32 v[44:45], v[34:35], v[62:63]
	v_pk_fma_f32 v[42:43], v[36:37], v[52:53], v[42:43] neg_lo:[0,0,1] neg_hi:[0,0,1]
	v_pk_mul_f32 v[36:37], v[36:37], v[60:61]
	v_pk_fma_f32 v[44:45], v[38:39], v[54:55], v[44:45] neg_lo:[0,0,1] neg_hi:[0,0,1]
	v_pk_fma_f32 v[32:33], v[32:33], v[52:53], v[36:37]
	v_pk_mul_f32 v[36:37], v[38:39], v[62:63]
	v_pk_mul_f32 v[32:33], v[140:141], v[32:33] op_sel_hi:[0,1]
	v_pk_fma_f32 v[34:35], v[34:35], v[54:55], v[36:37]
	v_cvt_pk_bf16_f32 v32, v32, v33
	v_pk_mul_f32 v[34:35], v[140:141], v[34:35] op_sel_hi:[0,1]
	v_cvt_pk_bf16_f32 v33, v34, v35
	v_add_co_u32_e32 v34, vcc, s4, v144
	s_mov_b32 s4, 0xb000
	s_nop 0
	v_addc_co_u32_e32 v35, vcc, 0, v145, vcc
	v_add_co_u32_e32 v36, vcc, s4, v144
	v_pk_mul_f32 v[42:43], v[140:141], v[42:43] op_sel_hi:[0,1]
	v_pk_mul_f32 v[44:45], v[140:141], v[44:45] op_sel_hi:[0,1]
	v_addc_co_u32_e32 v37, vcc, 0, v145, vcc
	v_pk_fma_f32 v[66:67], v[46:47], v[54:55], v[66:67] neg_lo:[0,0,1] neg_hi:[0,0,1]
	v_cvt_pk_bf16_f32 v42, v42, v43
	v_cvt_pk_bf16_f32 v43, v44, v45
	global_load_dwordx4 v[44:47], v[36:37], off offset:-4096
	global_load_dwordx4 v[52:55], v[34:35], off offset:128
	s_mov_b32 s4, 0x10000
	v_pk_mul_f32 v[50:51], v[140:141], v[50:51] op_sel_hi:[0,1]
	v_pk_mul_f32 v[66:67], v[140:141], v[66:67] op_sel_hi:[0,1]
	v_cvt_pk_bf16_f32 v50, v50, v51
	v_cvt_pk_bf16_f32 v51, v66, v67
	s_waitcnt vmcnt(0)
	v_pk_mul_f32 v[34:35], v[24:25], v[52:53]
	s_nop 0
	v_pk_fma_f32 v[34:35], v[28:29], v[44:45], v[34:35] neg_lo:[0,0,1] neg_hi:[0,0,1]
	v_pk_mul_f32 v[28:29], v[28:29], v[52:53]
	v_pk_mul_f32 v[38:39], v[26:27], v[54:55]
	v_pk_fma_f32 v[24:25], v[24:25], v[44:45], v[28:29]
	v_pk_mul_f32 v[28:29], v[30:31], v[54:55]
	v_pk_mul_f32 v[24:25], v[140:141], v[24:25] op_sel_hi:[0,1]
	v_pk_fma_f32 v[26:27], v[26:27], v[46:47], v[28:29]
	v_cvt_pk_bf16_f32 v24, v24, v25
	v_pk_mul_f32 v[26:27], v[140:141], v[26:27] op_sel_hi:[0,1]
	v_cvt_pk_bf16_f32 v25, v26, v27
	v_pk_mul_f32 v[26:27], v[16:17], v[52:53]
	v_pk_mul_f32 v[28:29], v[18:19], v[54:55]
	v_pk_fma_f32 v[26:27], v[20:21], v[44:45], v[26:27] neg_lo:[0,0,1] neg_hi:[0,0,1]
	v_pk_mul_f32 v[20:21], v[20:21], v[52:53]
	v_pk_fma_f32 v[28:29], v[22:23], v[46:47], v[28:29] neg_lo:[0,0,1] neg_hi:[0,0,1]
	v_pk_fma_f32 v[16:17], v[16:17], v[44:45], v[20:21]
	v_pk_mul_f32 v[20:21], v[22:23], v[54:55]
	v_pk_mul_f32 v[26:27], v[140:141], v[26:27] op_sel_hi:[0,1]
	v_pk_fma_f32 v[18:19], v[18:19], v[46:47], v[20:21]
	v_pk_mul_f32 v[28:29], v[140:141], v[28:29] op_sel_hi:[0,1]
	v_pk_mul_f32 v[16:17], v[140:141], v[16:17] op_sel_hi:[0,1]
	v_pk_mul_f32 v[18:19], v[140:141], v[18:19] op_sel_hi:[0,1]
	v_cvt_pk_bf16_f32 v26, v26, v27
	v_cvt_pk_bf16_f32 v27, v28, v29
	v_cvt_pk_bf16_f32 v28, v16, v17
	v_cvt_pk_bf16_f32 v29, v18, v19
	global_load_dwordx4 v[16:19], v[36:37], off
	global_load_dwordx4 v[20:23], v[36:37], off offset:128
	v_add_co_u32_e32 v36, vcc, s4, v142
	s_mov_b32 s4, 0x12000
	s_nop 0
	v_addc_co_u32_e32 v37, vcc, 0, v143, vcc
	global_store_dwordx2 v[36:37], v[64:65], off
	global_store_dwordx2 v[36:37], v[56:57], off offset:64
	global_store_dwordx2 v[36:37], v[58:59], off offset:256
	global_store_dwordx2 v[36:37], v[48:49], off offset:320
	v_add_co_u32_e32 v36, vcc, s4, v142
	v_pk_fma_f32 v[38:39], v[30:31], v[46:47], v[38:39] neg_lo:[0,0,1] neg_hi:[0,0,1]
	s_nop 0
	v_addc_co_u32_e32 v37, vcc, 0, v143, vcc
	s_mov_b32 s4, 0x14000
	v_pk_mul_f32 v[34:35], v[140:141], v[34:35] op_sel_hi:[0,1]
	v_pk_mul_f32 v[38:39], v[140:141], v[38:39] op_sel_hi:[0,1]
	global_store_dwordx2 v[36:37], v[50:51], off
	global_store_dwordx2 v[36:37], v[40:41], off offset:64
	global_store_dwordx2 v[36:37], v[42:43], off offset:256
	global_store_dwordx2 v[36:37], v[32:33], off offset:320
	v_add_co_u32_e32 v32, vcc, s4, v142
	v_cvt_pk_bf16_f32 v34, v34, v35
	v_cvt_pk_bf16_f32 v35, v38, v39
	v_addc_co_u32_e32 v33, vcc, 0, v143, vcc
	global_store_dwordx2 v[32:33], v[34:35], off
	global_store_dwordx2 v[32:33], v[24:25], off offset:64
	global_store_dwordx2 v[32:33], v[26:27], off offset:256
	global_store_dwordx2 v[32:33], v[28:29], off offset:320
	s_mov_b32 s4, 0x16000
	s_waitcnt vmcnt(0)
	v_pk_mul_f32 v[30:31], v[8:9], v[20:21]
	s_nop 0
	v_pk_fma_f32 v[30:31], v[12:13], v[16:17], v[30:31] neg_lo:[0,0,1] neg_hi:[0,0,1]
	v_pk_mul_f32 v[24:25], v[10:11], v[22:23]
	v_pk_mul_f32 v[12:13], v[12:13], v[20:21]
	v_pk_fma_f32 v[24:25], v[14:15], v[18:19], v[24:25] neg_lo:[0,0,1] neg_hi:[0,0,1]
	v_pk_fma_f32 v[8:9], v[8:9], v[16:17], v[12:13]
	v_pk_mul_f32 v[12:13], v[14:15], v[22:23]
	v_pk_mul_f32 v[24:25], v[140:141], v[24:25] op_sel_hi:[0,1]
	v_pk_fma_f32 v[10:11], v[10:11], v[18:19], v[12:13]
	v_cvt_pk_bf16_f32 v27, v24, v25
	v_add_co_u32_e32 v24, vcc, s4, v142
	v_pk_mul_f32 v[8:9], v[140:141], v[8:9] op_sel_hi:[0,1]
	v_pk_mul_f32 v[10:11], v[140:141], v[10:11] op_sel_hi:[0,1]
	v_addc_co_u32_e32 v25, vcc, 0, v143, vcc
	v_cvt_pk_bf16_f32 v8, v8, v9
	v_cvt_pk_bf16_f32 v9, v10, v11
	global_store_dwordx2 v[24:25], v[8:9], off offset:64
	v_pk_mul_f32 v[8:9], v[0:1], v[20:21]
	v_pk_mul_f32 v[10:11], v[2:3], v[22:23]
	v_pk_fma_f32 v[8:9], v[4:5], v[16:17], v[8:9] neg_lo:[0,0,1] neg_hi:[0,0,1]
	v_pk_mul_f32 v[4:5], v[4:5], v[20:21]
	v_pk_fma_f32 v[10:11], v[6:7], v[18:19], v[10:11] neg_lo:[0,0,1] neg_hi:[0,0,1]
	v_pk_fma_f32 v[0:1], v[0:1], v[16:17], v[4:5]
	v_pk_mul_f32 v[4:5], v[6:7], v[22:23]
	v_pk_mul_f32 v[30:31], v[140:141], v[30:31] op_sel_hi:[0,1]
	v_pk_fma_f32 v[2:3], v[2:3], v[18:19], v[4:5]
	v_pk_mul_f32 v[8:9], v[140:141], v[8:9] op_sel_hi:[0,1]
	v_pk_mul_f32 v[10:11], v[140:141], v[10:11] op_sel_hi:[0,1]
	v_pk_mul_f32 v[0:1], v[140:141], v[0:1] op_sel_hi:[0,1]
	v_pk_mul_f32 v[2:3], v[140:141], v[2:3] op_sel_hi:[0,1]
	v_cvt_pk_bf16_f32 v26, v30, v31
	v_cvt_pk_bf16_f32 v8, v8, v9
	v_cvt_pk_bf16_f32 v9, v10, v11
	v_cvt_pk_bf16_f32 v0, v0, v1
	v_cvt_pk_bf16_f32 v1, v2, v3
	global_store_dwordx2 v[24:25], v[26:27], off
	global_store_dwordx2 v[24:25], v[8:9], off offset:256
	global_store_dwordx2 v[24:25], v[0:1], off offset:320
	s_branch .LBB0_134
.LBB0_436:
	s_waitcnt vmcnt(0)
	s_cmpk_gt_u32 s31, 0xff
	s_cbranch_scc1 .LBB0_438
	s_barrier

.Lna_vwr_done:
.LBB0_531:
	v_add_u32_e32 v28, s17, v15
	v_lshlrev_b32_e32 v0, 6, v28
	v_lshl_or_b32 v30, s19, 4, v17
	v_add3_u32 v20, s6, v30, v0
	v_ashrrev_i32_e32 v21, 31, v20
	v_readlane_b32 s6, v254, 0
	v_lshlrev_b64 v[0:1], 9, v[20:21]
	v_readlane_b32 s7, v254, 1
	v_lshlrev_b32_e32 v192, 1, v14
	s_nop 0
	v_lshl_add_u64 v[0:1], s[6:7], 0, v[0:1]
	v_lshl_add_u64 v[0:1], v[18:19], 1, v[0:1]
	v_lshl_add_u64 v[0:1], v[0:1], 0, v[192:193]
	global_load_dwordx4 v[148:151], v[0:1], off
	global_load_dwordx4 v[152:155], v[0:1], off offset:64
	s_waitcnt lgkmcnt(0)
	s_barrier
	v_mov_b32_e32 v156, 0xf149f2ca
	v_add_u32_e32 v8, -4, v28
	v_min_i32_e32 v8, s18, v8
	v_cmp_lt_i32_e32 vcc, 3, v28
	v_add_u32_e32 v32, s8, v14
	v_med3_i32 v35, v30, 8, 56
	v_cndmask_b32_e32 v29, 0, v8, vcc
	v_subrev_u32_e32 v8, s16, v29
	v_lshlrev_b32_e32 v86, 5, v8
	v_or_b32_e32 v8, v86, v31
	v_mad_u64_u32 v[22:23], s[6:7], v8, s79, v[16:17]
	ds_read2_b64 v[8:11], v22 offset1:1
	ds_read2_b64 v[24:27], v22 offset0:8 offset1:9
	v_sub_u32_e32 v23, v32, v35
	v_add_u32_e32 v23, 8, v23
	v_sub_u32_e32 v28, v29, v28
	s_movk_i32 s0, 0x7c
	v_cmp_gt_u32_e32 vcc, 16, v23
	v_mul_lo_u32 v23, v28, s0
	v_add_u32_e32 v33, 0x1f300, v23
	v_sub_u32_e32 v23, v32, v30
	v_med3_i32 v44, v23, -15, 15
	s_waitcnt vmcnt(0)
	v_mov_b32_e32 v4, v148
	v_mov_b32_e32 v5, v149
	v_mov_b32_e32 v6, v150
	v_mov_b32_e32 v7, v151
	v_mov_b32_e32 v0, v152
	v_mov_b32_e32 v1, v153
	v_mov_b32_e32 v2, v154
	v_mov_b32_e32 v3, v155
	s_waitcnt lgkmcnt(1)
	v_mfma_f32_16x16x32_bf16 v[8:11], v[8:11], v[4:7], 0
	s_waitcnt lgkmcnt(0)
	v_mfma_f32_16x16x32_bf16 v[8:11], v[24:27], v[0:3], v[8:11]
	v_mov_b32_e32 v24, 0xf149f2ca
	v_mov_b32_e32 v26, 0xf149f2ca
	s_and_saveexec_b64 s[6:7], vcc
	s_cbranch_execz .LBB0_533
	v_lshl_add_u32 v23, v44, 2, v33
	ds_read_b32 v23, v23 offset:928
	s_waitcnt lgkmcnt(0)
	s_nop 0
	v_add_f32_e32 v26, v8, v23

.LBB0_547:
	s_or_b64 exec, exec, s[22:23]
	v_lshl_add_u32 v157, v44, 2, v33
	ds_read_b32 v157, v157 offset:1052
	v_lshl_add_u32 v158, v45, 2, v33
	ds_read_b32 v158, v158 offset:1052
	v_lshl_add_u32 v159, v46, 2, v33
	ds_read_b32 v159, v159 offset:1052
	v_lshl_add_u32 v160, v47, 2, v33
	ds_read_b32 v160, v160 offset:1052
	v_add_u32_e32 v8, 0x1100, v22
	ds_read2_b64 v[8:11], v8 offset1:1
	v_add_u32_e32 v30, 0x1140, v22
	ds_read2_b64 v[36:39], v30 offset1:1
	v_mov_b32_e32 v30, 0xf149f2ca
	v_mov_b32_e32 v32, 0xf149f2ca
	s_waitcnt lgkmcnt(1)
	v_mfma_f32_16x16x32_bf16 v[8:11], v[8:11], v[4:7], 0
	s_waitcnt lgkmcnt(0)
	v_mfma_f32_16x16x32_bf16 v[8:11], v[36:39], v[0:3], v[8:11]
	v_mov_b32_e32 v35, 0xf149f2ca
	v_mov_b32_e32 v36, 0xf149f2ca
	s_nop 4
	s_waitcnt lgkmcnt(0)
	v_add_f32_e32 v157, v8, v157
	v_add_f32_e32 v158, v9, v158
	v_add_f32_e32 v159, v10, v159
	v_add_f32_e32 v160, v11, v160
	v_cndmask_b32_e64 v32, v156, v157, vcc
	v_cndmask_b32_e64 v30, v156, v158, s[6:7]
	v_cndmask_b32_e64 v36, v156, v159, s[8:9]
	v_cndmask_b32_e64 v35, v156, v160, s[10:11]
	v_lshl_add_u32 v157, v49, 2, v33
	ds_read_b32 v157, v157 offset:1052
	v_lshl_add_u32 v158, v52, 2, v33
	ds_read_b32 v158, v158 offset:1052
	v_lshl_add_u32 v159, v53, 2, v33
	ds_read_b32 v159, v159 offset:1052
	v_lshl_add_u32 v160, v56, 2, v33
	ds_read_b32 v160, v160 offset:1052
	v_add_u32_e32 v8, 0x1320, v22
	ds_read2_b64 v[8:11], v8 offset1:1
	v_add_u32_e32 v37, 0x1360, v22
	ds_read2_b64 v[38:41], v37 offset1:1
	v_mov_b32_e32 v37, 0xf149f2ca
	s_waitcnt lgkmcnt(1)
	v_mfma_f32_16x16x32_bf16 v[8:11], v[8:11], v[4:7], 0
	s_waitcnt lgkmcnt(0)
	v_mfma_f32_16x16x32_bf16 v[8:11], v[38:41], v[0:3], v[8:11]
	v_mov_b32_e32 v38, 0xf149f2ca
	v_mov_b32_e32 v39, 0xf149f2ca
	v_mov_b32_e32 v40, 0xf149f2ca
	s_nop 3
	s_waitcnt lgkmcnt(0)
	v_add_f32_e32 v157, v8, v157
	v_add_f32_e32 v158, v9, v158
	v_add_f32_e32 v159, v10, v159
	v_add_f32_e32 v160, v11, v160
	v_cndmask_b32_e64 v38, v156, v157, s[12:13]
	v_cndmask_b32_e64 v37, v156, v158, s[14:15]
	v_cndmask_b32_e64 v40, v156, v159, s[16:17]
	v_cndmask_b32_e64 v39, v156, v160, s[18:19]
	v_lshl_add_u32 v157, v44, 2, v33
	ds_read_b32 v157, v157 offset:1176
	v_lshl_add_u32 v158, v45, 2, v33
	ds_read_b32 v158, v158 offset:1176
	v_lshl_add_u32 v159, v46, 2, v33
	ds_read_b32 v159, v159 offset:1176
	v_lshl_add_u32 v160, v47, 2, v33
	ds_read_b32 v160, v160 offset:1176
	v_add_u32_e32 v8, 0x2200, v22
	ds_read2_b64 v[8:11], v8 offset1:1
	v_add_u32_e32 v41, 0x2240, v22
	ds_read2_b64 v[58:61], v41 offset1:1
	v_mov_b32_e32 v41, 0xf149f2ca
	v_mov_b32_e32 v42, 0xf149f2ca
	s_waitcnt lgkmcnt(1)
	v_mfma_f32_16x16x32_bf16 v[8:11], v[8:11], v[4:7], 0
	s_waitcnt lgkmcnt(0)
	v_mfma_f32_16x16x32_bf16 v[8:11], v[58:61], v[0:3], v[8:11]
	v_mov_b32_e32 v43, 0xf149f2ca
	v_mov_b32_e32 v48, 0xf149f2ca
	s_nop 4
	s_waitcnt lgkmcnt(0)
	v_add_f32_e32 v157, v8, v157
	v_add_f32_e32 v158, v9, v158
	v_add_f32_e32 v159, v10, v159
	v_add_f32_e32 v160, v11, v160
	v_cndmask_b32_e64 v42, v156, v157, vcc
	v_cndmask_b32_e64 v41, v156, v158, s[6:7]
	v_cndmask_b32_e64 v48, v156, v159, s[8:9]
	v_cndmask_b32_e64 v43, v156, v160, s[10:11]
	v_lshl_add_u32 v157, v49, 2, v33
	ds_read_b32 v157, v157 offset:1176
	v_lshl_add_u32 v158, v52, 2, v33
	ds_read_b32 v158, v158 offset:1176
	v_lshl_add_u32 v159, v53, 2, v33
	ds_read_b32 v159, v159 offset:1176
	v_lshl_add_u32 v160, v56, 2, v33
	ds_read_b32 v160, v160 offset:1176
	v_add_u32_e32 v8, 0x2420, v22
	ds_read2_b64 v[8:11], v8 offset1:1
	v_add_u32_e32 v50, 0x2460, v22
	ds_read2_b64 v[58:61], v50 offset1:1
	v_mov_b32_e32 v50, 0xf149f2ca
	v_mov_b32_e32 v51, 0xf149f2ca
	s_waitcnt lgkmcnt(1)
	v_mfma_f32_16x16x32_bf16 v[8:11], v[8:11], v[4:7], 0
	s_waitcnt lgkmcnt(0)
	v_mfma_f32_16x16x32_bf16 v[8:11], v[58:61], v[0:3], v[8:11]
	v_mov_b32_e32 v54, 0xf149f2ca
	v_mov_b32_e32 v55, 0xf149f2ca
	s_nop 4
	s_waitcnt lgkmcnt(0)
	v_add_f32_e32 v157, v8, v157
	v_add_f32_e32 v158, v9, v158
	v_add_f32_e32 v159, v10, v159
	v_add_f32_e32 v160, v11, v160
	v_cndmask_b32_e64 v51, v156, v157, s[12:13]
	v_cndmask_b32_e64 v50, v156, v158, s[14:15]
	v_cndmask_b32_e64 v55, v156, v159, s[16:17]
	v_cndmask_b32_e64 v54, v156, v160, s[18:19]
	v_lshl_add_u32 v157, v44, 2, v33
	ds_read_b32 v157, v157 offset:1300
	v_lshl_add_u32 v158, v45, 2, v33
	ds_read_b32 v158, v158 offset:1300
	v_lshl_add_u32 v159, v46, 2, v33
	ds_read_b32 v159, v159 offset:1300
	v_lshl_add_u32 v160, v47, 2, v33
	ds_read_b32 v160, v160 offset:1300
	v_add_u32_e32 v8, 0x3300, v22
	ds_read2_b64 v[8:11], v8 offset1:1
	v_add_u32_e32 v57, 0x3340, v22
	ds_read2_b64 v[58:61], v57 offset1:1
	s_waitcnt lgkmcnt(1)
	v_mfma_f32_16x16x32_bf16 v[8:11], v[8:11], v[4:7], 0
	s_waitcnt lgkmcnt(0)
	v_mfma_f32_16x16x32_bf16 v[8:11], v[58:61], v[0:3], v[8:11]
	v_mov_b32_e32 v60, 0xf149f2ca
	v_mov_b32_e32 v61, 0xf149f2ca
	v_mov_b32_e32 v62, 0xf149f2ca
	v_mov_b32_e32 v63, 0xf149f2ca
	s_nop 2
	s_waitcnt lgkmcnt(0)
	v_add_f32_e32 v157, v8, v157
	v_add_f32_e32 v158, v9, v158
	v_add_f32_e32 v159, v10, v159
	v_add_f32_e32 v160, v11, v160
	v_cndmask_b32_e64 v61, v156, v157, vcc
	v_cndmask_b32_e64 v60, v156, v158, s[6:7]
	v_cndmask_b32_e64 v63, v156, v159, s[8:9]
	v_cndmask_b32_e64 v62, v156, v160, s[10:11]
	v_lshl_add_u32 v157, v49, 2, v33
	ds_read_b32 v157, v157 offset:1300
	v_lshl_add_u32 v158, v52, 2, v33
	ds_read_b32 v158, v158 offset:1300
	v_lshl_add_u32 v159, v53, 2, v33
	ds_read_b32 v159, v159 offset:1300
	v_lshl_add_u32 v160, v56, 2, v33
	ds_read_b32 v160, v160 offset:1300
	v_add_u32_e32 v8, 0x3520, v22
	ds_read2_b64 v[8:11], v8 offset1:1
	v_add_u32_e32 v57, 0x3560, v22
	ds_read2_b64 v[64:67], v57 offset1:1
	v_mov_b32_e32 v87, 0xf149f2ca
	v_mov_b32_e32 v88, 0xf149f2ca
	s_waitcnt lgkmcnt(1)
	v_mfma_f32_16x16x32_bf16 v[8:11], v[8:11], v[4:7], 0
	s_waitcnt lgkmcnt(0)
	v_mfma_f32_16x16x32_bf16 v[8:11], v[64:67], v[0:3], v[8:11]
	v_mov_b32_e32 v89, 0xf149f2ca
	v_mov_b32_e32 v90, 0xf149f2ca
	s_nop 4
	s_waitcnt lgkmcnt(0)
	v_add_f32_e32 v157, v8, v157
	v_add_f32_e32 v158, v9, v158
	v_add_f32_e32 v159, v10, v159
	v_add_f32_e32 v160, v11, v160
	v_cndmask_b32_e64 v88, v156, v157, s[12:13]
	v_cndmask_b32_e64 v87, v156, v158, s[14:15]
	v_cndmask_b32_e64 v90, v156, v159, s[16:17]
	v_cndmask_b32_e64 v89, v156, v160, s[18:19]
	v_lshl_add_u32 v157, v44, 2, v33
	ds_read_b32 v157, v157 offset:1424
	v_lshl_add_u32 v158, v45, 2, v33
	ds_read_b32 v158, v158 offset:1424
	v_lshl_add_u32 v159, v46, 2, v33
	ds_read_b32 v159, v159 offset:1424
	v_lshl_add_u32 v160, v47, 2, v33
	ds_read_b32 v160, v160 offset:1424
	v_add_u32_e32 v8, 0x4400, v22
	ds_read2_b64 v[8:11], v8 offset1:1
	v_add_u32_e32 v57, 0x4440, v22
	ds_read2_b64 v[64:67], v57 offset1:1
	v_mov_b32_e32 v91, 0xf149f2ca
	v_mov_b32_e32 v92, 0xf149f2ca
	s_waitcnt lgkmcnt(1)
	v_mfma_f32_16x16x32_bf16 v[8:11], v[8:11], v[4:7], 0
	s_waitcnt lgkmcnt(0)
	v_mfma_f32_16x16x32_bf16 v[8:11], v[64:67], v[0:3], v[8:11]
	v_mov_b32_e32 v93, 0xf149f2ca
	v_mov_b32_e32 v94, 0xf149f2ca
	s_nop 4
	s_waitcnt lgkmcnt(0)
	v_add_f32_e32 v157, v8, v157
	v_add_f32_e32 v158, v9, v158
	v_add_f32_e32 v159, v10, v159
	v_add_f32_e32 v160, v11, v160
	v_cndmask_b32_e64 v92, v156, v157, vcc
	v_cndmask_b32_e64 v91, v156, v158, s[6:7]
	v_cndmask_b32_e64 v94, v156, v159, s[8:9]
	v_cndmask_b32_e64 v93, v156, v160, s[10:11]
	v_lshl_add_u32 v157, v49, 2, v33
	ds_read_b32 v157, v157 offset:1424
	v_lshl_add_u32 v158, v52, 2, v33
	ds_read_b32 v158, v158 offset:1424
	v_lshl_add_u32 v159, v53, 2, v33
	ds_read_b32 v159, v159 offset:1424
	v_lshl_add_u32 v160, v56, 2, v33
	ds_read_b32 v160, v160 offset:1424
	v_add_u32_e32 v8, 0x4620, v22
	ds_read2_b64 v[8:11], v8 offset1:1
	v_add_u32_e32 v57, 0x4660, v22
	ds_read2_b64 v[64:67], v57 offset1:1
	v_mov_b32_e32 v95, 0xf149f2ca
	v_mov_b32_e32 v96, 0xf149f2ca
	s_waitcnt lgkmcnt(1)
	v_mfma_f32_16x16x32_bf16 v[8:11], v[8:11], v[4:7], 0
	s_waitcnt lgkmcnt(0)
	v_mfma_f32_16x16x32_bf16 v[8:11], v[64:67], v[0:3], v[8:11]
	v_mov_b32_e32 v97, 0xf149f2ca
	v_mov_b32_e32 v98, 0xf149f2ca
	s_nop 4
	s_waitcnt lgkmcnt(0)
	v_add_f32_e32 v157, v8, v157
	v_add_f32_e32 v158, v9, v158
	v_add_f32_e32 v159, v10, v159
	v_add_f32_e32 v160, v11, v160
	v_cndmask_b32_e64 v96, v156, v157, s[12:13]
	v_cndmask_b32_e64 v95, v156, v158, s[14:15]
	v_cndmask_b32_e64 v98, v156, v159, s[16:17]
	v_cndmask_b32_e64 v97, v156, v160, s[18:19]
	v_lshl_add_u32 v157, v44, 2, v33
	ds_read_b32 v157, v157 offset:1548
	v_lshl_add_u32 v158, v45, 2, v33
	ds_read_b32 v158, v158 offset:1548
	v_lshl_add_u32 v159, v46, 2, v33
	ds_read_b32 v159, v159 offset:1548
	v_lshl_add_u32 v160, v47, 2, v33
	ds_read_b32 v160, v160 offset:1548
	v_add_u32_e32 v8, 0x5500, v22
	ds_read2_b64 v[8:11], v8 offset1:1
	v_add_u32_e32 v57, 0x5540, v22
	ds_read2_b64 v[64:67], v57 offset1:1
	v_mov_b32_e32 v99, 0xf149f2ca
	v_mov_b32_e32 v100, 0xf149f2ca
	s_waitcnt lgkmcnt(1)
	v_mfma_f32_16x16x32_bf16 v[8:11], v[8:11], v[4:7], 0
	s_waitcnt lgkmcnt(0)
	v_mfma_f32_16x16x32_bf16 v[8:11], v[64:67], v[0:3], v[8:11]
	v_mov_b32_e32 v101, 0xf149f2ca
	v_mov_b32_e32 v102, 0xf149f2ca
	s_nop 4
	s_waitcnt lgkmcnt(0)
	v_add_f32_e32 v157, v8, v157
	v_add_f32_e32 v158, v9, v158
	v_add_f32_e32 v159, v10, v159
	v_add_f32_e32 v160, v11, v160
	v_cndmask_b32_e64 v100, v156, v157, vcc
	v_cndmask_b32_e64 v99, v156, v158, s[6:7]
	v_cndmask_b32_e64 v102, v156, v159, s[8:9]
	v_cndmask_b32_e64 v101, v156, v160, s[10:11]
	v_lshl_add_u32 v157, v49, 2, v33
	ds_read_b32 v157, v157 offset:1548
	v_lshl_add_u32 v158, v52, 2, v33
	ds_read_b32 v158, v158 offset:1548
	v_lshl_add_u32 v159, v53, 2, v33
	ds_read_b32 v159, v159 offset:1548
	v_lshl_add_u32 v160, v56, 2, v33
	ds_read_b32 v160, v160 offset:1548
	v_add_u32_e32 v8, 0x5720, v22
	ds_read2_b64 v[8:11], v8 offset1:1
	v_add_u32_e32 v57, 0x5760, v22
	ds_read2_b64 v[64:67], v57 offset1:1
	v_mov_b32_e32 v103, 0xf149f2ca
	v_mov_b32_e32 v104, 0xf149f2ca
	s_waitcnt lgkmcnt(1)
	v_mfma_f32_16x16x32_bf16 v[8:11], v[8:11], v[4:7], 0
	s_waitcnt lgkmcnt(0)
	v_mfma_f32_16x16x32_bf16 v[8:11], v[64:67], v[0:3], v[8:11]
	v_mov_b32_e32 v105, 0xf149f2ca
	v_mov_b32_e32 v106, 0xf149f2ca
	s_nop 4
	s_waitcnt lgkmcnt(0)
	v_add_f32_e32 v157, v8, v157
	v_add_f32_e32 v158, v9, v158
	v_add_f32_e32 v159, v10, v159
	v_add_f32_e32 v160, v11, v160
	v_cndmask_b32_e64 v104, v156, v157, s[12:13]
	v_cndmask_b32_e64 v103, v156, v158, s[14:15]
	v_cndmask_b32_e64 v106, v156, v159, s[16:17]
	v_cndmask_b32_e64 v105, v156, v160, s[18:19]
	v_lshl_add_u32 v157, v44, 2, v33
	ds_read_b32 v157, v157 offset:1672
	v_lshl_add_u32 v158, v45, 2, v33
	ds_read_b32 v158, v158 offset:1672
	v_lshl_add_u32 v159, v46, 2, v33
	ds_read_b32 v159, v159 offset:1672
	v_lshl_add_u32 v160, v47, 2, v33
	ds_read_b32 v160, v160 offset:1672
	v_add_u32_e32 v8, 0x6600, v22
	ds_read2_b64 v[8:11], v8 offset1:1
	v_add_u32_e32 v57, 0x6640, v22
	ds_read2_b64 v[64:67], v57 offset1:1
	v_mov_b32_e32 v107, 0xf149f2ca
	v_mov_b32_e32 v108, 0xf149f2ca
	s_waitcnt lgkmcnt(1)
	v_mfma_f32_16x16x32_bf16 v[8:11], v[8:11], v[4:7], 0
	s_waitcnt lgkmcnt(0)
	v_mfma_f32_16x16x32_bf16 v[8:11], v[64:67], v[0:3], v[8:11]
	v_mov_b32_e32 v109, 0xf149f2ca
	v_mov_b32_e32 v110, 0xf149f2ca
	s_nop 4
	s_waitcnt lgkmcnt(0)
	v_add_f32_e32 v157, v8, v157
	v_add_f32_e32 v158, v9, v158
	v_add_f32_e32 v159, v10, v159
	v_add_f32_e32 v160, v11, v160
	v_cndmask_b32_e64 v108, v156, v157, vcc
	v_cndmask_b32_e64 v107, v156, v158, s[6:7]
	v_cndmask_b32_e64 v110, v156, v159, s[8:9]
	v_cndmask_b32_e64 v109, v156, v160, s[10:11]
	v_lshl_add_u32 v157, v49, 2, v33
	ds_read_b32 v157, v157 offset:1672
	v_lshl_add_u32 v158, v52, 2, v33
	ds_read_b32 v158, v158 offset:1672
	v_lshl_add_u32 v159, v53, 2, v33
	ds_read_b32 v159, v159 offset:1672
	v_lshl_add_u32 v160, v56, 2, v33
	ds_read_b32 v160, v160 offset:1672
	v_add_u32_e32 v8, 0x6820, v22
	ds_read2_b64 v[8:11], v8 offset1:1
	v_add_u32_e32 v57, 0x6860, v22
	ds_read2_b64 v[64:67], v57 offset1:1
	v_mov_b32_e32 v111, 0xf149f2ca
	v_mov_b32_e32 v112, 0xf149f2ca
	s_waitcnt lgkmcnt(1)
	v_mfma_f32_16x16x32_bf16 v[8:11], v[8:11], v[4:7], 0
	s_waitcnt lgkmcnt(0)
	v_mfma_f32_16x16x32_bf16 v[8:11], v[64:67], v[0:3], v[8:11]
	v_mov_b32_e32 v113, 0xf149f2ca
	v_mov_b32_e32 v114, 0xf149f2ca
	s_nop 4
	s_waitcnt lgkmcnt(0)
	v_add_f32_e32 v157, v8, v157
	v_add_f32_e32 v158, v9, v158
	v_add_f32_e32 v159, v10, v159
	v_add_f32_e32 v160, v11, v160
	v_cndmask_b32_e64 v112, v156, v157, s[12:13]
	v_cndmask_b32_e64 v111, v156, v158, s[14:15]
	v_cndmask_b32_e64 v114, v156, v159, s[16:17]
	v_cndmask_b32_e64 v113, v156, v160, s[18:19]
	v_add_u32_e32 v8, 0x7700, v22
	ds_read2_b64 v[8:11], v8 offset1:1
	v_add_u32_e32 v57, 0x7740, v22
	ds_read2_b64 v[64:67], v57 offset1:1
	v_mov_b32_e32 v115, 0xf149f2ca
	v_mov_b32_e32 v116, 0xf149f2ca
	s_waitcnt lgkmcnt(1)
	v_mfma_f32_16x16x32_bf16 v[8:11], v[8:11], v[4:7], 0
	s_waitcnt lgkmcnt(0)
	v_mfma_f32_16x16x32_bf16 v[8:11], v[64:67], v[0:3], v[8:11]
	s_and_saveexec_b64 s[22:23], vcc
	s_cbranch_execz .LBB0_645
	v_lshl_add_u32 v44, v44, 2, v33
	ds_read_b32 v44, v44 offset:1796
	s_waitcnt lgkmcnt(0)
	s_nop 2
	v_add_f32_e32 v116, v8, v44

.LBB0_701:
	v_mov_b32_e32 v166, 0xf149f2ca
	s_or_b32 s25, s97, s24
	s_or_b32 s0, s25, s23
	s_lshl_b64 s[18:19], s[0:1], 2
	s_add_u32 s18, s62, s18
	s_addc_u32 s19, s63, s19
	s_lshl_b32 s0, s25, 7
	v_lshl_add_u64 v[0:1], v[20:21], 0, s[0:1]
	s_cmp_lg_u32 s97, 0
	s_cbranch_scc1 .Lswa_q1
	s_waitcnt vmcnt(0)
	v_mov_b32_e32 v4, v148
	v_mov_b32_e32 v5, v149
	v_mov_b32_e32 v6, v150
	v_mov_b32_e32 v7, v151
	v_mov_b32_e32 v0, v152
	v_mov_b32_e32 v1, v153
	v_mov_b32_e32 v2, v154
	v_mov_b32_e32 v3, v155
	s_branch .Lswa_qd

.Lswa_qd:
	global_load_dword v19, v193, s[18:19]
	ds_read2_b64 v[8:11], v14 offset1:1
	ds_read2_b64 v[24:27], v14 offset0:8 offset1:9
	s_mul_i32 s0, s97, 0x404
	s_add_i32 s0, s0, 0x19000
	v_lshl_add_u32 v42, v88, 2, s0
	v_mov_b32_e32 v28, 0xf149f2ca
	s_waitcnt lgkmcnt(1)
	v_mfma_f32_16x16x32_bf16 v[8:11], v[8:11], v[4:7], 0
	s_waitcnt lgkmcnt(0)
	v_mfma_f32_16x16x32_bf16 v[8:11], v[24:27], v[0:3], v[8:11]
	v_mov_b32_e32 v24, 0xf149f2ca
	v_mov_b32_e32 v25, 0xf149f2ca
	v_mov_b32_e32 v26, 0xf149f2ca
	ds_read_b32 v167, v42 offset:512
	ds_read_b32 v168, v42 offset:516
	ds_read_b32 v169, v42 offset:520
	ds_read_b32 v170, v42 offset:524
	s_waitcnt lgkmcnt(0)
	v_add_f32_e32 v167, v8, v167
	v_add_f32_e32 v168, v9, v168
	v_add_f32_e32 v169, v10, v169
	v_add_f32_e32 v170, v11, v170
	v_cndmask_b32_e64 v28, v166, v167, s[66:67]
	v_cndmask_b32_e64 v24, v166, v168, s[68:69]
	v_cndmask_b32_e64 v26, v166, v169, s[70:71]
	v_cndmask_b32_e64 v25, v166, v170, s[74:75]
	ds_read_b32 v167, v42 offset:528
	ds_read_b32 v168, v42 offset:532
	ds_read_b32 v169, v42 offset:536
	ds_read_b32 v170, v42 offset:540
	ds_read2_b64 v[8:11], v14 offset0:68 offset1:69
	ds_read2_b64 v[30:33], v14 offset0:76 offset1:77
	v_mov_b32_e32 v27, 0xf149f2ca
	v_mov_b32_e32 v29, 0xf149f2ca
	s_waitcnt lgkmcnt(1)
	v_mfma_f32_16x16x32_bf16 v[8:11], v[8:11], v[4:7], 0
	s_waitcnt lgkmcnt(0)
	v_mfma_f32_16x16x32_bf16 v[8:11], v[30:33], v[0:3], v[8:11]
	v_mov_b32_e32 v30, 0xf149f2ca
	v_mov_b32_e32 v31, 0xf149f2ca
	s_nop 4
	s_waitcnt lgkmcnt(0)
	v_add_f32_e32 v167, v8, v167
	v_add_f32_e32 v168, v9, v168
	v_add_f32_e32 v169, v10, v169
	v_add_f32_e32 v170, v11, v170
	v_cndmask_b32_e64 v29, v166, v167, s[76:77]
	v_cndmask_b32_e64 v27, v166, v168, s[78:79]
	v_cndmask_b32_e64 v31, v166, v169, s[80:81]
	v_cndmask_b32_e64 v30, v166, v170, s[82:83]
	ds_read_b32 v167, v42 offset:640
	ds_read_b32 v168, v42 offset:644
	ds_read_b32 v169, v42 offset:648
	ds_read_b32 v170, v42 offset:652
	v_add_u32_e32 v8, 0x1100, v14
	ds_read2_b64 v[8:11], v8 offset1:1
	v_add_u32_e32 v32, 0x1140, v14
	ds_read2_b64 v[32:35], v32 offset1:1
	s_waitcnt lgkmcnt(1)
	v_mfma_f32_16x16x32_bf16 v[8:11], v[8:11], v[4:7], 0
	s_waitcnt lgkmcnt(0)
	v_mfma_f32_16x16x32_bf16 v[8:11], v[32:35], v[0:3], v[8:11]
	v_mov_b32_e32 v32, 0xf149f2ca
	v_mov_b32_e32 v33, 0xf149f2ca
	v_mov_b32_e32 v34, 0xf149f2ca
	v_mov_b32_e32 v35, 0xf149f2ca
	s_nop 2
	s_waitcnt lgkmcnt(0)
	v_add_f32_e32 v167, v8, v167
	v_add_f32_e32 v168, v9, v168
	v_add_f32_e32 v169, v10, v169
	v_add_f32_e32 v170, v11, v170
	v_cndmask_b32_e64 v33, v166, v167, s[88:89]
	v_cndmask_b32_e64 v32, v166, v168, s[88:89]
	v_cndmask_b32_e64 v35, v166, v169, s[88:89]
	v_cndmask_b32_e64 v34, v166, v170, s[88:89]
	ds_read_b32 v167, v42 offset:656
	ds_read_b32 v168, v42 offset:660
	ds_read_b32 v169, v42 offset:664
	ds_read_b32 v170, v42 offset:668
	v_add_u32_e32 v8, 0x1320, v14
	ds_read2_b64 v[8:11], v8 offset1:1
	v_add_u32_e32 v36, 0x1360, v14
	ds_read2_b64 v[38:41], v36 offset1:1
	v_mov_b32_e32 v36, 0xf149f2ca
	s_waitcnt lgkmcnt(1)
	v_mfma_f32_16x16x32_bf16 v[8:11], v[8:11], v[4:7], 0
	s_waitcnt lgkmcnt(0)
	v_mfma_f32_16x16x32_bf16 v[8:11], v[38:41], v[0:3], v[8:11]
	v_mov_b32_e32 v38, 0xf149f2ca
	v_mov_b32_e32 v39, 0xf149f2ca
	v_mov_b32_e32 v40, 0xf149f2ca
	s_nop 3
	s_waitcnt lgkmcnt(0)
	v_add_f32_e32 v167, v8, v167
	v_add_f32_e32 v168, v9, v168
	v_add_f32_e32 v169, v10, v169
	v_add_f32_e32 v170, v11, v170
	v_cndmask_b32_e64 v38, v166, v167, s[88:89]
	v_cndmask_b32_e64 v36, v166, v168, s[88:89]
	v_cndmask_b32_e64 v40, v166, v169, s[88:89]
	v_cndmask_b32_e64 v39, v166, v170, s[88:89]
	ds_read_b32 v167, v42 offset:768
	ds_read_b32 v168, v42 offset:772
	ds_read_b32 v169, v42 offset:776
	ds_read_b32 v170, v42 offset:780
	v_add_u32_e32 v8, 0x2200, v14
	ds_read2_b64 v[8:11], v8 offset1:1
	v_add_u32_e32 v41, 0x2240, v14
	ds_read2_b64 v[44:47], v41 offset1:1
	v_mov_b32_e32 v41, 0xf149f2ca
	v_mov_b32_e32 v43, 0xf149f2ca
	s_waitcnt lgkmcnt(1)
	v_mfma_f32_16x16x32_bf16 v[8:11], v[8:11], v[4:7], 0
	s_waitcnt lgkmcnt(0)
	v_mfma_f32_16x16x32_bf16 v[8:11], v[44:47], v[0:3], v[8:11]
	v_mov_b32_e32 v44, 0xf149f2ca
	v_mov_b32_e32 v45, 0xf149f2ca
	s_nop 4
	s_waitcnt lgkmcnt(0)
	v_add_f32_e32 v167, v8, v167
	v_add_f32_e32 v168, v9, v168
	v_add_f32_e32 v169, v10, v169
	v_add_f32_e32 v170, v11, v170
	v_cndmask_b32_e64 v43, v166, v167, s[90:91]
	v_cndmask_b32_e64 v41, v166, v168, s[90:91]
	v_cndmask_b32_e64 v45, v166, v169, s[90:91]
	v_cndmask_b32_e64 v44, v166, v170, s[90:91]
	ds_read_b32 v167, v42 offset:784
	ds_read_b32 v168, v42 offset:788
	ds_read_b32 v169, v42 offset:792
	ds_read_b32 v170, v42 offset:796
	v_add_u32_e32 v8, 0x2420, v14
	ds_read2_b64 v[8:11], v8 offset1:1
	v_add_u32_e32 v46, 0x2460, v14
	ds_read2_b64 v[46:49], v46 offset1:1
	s_waitcnt lgkmcnt(1)
	v_mfma_f32_16x16x32_bf16 v[8:11], v[8:11], v[4:7], 0
	s_waitcnt lgkmcnt(0)
	v_mfma_f32_16x16x32_bf16 v[8:11], v[46:49], v[0:3], v[8:11]
	v_mov_b32_e32 v46, 0xf149f2ca
	v_mov_b32_e32 v47, 0xf149f2ca
	v_mov_b32_e32 v48, 0xf149f2ca
	v_mov_b32_e32 v49, 0xf149f2ca
	s_nop 2
	s_waitcnt lgkmcnt(0)
	v_add_f32_e32 v167, v8, v167
	v_add_f32_e32 v168, v9, v168
	v_add_f32_e32 v169, v10, v169
	v_add_f32_e32 v170, v11, v170
	v_cndmask_b32_e64 v47, v166, v167, s[90:91]
	v_cndmask_b32_e64 v46, v166, v168, s[90:91]
	v_cndmask_b32_e64 v49, v166, v169, s[90:91]
	v_cndmask_b32_e64 v48, v166, v170, s[90:91]
	ds_read_b32 v167, v42 offset:896
	ds_read_b32 v168, v42 offset:900
	ds_read_b32 v169, v42 offset:904
	ds_read_b32 v170, v42 offset:908
	v_add_u32_e32 v8, 0x3300, v14
	ds_read2_b64 v[8:11], v8 offset1:1
	v_add_u32_e32 v50, 0x3340, v14
	ds_read2_b64 v[50:53], v50 offset1:1
	s_waitcnt lgkmcnt(1)
	v_mfma_f32_16x16x32_bf16 v[8:11], v[8:11], v[4:7], 0
	s_waitcnt lgkmcnt(0)
	v_mfma_f32_16x16x32_bf16 v[8:11], v[50:53], v[0:3], v[8:11]
	v_mov_b32_e32 v50, 0xf149f2ca
	v_mov_b32_e32 v51, 0xf149f2ca
	v_mov_b32_e32 v52, 0xf149f2ca
	v_mov_b32_e32 v53, 0xf149f2ca
	s_nop 2
	s_waitcnt lgkmcnt(0)
	v_add_f32_e32 v167, v8, v167
	v_add_f32_e32 v168, v9, v168
	v_add_f32_e32 v169, v10, v169
	v_add_f32_e32 v170, v11, v170
	v_cndmask_b32_e64 v51, v166, v167, s[64:65]
	v_cndmask_b32_e64 v50, v166, v168, s[64:65]
	v_cndmask_b32_e64 v53, v166, v169, s[64:65]
	v_cndmask_b32_e64 v52, v166, v170, s[64:65]
	ds_read_b32 v167, v42 offset:912
	ds_read_b32 v168, v42 offset:916
	ds_read_b32 v169, v42 offset:920
	ds_read_b32 v170, v42 offset:924
	v_add_u32_e32 v8, 0x3520, v14
	ds_read2_b64 v[8:11], v8 offset1:1
	v_add_u32_e32 v54, 0x3560, v14
	ds_read2_b64 v[54:57], v54 offset1:1
	v_mov_b32_e32 v58, 0xf149f2ca
	v_mov_b32_e32 v59, 0xf149f2ca
	s_waitcnt lgkmcnt(1)
	v_mfma_f32_16x16x32_bf16 v[8:11], v[8:11], v[4:7], 0
	s_waitcnt lgkmcnt(0)
	v_mfma_f32_16x16x32_bf16 v[8:11], v[54:57], v[0:3], v[8:11]
	v_mov_b32_e32 v67, 0xf149f2ca
	v_mov_b32_e32 v66, 0xf149f2ca
	s_nop 4
	s_waitcnt lgkmcnt(0)
	v_add_f32_e32 v167, v8, v167
	v_add_f32_e32 v168, v9, v168
	v_add_f32_e32 v169, v10, v169
	v_add_f32_e32 v170, v11, v170
	v_cndmask_b32_e64 v59, v166, v167, s[64:65]
	v_cndmask_b32_e64 v58, v166, v168, s[64:65]
	v_cndmask_b32_e64 v66, v166, v169, s[64:65]
	v_cndmask_b32_e64 v67, v166, v170, s[64:65]
	v_add_u32_e32 v8, 0x4400, v14
	ds_read2_b64 v[8:11], v8 offset1:1
	v_add_u32_e32 v54, 0x4440, v14
	ds_read2_b64 v[54:57], v54 offset1:1
	v_mov_b32_e32 v94, 0xf149f2ca
	v_mov_b32_e32 v95, 0xf149f2ca
	s_waitcnt lgkmcnt(1)
	v_mfma_f32_16x16x32_bf16 v[8:11], v[8:11], v[4:7], 0
	s_waitcnt lgkmcnt(0)
	v_mfma_f32_16x16x32_bf16 v[8:11], v[54:57], v[0:3], v[8:11]
	s_and_saveexec_b64 s[18:19], s[42:43]
	s_cbranch_execz .LBB0_767
	v_lshl_add_u32 v54, v89, 2, s0
	ds_read_b32 v54, v54 offset:512
	s_waitcnt lgkmcnt(0)
	s_nop 2
	v_add_f32_e32 v95, v8, v54

.LBB0_773:
	s_or_b64 exec, exec, s[18:19]
	ds_read_b32 v167, v42 offset:1040
	ds_read_b32 v168, v42 offset:1044
	ds_read_b32 v169, v42 offset:1048
	ds_read_b32 v170, v42 offset:1052
	v_add_u32_e32 v8, 0x4620, v14
	ds_read2_b64 v[8:11], v8 offset1:1
	v_add_u32_e32 v54, 0x4660, v14
	ds_read2_b64 v[54:57], v54 offset1:1
	v_mov_b32_e32 v98, 0xf149f2ca
	v_mov_b32_e32 v99, 0xf149f2ca
	s_waitcnt lgkmcnt(1)
	v_mfma_f32_16x16x32_bf16 v[8:11], v[8:11], v[4:7], 0
	s_waitcnt lgkmcnt(0)
	v_mfma_f32_16x16x32_bf16 v[8:11], v[54:57], v[0:3], v[8:11]
	v_mov_b32_e32 v100, 0xf149f2ca
	v_mov_b32_e32 v101, 0xf149f2ca
	s_nop 4
	s_waitcnt lgkmcnt(0)
	v_add_f32_e32 v167, v8, v167
	v_add_f32_e32 v168, v9, v168
	v_add_f32_e32 v169, v10, v169
	v_add_f32_e32 v170, v11, v170
	v_cndmask_b32_e64 v99, v166, v167, s[42:43]
	v_cndmask_b32_e64 v98, v166, v168, s[42:43]
	v_cndmask_b32_e64 v101, v166, v169, s[42:43]
	v_cndmask_b32_e64 v100, v166, v170, s[42:43]
	ds_read_b32 v167, v42 offset:1152
	ds_read_b32 v168, v42 offset:1156
	ds_read_b32 v169, v42 offset:1160
	ds_read_b32 v170, v42 offset:1164
	v_add_u32_e32 v8, 0x5500, v14
	ds_read2_b64 v[8:11], v8 offset1:1
	v_add_u32_e32 v54, 0x5540, v14
	ds_read2_b64 v[54:57], v54 offset1:1
	v_mov_b32_e32 v102, 0xf149f2ca
	v_mov_b32_e32 v103, 0xf149f2ca
	s_waitcnt lgkmcnt(1)
	v_mfma_f32_16x16x32_bf16 v[8:11], v[8:11], v[4:7], 0
	s_waitcnt lgkmcnt(0)
	v_mfma_f32_16x16x32_bf16 v[8:11], v[54:57], v[0:3], v[8:11]
	v_mov_b32_e32 v104, 0xf149f2ca
	v_mov_b32_e32 v105, 0xf149f2ca
	s_nop 4
	s_waitcnt lgkmcnt(0)
	v_add_f32_e32 v167, v8, v167
	v_add_f32_e32 v168, v9, v168
	v_add_f32_e32 v169, v10, v169
	v_add_f32_e32 v170, v11, v170
	v_cndmask_b32_e64 v103, v166, v167, s[40:41]
	v_cndmask_b32_e64 v102, v166, v168, s[40:41]
	v_cndmask_b32_e64 v105, v166, v169, s[40:41]
	v_cndmask_b32_e64 v104, v166, v170, s[40:41]
	ds_read_b32 v167, v42 offset:1168
	ds_read_b32 v168, v42 offset:1172
	ds_read_b32 v169, v42 offset:1176
	ds_read_b32 v170, v42 offset:1180
	v_add_u32_e32 v8, 0x5720, v14
	ds_read2_b64 v[8:11], v8 offset1:1
	v_add_u32_e32 v54, 0x5760, v14
	ds_read2_b64 v[54:57], v54 offset1:1
	v_mov_b32_e32 v106, 0xf149f2ca
	v_mov_b32_e32 v107, 0xf149f2ca
	s_waitcnt lgkmcnt(1)
	v_mfma_f32_16x16x32_bf16 v[8:11], v[8:11], v[4:7], 0
	s_waitcnt lgkmcnt(0)
	v_mfma_f32_16x16x32_bf16 v[8:11], v[54:57], v[0:3], v[8:11]
	v_mov_b32_e32 v108, 0xf149f2ca
	v_mov_b32_e32 v109, 0xf149f2ca
	s_nop 4
	s_waitcnt lgkmcnt(0)
	v_add_f32_e32 v167, v8, v167
	v_add_f32_e32 v168, v9, v168
	v_add_f32_e32 v169, v10, v169
	v_add_f32_e32 v170, v11, v170
	v_cndmask_b32_e64 v107, v166, v167, s[40:41]
	v_cndmask_b32_e64 v106, v166, v168, s[40:41]
	v_cndmask_b32_e64 v109, v166, v169, s[40:41]
	v_cndmask_b32_e64 v108, v166, v170, s[40:41]
	ds_read_b32 v167, v42 offset:1280
	ds_read_b32 v168, v42 offset:1284
	ds_read_b32 v169, v42 offset:1288
	ds_read_b32 v170, v42 offset:1292
	v_add_u32_e32 v8, 0x6600, v14
	ds_read2_b64 v[8:11], v8 offset1:1
	v_add_u32_e32 v54, 0x6640, v14
	ds_read2_b64 v[54:57], v54 offset1:1
	v_mov_b32_e32 v110, 0xf149f2ca
	v_mov_b32_e32 v111, 0xf149f2ca
	s_waitcnt lgkmcnt(1)
	v_mfma_f32_16x16x32_bf16 v[8:11], v[8:11], v[4:7], 0
	s_waitcnt lgkmcnt(0)
	v_mfma_f32_16x16x32_bf16 v[8:11], v[54:57], v[0:3], v[8:11]
	v_mov_b32_e32 v112, 0xf149f2ca
	v_mov_b32_e32 v113, 0xf149f2ca
	s_nop 4
	s_waitcnt lgkmcnt(0)
	v_add_f32_e32 v167, v8, v167
	v_add_f32_e32 v168, v9, v168
	v_add_f32_e32 v169, v10, v169
	v_add_f32_e32 v170, v11, v170
	v_cndmask_b32_e64 v111, v166, v167, s[46:47]
	v_cndmask_b32_e64 v110, v166, v168, s[46:47]
	v_cndmask_b32_e64 v113, v166, v169, s[46:47]
	v_cndmask_b32_e64 v112, v166, v170, s[46:47]
	ds_read_b32 v167, v42 offset:1296
	ds_read_b32 v168, v42 offset:1300
	ds_read_b32 v169, v42 offset:1304
	ds_read_b32 v170, v42 offset:1308
	v_add_u32_e32 v8, 0x6820, v14
	ds_read2_b64 v[8:11], v8 offset1:1
	v_add_u32_e32 v54, 0x6860, v14
	ds_read2_b64 v[54:57], v54 offset1:1
	v_mov_b32_e32 v114, 0xf149f2ca
	v_mov_b32_e32 v115, 0xf149f2ca
	s_waitcnt lgkmcnt(1)
	v_mfma_f32_16x16x32_bf16 v[8:11], v[8:11], v[4:7], 0
	s_waitcnt lgkmcnt(0)
	v_mfma_f32_16x16x32_bf16 v[8:11], v[54:57], v[0:3], v[8:11]
	v_mov_b32_e32 v116, 0xf149f2ca
	v_mov_b32_e32 v117, 0xf149f2ca
	s_nop 4
	s_waitcnt lgkmcnt(0)
	v_add_f32_e32 v167, v8, v167
	v_add_f32_e32 v168, v9, v168
	v_add_f32_e32 v169, v10, v169
	v_add_f32_e32 v170, v11, v170
	v_cndmask_b32_e64 v115, v166, v167, s[46:47]
	v_cndmask_b32_e64 v114, v166, v168, s[46:47]
	v_cndmask_b32_e64 v117, v166, v169, s[46:47]
	v_cndmask_b32_e64 v116, v166, v170, s[46:47]
	ds_read_b32 v167, v42 offset:1408
	ds_read_b32 v168, v42 offset:1412
	ds_read_b32 v169, v42 offset:1416
	ds_read_b32 v170, v42 offset:1420
	v_add_u32_e32 v8, 0x7700, v14
	ds_read2_b64 v[8:11], v8 offset1:1
	v_add_u32_e32 v54, 0x7740, v14
	ds_read2_b64 v[54:57], v54 offset1:1
	v_mov_b32_e32 v118, 0xf149f2ca
	v_mov_b32_e32 v119, 0xf149f2ca
	s_waitcnt lgkmcnt(1)
	v_mfma_f32_16x16x32_bf16 v[8:11], v[8:11], v[4:7], 0
	s_waitcnt lgkmcnt(0)
	v_mfma_f32_16x16x32_bf16 v[8:11], v[54:57], v[0:3], v[8:11]
	v_mov_b32_e32 v120, 0xf149f2ca
	v_mov_b32_e32 v121, 0xf149f2ca
	s_nop 4
	s_waitcnt lgkmcnt(0)
	v_add_f32_e32 v167, v8, v167
	v_add_f32_e32 v168, v9, v168
	v_add_f32_e32 v169, v10, v169
	v_add_f32_e32 v170, v11, v170
	v_cndmask_b32_e64 v119, v166, v167, s[2:3]
	v_cndmask_b32_e64 v118, v166, v168, s[2:3]
	v_cndmask_b32_e64 v121, v166, v169, s[2:3]
	v_cndmask_b32_e64 v120, v166, v170, s[2:3]
	ds_read_b32 v167, v42 offset:1424
	ds_read_b32 v168, v42 offset:1428
	ds_read_b32 v169, v42 offset:1432
	ds_read_b32 v170, v42 offset:1436
	v_add_u32_e32 v8, 0x7920, v14
	ds_read2_b64 v[8:11], v8 offset1:1
	v_add_u32_e32 v54, 0x7960, v14
	ds_read2_b64 v[54:57], v54 offset1:1
	v_mov_b32_e32 v122, 0xf149f2ca
	v_mov_b32_e32 v123, 0xf149f2ca
	s_waitcnt lgkmcnt(1)
	v_mfma_f32_16x16x32_bf16 v[8:11], v[8:11], v[4:7], 0
	s_waitcnt lgkmcnt(0)
	v_mfma_f32_16x16x32_bf16 v[8:11], v[54:57], v[0:3], v[8:11]
	v_mov_b32_e32 v124, 0xf149f2ca
	v_mov_b32_e32 v125, 0xf149f2ca
	s_nop 4
	s_waitcnt lgkmcnt(0)
	v_add_f32_e32 v167, v8, v167
	v_add_f32_e32 v168, v9, v168
	v_add_f32_e32 v169, v10, v169
	v_add_f32_e32 v170, v11, v170
	v_cndmask_b32_e64 v123, v166, v167, s[2:3]
	v_cndmask_b32_e64 v122, v166, v168, s[2:3]
	v_cndmask_b32_e64 v125, v166, v169, s[2:3]
	v_cndmask_b32_e64 v124, v166, v170, s[2:3]
	ds_read_b32 v167, v42 offset:1536
	ds_read_b32 v168, v42 offset:1540
	ds_read_b32 v169, v42 offset:1544
	ds_read_b32 v170, v42 offset:1548
	v_add_u32_e32 v8, 0x8800, v14
	ds_read2_b64 v[8:11], v8 offset1:1
	v_add_u32_e32 v54, 0x8840, v14
	ds_read2_b64 v[54:57], v54 offset1:1
	v_mov_b32_e32 v126, 0xf149f2ca
	v_mov_b32_e32 v127, 0xf149f2ca
	s_waitcnt lgkmcnt(1)
	v_mfma_f32_16x16x32_bf16 v[8:11], v[8:11], v[4:7], 0
	s_waitcnt lgkmcnt(0)
	v_mfma_f32_16x16x32_bf16 v[8:11], v[54:57], v[0:3], v[8:11]
	v_mov_b32_e32 v128, 0xf149f2ca
	v_mov_b32_e32 v129, 0xf149f2ca
	s_nop 4
	s_waitcnt lgkmcnt(0)
	v_add_f32_e32 v167, v8, v167
	v_add_f32_e32 v168, v9, v168
	v_add_f32_e32 v169, v10, v169
	v_add_f32_e32 v170, v11, v170
	v_cndmask_b32_e64 v127, v166, v167, s[44:45]
	v_cndmask_b32_e64 v126, v166, v168, s[4:5]
	v_cndmask_b32_e64 v129, v166, v169, s[6:7]
	v_cndmask_b32_e64 v128, v166, v170, s[8:9]
	v_add_u32_e32 v8, 0x8a20, v14
	ds_read2_b64 v[8:11], v8 offset1:1
	v_add_u32_e32 v54, 0x8a60, v14
	s_waitcnt lgkmcnt(0)
	v_mfma_f32_16x16x32_bf16 v[4:7], v[8:11], v[4:7], 0
	ds_read2_b64 v[8:11], v54 offset1:1
	s_waitcnt lgkmcnt(0)
	v_mfma_f32_16x16x32_bf16 v[0:3], v[8:11], v[0:3], v[4:7]
	s_nop 4
	v_mov_b32_e32 v7, 0xf149f2ca
	v_mov_b32_e32 v6, 0xf149f2ca
	s_and_saveexec_b64 s[18:19], s[10:11]
	s_cbranch_execz .LBB0_839
	ds_read_b32 v4, v42 offset:1552
	s_waitcnt lgkmcnt(0)
	v_add_f32_e32 v6, v0, v4
